# v030 + GEMM K-loops: back-to-back s_setprio 0 / s_setprio 1 pairs between the two MFMA blocks of each super-phase removed (28 sites)
# speedup vs baseline: 1.0075x; 1.0075x over previous
; #define PG8_STAGE(bufoff, gbase, voff) do { _Pragma("unroll") for (int _i = 0; _i < 2; ++_i) \
;         __builtin_amdgcn_global_load_lds((const unsigned*)((const char*)(gbase) + (voff)[_i]), (PG8_LAS unsigned*)(lds + (bufoff) + ldsw + _i * 8192), 16, 0, 0); } while (0)
; #define PG8_LDA(dst, b, h) do { _Pragma("unroll") for (int m = 0; m < 4; ++m) _Pragma("unroll") for (int k = 0; k < 2; ++k) dst[m][k] = *(const PG8_LAS bf16x8*)(lds + PG8_SA(b, h) + aoff + m * 2048 + k * 1024); } while (0)
; #define PG8_LDB(dst, b, h) do { _Pragma("unroll") for (int n = 0; n < 2; ++n) _Pragma("unroll") for (int k = 0; k < 2; ++k) dst[n][k] = *(const PG8_LAS bf16x8*)(lds + PG8_SB(b, h) + boff + n * 2048 + k * 1024); } while (0)
; #define PG8_MMA(ai, bj, At, Bt) do { __builtin_amdgcn_s_setprio(1); _Pragma("unroll") for (int m = 0; m < 4; ++m) _Pragma("unroll") for (int n = 0; n < 2; ++n) _Pragma("unroll") for (int k = 0; k < 2; ++k) \
;         acc[ai][bj][m][n] = __builtin_amdgcn_mfma_f32_16x16x32_bf16(Bt[n][k], At[m][k], acc[ai][bj][m][n], 0, 0, 0); __builtin_amdgcn_s_setprio(0); } while (0)
; #define PG8_WAIT_V(n) asm volatile("s_waitcnt vmcnt(" #n ")" ::: "memory")
; #define PG8_WAIT_L(n) asm volatile("s_waitcnt lgkmcnt(" #n ")" ::: "memory")
; #define PG8_BAR __builtin_amdgcn_s_barrier()
; #define PG8_SCHED __builtin_amdgcn_sched_barrier(0)
; template <class Epi, class Sched, bool ALIGN_EPI = false, bool SP2 = false>
; __device__ __forceinline__ void gemm_phase(PG8_LAS unsigned char* lds, const Gemm g, const Sched& S, const Epi& E, const int wv) {
;     ...
;             const bool last = (t == nt - 2);
;             const char* a1 = cA + (size_t)(t + 1) * kstep;
;             const char* a2 = last ? nA : cA + (size_t)(t + 2) * kstep; const char* b2 = last ? nB : cB + (size_t)(t + 2) * kstep;
;             const char* a3 = a2 + kstep; const char* b3 = b2 + kstep;
;             if (last && has_next) S.a_ready(nxt);
;             if constexpr (SP2) {
;             PG8_LDB(B0, 0, 0); PG8_LDB(B1, 0, 1); PG8_SCHED; PG8_LDA(At, 0, 0); PG8_STAGE(PG8_SA(1, 1), a1 + hstepA, voffA);
;             PG8_WAIT_V(8); PG8_WAIT_L(0); PG8_BAR; PG8_MMA(0, 0, At, B0); PG8_MMA(0, 1, At, B1); PG8_BAR; PG8_SCHED;
;             PG8_LDA(At, 0, 1); PG8_STAGE(PG8_SB(0, 0), b2, voffB); PG8_STAGE(PG8_SB(0, 1), b2 + hstepB, voffB); PG8_STAGE(PG8_SA(0, 0), a2, voffA);
.LBB0_208:
	s_add_u32 s1, s40, 0xfffc0080
	s_addc_u32 s44, s41, -1
	s_add_i32 s69, 0, 0x10000
	s_cmp_eq_u32 s68, 12
	s_cselect_b32 s65, s5, s44
	s_cselect_b32 s64, s7, s1
	v_add_u32_e32 v114, s69, v247
	s_cselect_b32 s45, s57, s67
	s_cselect_b32 s44, s59, s66
	s_add_i32 s1, 0, 0x14000
	ds_read_b128 v[132:135], v114
	ds_read_b128 v[136:139], v114 offset:1024
	ds_read_b128 v[140:143], v114 offset:2048
	ds_read_b128 v[144:147], v114 offset:3072
	v_add_u32_e32 v114, s1, v247
	ds_read_b128 v[148:151], v114
	ds_read_b128 v[152:155], v114 offset:1024
	ds_read_b128 v[166:169], v114 offset:2048
	ds_read_b128 v[170:173], v114 offset:3072
	v_lshl_add_u64 v[186:187], s[40:41], 0, v[162:163]
	s_add_i32 m0, s72, 0xc000
	ds_read_b128 v[174:177], v248
	ds_read_b128 v[178:181], v248 offset:1024
	ds_read_b128 v[182:185], v248 offset:2048
	ds_read_b128 v[198:201], v248 offset:3072
	ds_read_b128 v[202:205], v248 offset:4096
	ds_read_b128 v[206:209], v248 offset:5120
	ds_read_b128 v[210:213], v248 offset:6144
	ds_read_b128 v[214:217], v248 offset:7168
	global_load_lds_dwordx4 v[186:187], off
	v_lshl_add_u64 v[186:187], s[40:41], 0, v[164:165]
	s_add_i32 m0, s72, 0xe000
	s_nop 0
	global_load_lds_dwordx4 v[186:187], off
	s_waitcnt vmcnt(8)
	s_waitcnt lgkmcnt(0)
	s_barrier
	s_setprio 1
	s_waitcnt lgkmcnt(0)
	v_mfma_f32_16x16x32_bf16 v[128:131], v[132:135], v[174:177], v[128:131]
	v_mfma_f32_16x16x32_bf16 v[124:127], v[140:143], v[174:177], v[124:127]
	v_mfma_f32_16x16x32_bf16 v[108:111], v[132:135], v[182:185], v[108:111]
	v_mfma_f32_16x16x32_bf16 v[104:107], v[140:143], v[182:185], v[104:107]
	v_mfma_f32_16x16x32_bf16 v[92:95], v[132:135], v[202:205], v[92:95]
	v_mfma_f32_16x16x32_bf16 v[88:91], v[140:143], v[202:205], v[88:91]
	v_mfma_f32_16x16x32_bf16 v[76:79], v[132:135], v[210:213], v[76:79]
	v_mfma_f32_16x16x32_bf16 v[72:75], v[140:143], v[210:213], v[72:75]
	v_mfma_f32_16x16x32_bf16 v[128:131], v[136:139], v[178:181], v[128:131]
	v_mfma_f32_16x16x32_bf16 v[124:127], v[144:147], v[178:181], v[124:127]
	v_mfma_f32_16x16x32_bf16 v[108:111], v[136:139], v[198:201], v[108:111]
	v_mfma_f32_16x16x32_bf16 v[104:107], v[144:147], v[198:201], v[104:107]
	v_mfma_f32_16x16x32_bf16 v[92:95], v[136:139], v[206:209], v[92:95]
	v_mfma_f32_16x16x32_bf16 v[88:91], v[144:147], v[206:209], v[88:91]
	v_mfma_f32_16x16x32_bf16 v[76:79], v[136:139], v[214:217], v[76:79]
	v_mfma_f32_16x16x32_bf16 v[72:75], v[144:147], v[214:217], v[72:75]
	v_mfma_f32_16x16x32_bf16 v[120:123], v[148:151], v[174:177], v[120:123]
	v_mfma_f32_16x16x32_bf16 v[116:119], v[166:169], v[174:177], v[116:119]
	v_mfma_f32_16x16x32_bf16 v[100:103], v[148:151], v[182:185], v[100:103]
	v_mfma_f32_16x16x32_bf16 v[96:99], v[166:169], v[182:185], v[96:99]
	v_mfma_f32_16x16x32_bf16 v[84:87], v[148:151], v[202:205], v[84:87]
	v_mfma_f32_16x16x32_bf16 v[80:83], v[166:169], v[202:205], v[80:83]
	v_mfma_f32_16x16x32_bf16 v[68:71], v[148:151], v[210:213], v[68:71]
	v_mfma_f32_16x16x32_bf16 v[64:67], v[166:169], v[210:213], v[64:67]
	v_mfma_f32_16x16x32_bf16 v[120:123], v[152:155], v[178:181], v[120:123]
	v_mfma_f32_16x16x32_bf16 v[116:119], v[170:173], v[178:181], v[116:119]
	v_mfma_f32_16x16x32_bf16 v[100:103], v[152:155], v[198:201], v[100:103]
	v_mfma_f32_16x16x32_bf16 v[96:99], v[170:173], v[198:201], v[96:99]
	v_mfma_f32_16x16x32_bf16 v[84:87], v[152:155], v[206:209], v[84:87]
	v_mfma_f32_16x16x32_bf16 v[80:83], v[170:173], v[206:209], v[80:83]
	v_mfma_f32_16x16x32_bf16 v[68:71], v[152:155], v[214:217], v[68:71]
	v_mfma_f32_16x16x32_bf16 v[64:67], v[170:173], v[214:217], v[64:67]
	s_setprio 0
	s_barrier
	s_add_i32 s69, s69, s37
	v_lshl_add_u64 v[186:187], s[44:45], 0, v[156:157]
	s_mov_b32 m0, s69
	ds_read_b128 v[174:177], v248 offset:16384
	ds_read_b128 v[178:181], v248 offset:17408
	ds_read_b128 v[182:185], v248 offset:18432
	ds_read_b128 v[198:201], v248 offset:19456
	ds_read_b128 v[202:205], v248 offset:20480
	ds_read_b128 v[206:209], v248 offset:21504
	ds_read_b128 v[210:213], v248 offset:22528
	ds_read_b128 v[214:217], v248 offset:23552
	global_load_lds_dwordx4 v[186:187], off
	s_add_i32 m0, s69, 0x2000
	s_add_u32 s70, s44, 0x40000
	v_lshl_add_u64 v[188:189], s[44:45], 0, v[160:161]
	s_addc_u32 s71, s45, 0
	s_add_i32 s1, s1, s37
	global_load_lds_dwordx4 v[188:189], off
	v_lshl_add_u64 v[190:191], s[70:71], 0, v[156:157]
	s_mov_b32 m0, s1
	v_lshl_add_u64 v[192:193], s[64:65], 0, v[158:159]
	global_load_lds_dwordx4 v[190:191], off
	v_lshl_add_u64 v[190:191], s[70:71], 0, v[160:161]
	s_add_i32 m0, s1, 0x2000
	s_nop 0
	global_load_lds_dwordx4 v[190:191], off
	v_lshl_add_u64 v[190:191], s[64:65], 0, v[112:113]
	s_mov_b32 m0, s72
	s_nop 0
	global_load_lds_dwordx4 v[190:191], off
	s_mov_b32 m0, s73
	s_nop 0
	global_load_lds_dwordx4 v[192:193], off
	s_waitcnt vmcnt(8)
	s_waitcnt lgkmcnt(0)
	s_barrier
; #define PG8_STAGE(bufoff, gbase, voff) do { _Pragma("unroll") for (int _i = 0; _i < 2; ++_i) \
;         __builtin_amdgcn_global_load_lds((const unsigned*)((const char*)(gbase) + (voff)[_i]), (PG8_LAS unsigned*)(lds + (bufoff) + ldsw + _i * 8192), 16, 0, 0); } while (0)
; #define PG8_LDA(dst, b, h) do { _Pragma("unroll") for (int m = 0; m < 4; ++m) _Pragma("unroll") for (int k = 0; k < 2; ++k) dst[m][k] = *(const PG8_LAS bf16x8*)(lds + PG8_SA(b, h) + aoff + m * 2048 + k * 1024); } while (0)
; #define PG8_LDB(dst, b, h) do { _Pragma("unroll") for (int n = 0; n < 2; ++n) _Pragma("unroll") for (int k = 0; k < 2; ++k) dst[n][k] = *(const PG8_LAS bf16x8*)(lds + PG8_SB(b, h) + boff + n * 2048 + k * 1024); } while (0)
; #define PG8_MMA(ai, bj, At, Bt) do { __builtin_amdgcn_s_setprio(1); _Pragma("unroll") for (int m = 0; m < 4; ++m) _Pragma("unroll") for (int n = 0; n < 2; ++n) _Pragma("unroll") for (int k = 0; k < 2; ++k) \
;         acc[ai][bj][m][n] = __builtin_amdgcn_mfma_f32_16x16x32_bf16(Bt[n][k], At[m][k], acc[ai][bj][m][n], 0, 0, 0); __builtin_amdgcn_s_setprio(0); } while (0)
; #define PG8_WAIT_V(n) asm volatile("s_waitcnt vmcnt(" #n ")" ::: "memory")
; #define PG8_WAIT_L(n) asm volatile("s_waitcnt lgkmcnt(" #n ")" ::: "memory")
; #define PG8_BAR __builtin_amdgcn_s_barrier()
; #define PG8_SCHED __builtin_amdgcn_sched_barrier(0)
; template <class Epi, class Sched, bool ALIGN_EPI = false, bool SP2 = false>
; __device__ __forceinline__ void gemm_phase(PG8_LAS unsigned char* lds, const Gemm g, const Sched& S, const Epi& E, const int wv) {
;     ...
;             PG8_WAIT_V(8); PG8_WAIT_L(0); PG8_BAR; PG8_MMA(1, 0, At, B0); PG8_MMA(1, 1, At, B1); PG8_BAR; PG8_SCHED;
;             PG8_LDB(B0, 1, 0); PG8_LDB(B1, 1, 1); PG8_SCHED; PG8_LDA(At, 1, 0); PG8_STAGE(PG8_SA(0, 1), a2 + hstepA, voffA);
;             PG8_WAIT_V(8); PG8_WAIT_L(0); PG8_BAR; PG8_MMA(0, 0, At, B0); PG8_MMA(0, 1, At, B1); PG8_BAR; PG8_SCHED;
	s_setprio 1
	s_waitcnt lgkmcnt(0)
	v_mfma_f32_16x16x32_bf16 v[60:63], v[132:135], v[174:177], v[60:63]
	v_mfma_f32_16x16x32_bf16 v[56:59], v[140:143], v[174:177], v[56:59]
	v_mfma_f32_16x16x32_bf16 v[44:47], v[132:135], v[182:185], v[44:47]
	v_mfma_f32_16x16x32_bf16 v[40:43], v[140:143], v[182:185], v[40:43]
	v_mfma_f32_16x16x32_bf16 v[28:31], v[132:135], v[202:205], v[28:31]
	v_mfma_f32_16x16x32_bf16 v[24:27], v[140:143], v[202:205], v[24:27]
	v_mfma_f32_16x16x32_bf16 v[12:15], v[132:135], v[210:213], v[12:15]
	v_mfma_f32_16x16x32_bf16 v[8:11], v[140:143], v[210:213], v[8:11]
	v_mfma_f32_16x16x32_bf16 v[60:63], v[136:139], v[178:181], v[60:63]
	v_mfma_f32_16x16x32_bf16 v[56:59], v[144:147], v[178:181], v[56:59]
	v_mfma_f32_16x16x32_bf16 v[44:47], v[136:139], v[198:201], v[44:47]
	v_mfma_f32_16x16x32_bf16 v[40:43], v[144:147], v[198:201], v[40:43]
	v_mfma_f32_16x16x32_bf16 v[28:31], v[136:139], v[206:209], v[28:31]
	v_mfma_f32_16x16x32_bf16 v[24:27], v[144:147], v[206:209], v[24:27]
	v_mfma_f32_16x16x32_bf16 v[12:15], v[136:139], v[214:217], v[12:15]
	v_mfma_f32_16x16x32_bf16 v[8:11], v[144:147], v[214:217], v[8:11]
	v_mfma_f32_16x16x32_bf16 v[52:55], v[148:151], v[174:177], v[52:55]
	v_mfma_f32_16x16x32_bf16 v[48:51], v[166:169], v[174:177], v[48:51]
	v_mfma_f32_16x16x32_bf16 v[36:39], v[148:151], v[182:185], v[36:39]
	v_mfma_f32_16x16x32_bf16 v[32:35], v[166:169], v[182:185], v[32:35]
	v_mfma_f32_16x16x32_bf16 v[20:23], v[148:151], v[202:205], v[20:23]
	v_mfma_f32_16x16x32_bf16 v[16:19], v[166:169], v[202:205], v[16:19]
	v_mfma_f32_16x16x32_bf16 v[4:7], v[148:151], v[210:213], v[4:7]
	v_mfma_f32_16x16x32_bf16 v[0:3], v[166:169], v[210:213], v[0:3]
	v_mfma_f32_16x16x32_bf16 v[52:55], v[152:155], v[178:181], v[52:55]
	v_mfma_f32_16x16x32_bf16 v[48:51], v[170:173], v[178:181], v[48:51]
	v_mfma_f32_16x16x32_bf16 v[36:39], v[152:155], v[198:201], v[36:39]
	v_mfma_f32_16x16x32_bf16 v[32:35], v[170:173], v[198:201], v[32:35]
	v_mfma_f32_16x16x32_bf16 v[20:23], v[152:155], v[206:209], v[20:23]
	v_mfma_f32_16x16x32_bf16 v[16:19], v[170:173], v[206:209], v[16:19]
	v_mfma_f32_16x16x32_bf16 v[4:7], v[152:155], v[214:217], v[4:7]
	v_mfma_f32_16x16x32_bf16 v[0:3], v[170:173], v[214:217], v[0:3]
	s_setprio 0
	s_barrier
	s_add_i32 s1, 0, 0x18000
	v_add_u32_e32 v114, s1, v247
	s_add_i32 s69, 0, 0x1c000
	ds_read_b128 v[132:135], v114
	ds_read_b128 v[136:139], v114 offset:1024
	ds_read_b128 v[140:143], v114 offset:2048
	ds_read_b128 v[144:147], v114 offset:3072
	v_add_u32_e32 v114, s69, v247
	ds_read_b128 v[148:151], v114
	ds_read_b128 v[152:155], v114 offset:1024
	ds_read_b128 v[166:169], v114 offset:2048
	ds_read_b128 v[170:173], v114 offset:3072
	s_add_u32 s64, s64, 0x40000
	s_addc_u32 s65, s65, 0
	s_mov_b32 m0, s74
	v_lshl_add_u64 v[218:219], s[64:65], 0, v[112:113]
	ds_read_b128 v[174:177], v248 offset:32768
	ds_read_b128 v[178:181], v248 offset:33792
	ds_read_b128 v[182:185], v248 offset:34816
	ds_read_b128 v[198:201], v248 offset:35840
	ds_read_b128 v[202:205], v248 offset:36864
	ds_read_b128 v[206:209], v248 offset:37888
	ds_read_b128 v[210:213], v248 offset:38912
	ds_read_b128 v[214:217], v248 offset:39936
	global_load_lds_dwordx4 v[218:219], off
	v_lshl_add_u64 v[218:219], s[64:65], 0, v[158:159]
	s_mov_b32 m0, s75
	s_nop 0
	global_load_lds_dwordx4 v[218:219], off
	s_waitcnt vmcnt(8)
	s_waitcnt lgkmcnt(0)
	s_barrier
	s_setprio 1
	s_waitcnt lgkmcnt(0)
	v_mfma_f32_16x16x32_bf16 v[128:131], v[132:135], v[174:177], v[128:131]
	v_mfma_f32_16x16x32_bf16 v[124:127], v[140:143], v[174:177], v[124:127]
	v_mfma_f32_16x16x32_bf16 v[108:111], v[132:135], v[182:185], v[108:111]
	v_mfma_f32_16x16x32_bf16 v[104:107], v[140:143], v[182:185], v[104:107]
	v_mfma_f32_16x16x32_bf16 v[92:95], v[132:135], v[202:205], v[92:95]
	v_mfma_f32_16x16x32_bf16 v[88:91], v[140:143], v[202:205], v[88:91]
	v_mfma_f32_16x16x32_bf16 v[76:79], v[132:135], v[210:213], v[76:79]
	v_mfma_f32_16x16x32_bf16 v[72:75], v[140:143], v[210:213], v[72:75]
	v_mfma_f32_16x16x32_bf16 v[128:131], v[136:139], v[178:181], v[128:131]
	v_mfma_f32_16x16x32_bf16 v[124:127], v[144:147], v[178:181], v[124:127]
	v_mfma_f32_16x16x32_bf16 v[108:111], v[136:139], v[198:201], v[108:111]
	v_mfma_f32_16x16x32_bf16 v[104:107], v[144:147], v[198:201], v[104:107]
	v_mfma_f32_16x16x32_bf16 v[92:95], v[136:139], v[206:209], v[92:95]
	v_mfma_f32_16x16x32_bf16 v[88:91], v[144:147], v[206:209], v[88:91]
	v_mfma_f32_16x16x32_bf16 v[76:79], v[136:139], v[214:217], v[76:79]
	v_mfma_f32_16x16x32_bf16 v[72:75], v[144:147], v[214:217], v[72:75]
	v_mfma_f32_16x16x32_bf16 v[120:123], v[148:151], v[174:177], v[120:123]
	v_mfma_f32_16x16x32_bf16 v[116:119], v[166:169], v[174:177], v[116:119]
	v_mfma_f32_16x16x32_bf16 v[100:103], v[148:151], v[182:185], v[100:103]
	v_mfma_f32_16x16x32_bf16 v[96:99], v[166:169], v[182:185], v[96:99]
	v_mfma_f32_16x16x32_bf16 v[84:87], v[148:151], v[202:205], v[84:87]
	v_mfma_f32_16x16x32_bf16 v[80:83], v[166:169], v[202:205], v[80:83]
	v_mfma_f32_16x16x32_bf16 v[68:71], v[148:151], v[210:213], v[68:71]
	v_mfma_f32_16x16x32_bf16 v[64:67], v[166:169], v[210:213], v[64:67]
	v_mfma_f32_16x16x32_bf16 v[120:123], v[152:155], v[178:181], v[120:123]
	v_mfma_f32_16x16x32_bf16 v[116:119], v[170:173], v[178:181], v[116:119]
	v_mfma_f32_16x16x32_bf16 v[100:103], v[152:155], v[198:201], v[100:103]
	v_mfma_f32_16x16x32_bf16 v[96:99], v[170:173], v[198:201], v[96:99]
	v_mfma_f32_16x16x32_bf16 v[84:87], v[152:155], v[206:209], v[84:87]
	v_mfma_f32_16x16x32_bf16 v[80:83], v[170:173], v[206:209], v[80:83]
	v_mfma_f32_16x16x32_bf16 v[68:71], v[152:155], v[214:217], v[68:71]
	v_mfma_f32_16x16x32_bf16 v[64:67], v[170:173], v[214:217], v[64:67]
	s_setprio 0
	s_barrier
; #define PG8_STAGE(bufoff, gbase, voff) do { _Pragma("unroll") for (int _i = 0; _i < 2; ++_i) \
;         __builtin_amdgcn_global_load_lds((const unsigned*)((const char*)(gbase) + (voff)[_i]), (PG8_LAS unsigned*)(lds + (bufoff) + ldsw + _i * 8192), 16, 0, 0); } while (0)
; #define PG8_LDA(dst, b, h) do { _Pragma("unroll") for (int m = 0; m < 4; ++m) _Pragma("unroll") for (int k = 0; k < 2; ++k) dst[m][k] = *(const PG8_LAS bf16x8*)(lds + PG8_SA(b, h) + aoff + m * 2048 + k * 1024); } while (0)
; #define PG8_MMA(ai, bj, At, Bt) do { __builtin_amdgcn_s_setprio(1); _Pragma("unroll") for (int m = 0; m < 4; ++m) _Pragma("unroll") for (int n = 0; n < 2; ++n) _Pragma("unroll") for (int k = 0; k < 2; ++k) \
;         acc[ai][bj][m][n] = __builtin_amdgcn_mfma_f32_16x16x32_bf16(Bt[n][k], At[m][k], acc[ai][bj][m][n], 0, 0, 0); __builtin_amdgcn_s_setprio(0); } while (0)
; #define PG8_WAIT_V(n) asm volatile("s_waitcnt vmcnt(" #n ")" ::: "memory")
; #define PG8_WAIT_L(n) asm volatile("s_waitcnt lgkmcnt(" #n ")" ::: "memory")
; #define PG8_BAR __builtin_amdgcn_s_barrier()
; #define PG8_SCHED __builtin_amdgcn_sched_barrier(0)
; template <class Epi, class Sched, bool ALIGN_EPI = false, bool SP2 = false>
; __device__ __forceinline__ void gemm_phase(PG8_LAS unsigned char* lds, const Gemm g, const Sched& S, const Epi& E, const int wv) {
;     ...
;             PG8_LDA(At, 1, 1); PG8_STAGE(PG8_SB(1, 0), b3, voffB); PG8_STAGE(PG8_SB(1, 1), b3 + hstepB, voffB); PG8_STAGE(PG8_SA(1, 0), a3, voffA);
;             PG8_WAIT_V(8); PG8_WAIT_L(0); PG8_BAR; PG8_MMA(1, 0, At, B0); PG8_MMA(1, 1, At, B1); PG8_BAR; PG8_SCHED;
	s_add_i32 s1, s1, s37
	v_lshl_add_u64 v[186:187], v[186:187], 0, s[28:29]
	s_mov_b32 m0, s1
	ds_read_b128 v[174:177], v248 offset:49152
	ds_read_b128 v[178:181], v248 offset:50176
	ds_read_b128 v[182:185], v248 offset:51200
	ds_read_b128 v[198:201], v248 offset:52224
	ds_read_b128 v[202:205], v248 offset:53248
	ds_read_b128 v[206:209], v248 offset:54272
	ds_read_b128 v[210:213], v248 offset:55296
	ds_read_b128 v[214:217], v248 offset:56320
	global_load_lds_dwordx4 v[186:187], off
	s_add_i32 m0, s1, 0x2000
	s_add_u32 s44, s44, 0x40080
	v_lshl_add_u64 v[186:187], v[188:189], 0, s[28:29]
	s_addc_u32 s45, s45, 0
	s_add_i32 s1, s69, s37
	global_load_lds_dwordx4 v[186:187], off
	v_lshl_add_u64 v[186:187], s[44:45], 0, v[156:157]
	s_mov_b32 m0, s1
	s_nop 0
	global_load_lds_dwordx4 v[186:187], off
	v_lshl_add_u64 v[186:187], s[44:45], 0, v[160:161]
	s_add_i32 m0, s1, 0x2000
	s_nop 0
	global_load_lds_dwordx4 v[186:187], off
	v_lshl_add_u64 v[186:187], v[190:191], 0, s[28:29]
	s_mov_b32 m0, s79
	s_nop 0
	global_load_lds_dwordx4 v[186:187], off
	v_lshl_add_u64 v[186:187], v[192:193], 0, s[28:29]
	s_mov_b32 m0, s80
	s_nop 0
	global_load_lds_dwordx4 v[186:187], off
	s_waitcnt vmcnt(8)
	s_waitcnt lgkmcnt(0)
	s_barrier
	s_setprio 1
	s_waitcnt lgkmcnt(0)
	v_mfma_f32_16x16x32_bf16 v[60:63], v[132:135], v[174:177], v[60:63]
	v_mfma_f32_16x16x32_bf16 v[56:59], v[140:143], v[174:177], v[56:59]
	v_mfma_f32_16x16x32_bf16 v[44:47], v[132:135], v[182:185], v[44:47]
	v_mfma_f32_16x16x32_bf16 v[40:43], v[140:143], v[182:185], v[40:43]
	v_mfma_f32_16x16x32_bf16 v[28:31], v[132:135], v[202:205], v[28:31]
	v_mfma_f32_16x16x32_bf16 v[24:27], v[140:143], v[202:205], v[24:27]
	v_mfma_f32_16x16x32_bf16 v[12:15], v[132:135], v[210:213], v[12:15]
	v_mfma_f32_16x16x32_bf16 v[8:11], v[140:143], v[210:213], v[8:11]
	v_mfma_f32_16x16x32_bf16 v[60:63], v[136:139], v[178:181], v[60:63]
	v_mfma_f32_16x16x32_bf16 v[56:59], v[144:147], v[178:181], v[56:59]
	v_mfma_f32_16x16x32_bf16 v[44:47], v[136:139], v[198:201], v[44:47]
	v_mfma_f32_16x16x32_bf16 v[40:43], v[144:147], v[198:201], v[40:43]
	v_mfma_f32_16x16x32_bf16 v[28:31], v[136:139], v[206:209], v[28:31]
	v_mfma_f32_16x16x32_bf16 v[24:27], v[144:147], v[206:209], v[24:27]
	v_mfma_f32_16x16x32_bf16 v[12:15], v[136:139], v[214:217], v[12:15]
	v_mfma_f32_16x16x32_bf16 v[8:11], v[144:147], v[214:217], v[8:11]
	v_mfma_f32_16x16x32_bf16 v[52:55], v[148:151], v[174:177], v[52:55]
	v_mfma_f32_16x16x32_bf16 v[48:51], v[166:169], v[174:177], v[48:51]
	v_mfma_f32_16x16x32_bf16 v[36:39], v[148:151], v[182:185], v[36:39]
	v_mfma_f32_16x16x32_bf16 v[32:35], v[166:169], v[182:185], v[32:35]
	v_mfma_f32_16x16x32_bf16 v[20:23], v[148:151], v[202:205], v[20:23]
	v_mfma_f32_16x16x32_bf16 v[16:19], v[166:169], v[202:205], v[16:19]
	v_mfma_f32_16x16x32_bf16 v[4:7], v[148:151], v[210:213], v[4:7]
	v_mfma_f32_16x16x32_bf16 v[0:3], v[166:169], v[210:213], v[0:3]
	v_mfma_f32_16x16x32_bf16 v[52:55], v[152:155], v[178:181], v[52:55]
	v_mfma_f32_16x16x32_bf16 v[48:51], v[170:173], v[178:181], v[48:51]
	v_mfma_f32_16x16x32_bf16 v[36:39], v[152:155], v[198:201], v[36:39]
	v_mfma_f32_16x16x32_bf16 v[32:35], v[170:173], v[198:201], v[32:35]
	v_mfma_f32_16x16x32_bf16 v[20:23], v[152:155], v[206:209], v[20:23]
	v_mfma_f32_16x16x32_bf16 v[16:19], v[170:173], v[206:209], v[16:19]
	v_mfma_f32_16x16x32_bf16 v[4:7], v[152:155], v[214:217], v[4:7]
	v_mfma_f32_16x16x32_bf16 v[0:3], v[170:173], v[214:217], v[0:3]
	s_setprio 0
	s_barrier
	s_add_i32 s68, s68, 2
	s_add_u32 s40, s40, 0x100
	s_addc_u32 s41, s41, 0
	s_add_u32 s66, s66, 0x100
	s_addc_u32 s67, s67, 0
	s_cmp_gt_u32 s68, 13
	s_cbranch_scc0 .LBB0_208
	s_and_b64 vcc, exec, s[52:53]
	s_cbranch_vccz .LBB0_211
	s_barrier

; #define PG8_STAGE(bufoff, gbase, voff) do { _Pragma("unroll") for (int _i = 0; _i < 2; ++_i) \
;         __builtin_amdgcn_global_load_lds((const unsigned*)((const char*)(gbase) + (voff)[_i]), (PG8_LAS unsigned*)(lds + (bufoff) + ldsw + _i * 8192), 16, 0, 0); } while (0)
; #define PG8_LDA(dst, b, h) do { _Pragma("unroll") for (int m = 0; m < 4; ++m) _Pragma("unroll") for (int k = 0; k < 2; ++k) dst[m][k] = *(const PG8_LAS bf16x8*)(lds + PG8_SA(b, h) + aoff + m * 2048 + k * 1024); } while (0)
; #define PG8_LDB(dst, b, h) do { _Pragma("unroll") for (int n = 0; n < 2; ++n) _Pragma("unroll") for (int k = 0; k < 2; ++k) dst[n][k] = *(const PG8_LAS bf16x8*)(lds + PG8_SB(b, h) + boff + n * 2048 + k * 1024); } while (0)
; #define PG8_MMA(ai, bj, At, Bt) do { __builtin_amdgcn_s_setprio(1); _Pragma("unroll") for (int m = 0; m < 4; ++m) _Pragma("unroll") for (int n = 0; n < 2; ++n) _Pragma("unroll") for (int k = 0; k < 2; ++k) \
;         acc[ai][bj][m][n] = __builtin_amdgcn_mfma_f32_16x16x32_bf16(Bt[n][k], At[m][k], acc[ai][bj][m][n], 0, 0, 0); __builtin_amdgcn_s_setprio(0); } while (0)
; #define PG8_WAIT_V(n) asm volatile("s_waitcnt vmcnt(" #n ")" ::: "memory")
; #define PG8_WAIT_L(n) asm volatile("s_waitcnt lgkmcnt(" #n ")" ::: "memory")
; #define PG8_BAR __builtin_amdgcn_s_barrier()
; #define PG8_SCHED __builtin_amdgcn_sched_barrier(0)
; template <class Epi, class Sched, bool ALIGN_EPI = false, bool SP2 = false>
; __device__ __forceinline__ void gemm_phase(PG8_LAS unsigned char* lds, const Gemm g, const Sched& S, const Epi& E, const int wv) {
;     ...
;             const bool last = (t == nt - 2);
;             const char* a1 = cA + (size_t)(t + 1) * kstep;
;             const char* a2 = last ? nA : cA + (size_t)(t + 2) * kstep; const char* b2 = last ? nB : cB + (size_t)(t + 2) * kstep;
;             const char* a3 = a2 + kstep; const char* b3 = b2 + kstep;
;             if (last && has_next) S.a_ready(nxt);
;             if constexpr (SP2) {
;             PG8_LDB(B0, 0, 0); PG8_LDB(B1, 0, 1); PG8_SCHED; PG8_LDA(At, 0, 0); PG8_STAGE(PG8_SA(1, 1), a1 + hstepA, voffA);
;             PG8_WAIT_V(8); PG8_WAIT_L(0); PG8_BAR; PG8_MMA(0, 0, At, B0); PG8_MMA(0, 1, At, B1); PG8_BAR; PG8_SCHED;
;             PG8_LDA(At, 0, 1); PG8_STAGE(PG8_SB(0, 0), b2, voffB); PG8_STAGE(PG8_SB(0, 1), b2 + hstepB, voffB); PG8_STAGE(PG8_SA(0, 0), a2, voffA);
.LBB0_329:
	s_add_u32 s1, s4, 0xfffc0080
	s_addc_u32 s40, s5, -1
	s_add_i32 s68, 0, 0x10000
	s_cmp_eq_u32 s67, 12
	s_cselect_b32 s45, s31, s40
	s_cselect_b32 s44, s46, s1
	s_cselect_b32 s41, s21, s66
	s_cselect_b32 s40, s47, s65
	s_add_i32 s1, 0, 0x14000
	v_add_u32_e32 v44, s68, v208
	v_add_u32_e32 v114, s1, v208
	ds_read_b128 v[28:31], v44
	ds_read_b128 v[32:35], v44 offset:1024
	ds_read_b128 v[36:39], v44 offset:2048
	ds_read_b128 v[44:47], v44 offset:3072
	ds_read_b128 v[160:163], v114
	ds_read_b128 v[164:167], v114 offset:1024
	ds_read_b128 v[168:171], v114 offset:2048
	ds_read_b128 v[172:175], v114 offset:3072
	v_lshl_add_u64 v[116:117], s[4:5], 0, v[156:157]
	s_add_i32 m0, s51, 0xc000
	ds_read_b128 v[176:179], v209
	ds_read_b128 v[180:183], v209 offset:1024
	ds_read_b128 v[198:201], v209 offset:2048
	ds_read_b128 v[202:205], v209 offset:3072
	ds_read_b128 v[210:213], v209 offset:4096
	ds_read_b128 v[214:217], v209 offset:5120
	ds_read_b128 v[218:221], v209 offset:6144
	ds_read_b128 v[222:225], v209 offset:7168
	global_load_lds_dwordx4 v[116:117], off
	v_lshl_add_u64 v[116:117], s[4:5], 0, v[158:159]
	s_add_i32 m0, s51, 0xe000
	s_nop 0
	global_load_lds_dwordx4 v[116:117], off
	s_waitcnt vmcnt(8)
	s_waitcnt lgkmcnt(0)
	s_barrier
	s_setprio 1
	s_waitcnt lgkmcnt(0)
	v_mfma_f32_16x16x32_bf16 v[52:55], v[28:31], v[176:179], v[52:55]
	v_mfma_f32_16x16x32_bf16 v[24:27], v[36:39], v[176:179], v[24:27]
	v_mfma_f32_16x16x32_bf16 v[146:149], v[28:31], v[198:201], v[146:149]
	v_mfma_f32_16x16x32_bf16 v[142:145], v[36:39], v[198:201], v[142:145]
	v_mfma_f32_16x16x32_bf16 v[130:133], v[28:31], v[210:213], v[130:133]
	v_mfma_f32_16x16x32_bf16 v[126:129], v[36:39], v[210:213], v[126:129]
	v_mfma_f32_16x16x32_bf16 v[108:111], v[28:31], v[218:221], v[108:111]
	v_mfma_f32_16x16x32_bf16 v[104:107], v[36:39], v[218:221], v[104:107]
	v_mfma_f32_16x16x32_bf16 v[52:55], v[32:35], v[180:183], v[52:55]
	v_mfma_f32_16x16x32_bf16 v[24:27], v[44:47], v[180:183], v[24:27]
	v_mfma_f32_16x16x32_bf16 v[146:149], v[32:35], v[202:205], v[146:149]
	v_mfma_f32_16x16x32_bf16 v[142:145], v[44:47], v[202:205], v[142:145]
	v_mfma_f32_16x16x32_bf16 v[130:133], v[32:35], v[214:217], v[130:133]
	v_mfma_f32_16x16x32_bf16 v[126:129], v[44:47], v[214:217], v[126:129]
	v_mfma_f32_16x16x32_bf16 v[108:111], v[32:35], v[222:225], v[108:111]
	v_mfma_f32_16x16x32_bf16 v[104:107], v[44:47], v[222:225], v[104:107]
	v_mfma_f32_16x16x32_bf16 v[20:23], v[160:163], v[176:179], v[20:23]
	v_mfma_f32_16x16x32_bf16 v[16:19], v[168:171], v[176:179], v[16:19]
	v_mfma_f32_16x16x32_bf16 v[138:141], v[160:163], v[198:201], v[138:141]
	v_mfma_f32_16x16x32_bf16 v[134:137], v[168:171], v[198:201], v[134:137]
	v_mfma_f32_16x16x32_bf16 v[122:125], v[160:163], v[210:213], v[122:125]
	v_mfma_f32_16x16x32_bf16 v[116:119], v[168:171], v[210:213], v[118:121]
	v_mfma_f32_16x16x32_bf16 v[100:103], v[160:163], v[218:221], v[100:103]
	v_mfma_f32_16x16x32_bf16 v[96:99], v[168:171], v[218:221], v[96:99]
	v_mfma_f32_16x16x32_bf16 v[20:23], v[164:167], v[180:183], v[20:23]
	v_mfma_f32_16x16x32_bf16 v[16:19], v[172:175], v[180:183], v[16:19]
	v_mfma_f32_16x16x32_bf16 v[138:141], v[164:167], v[202:205], v[138:141]
	v_mfma_f32_16x16x32_bf16 v[134:137], v[172:175], v[202:205], v[134:137]
	v_mfma_f32_16x16x32_bf16 v[122:125], v[164:167], v[214:217], v[122:125]
	v_mfma_f32_16x16x32_bf16 v[116:119], v[172:175], v[214:217], v[116:119]
	v_mfma_f32_16x16x32_bf16 v[100:103], v[164:167], v[222:225], v[100:103]
	v_mfma_f32_16x16x32_bf16 v[96:99], v[172:175], v[222:225], v[96:99]
	s_setprio 0
	s_barrier
	s_add_i32 s68, s68, s37
	v_lshl_add_u64 v[184:185], s[40:41], 0, v[150:151]
	s_mov_b32 m0, s68
	ds_read_b128 v[176:179], v209 offset:16384
	ds_read_b128 v[180:183], v209 offset:17408
	ds_read_b128 v[198:201], v209 offset:18432
	ds_read_b128 v[202:205], v209 offset:19456
	ds_read_b128 v[210:213], v209 offset:20480
	ds_read_b128 v[214:217], v209 offset:21504
	ds_read_b128 v[218:221], v209 offset:22528
	ds_read_b128 v[222:225], v209 offset:23552
	global_load_lds_dwordx4 v[184:185], off
	s_add_i32 m0, s68, 0x2000
	s_add_u32 s68, s40, 0x40000
	v_lshl_add_u64 v[186:187], s[40:41], 0, v[154:155]
	s_addc_u32 s69, s41, 0
	s_add_i32 s1, s1, s37
	global_load_lds_dwordx4 v[186:187], off
	v_lshl_add_u64 v[120:121], s[68:69], 0, v[150:151]
	s_mov_b32 m0, s1
	v_lshl_add_u64 v[188:189], s[44:45], 0, v[112:113]
	global_load_lds_dwordx4 v[120:121], off
	v_lshl_add_u64 v[120:121], s[68:69], 0, v[154:155]
	s_add_i32 m0, s1, 0x2000
	v_lshl_add_u64 v[190:191], s[44:45], 0, v[152:153]
	global_load_lds_dwordx4 v[120:121], off
	s_mov_b32 m0, s51
	s_nop 0
	global_load_lds_dwordx4 v[188:189], off
	s_mov_b32 m0, s53
	s_nop 0
	global_load_lds_dwordx4 v[190:191], off
	s_waitcnt vmcnt(8)
	s_waitcnt lgkmcnt(0)
	s_barrier
; #define PG8_STAGE(bufoff, gbase, voff) do { _Pragma("unroll") for (int _i = 0; _i < 2; ++_i) \
;         __builtin_amdgcn_global_load_lds((const unsigned*)((const char*)(gbase) + (voff)[_i]), (PG8_LAS unsigned*)(lds + (bufoff) + ldsw + _i * 8192), 16, 0, 0); } while (0)
; #define PG8_LDA(dst, b, h) do { _Pragma("unroll") for (int m = 0; m < 4; ++m) _Pragma("unroll") for (int k = 0; k < 2; ++k) dst[m][k] = *(const PG8_LAS bf16x8*)(lds + PG8_SA(b, h) + aoff + m * 2048 + k * 1024); } while (0)
; #define PG8_LDB(dst, b, h) do { _Pragma("unroll") for (int n = 0; n < 2; ++n) _Pragma("unroll") for (int k = 0; k < 2; ++k) dst[n][k] = *(const PG8_LAS bf16x8*)(lds + PG8_SB(b, h) + boff + n * 2048 + k * 1024); } while (0)
; #define PG8_MMA(ai, bj, At, Bt) do { __builtin_amdgcn_s_setprio(1); _Pragma("unroll") for (int m = 0; m < 4; ++m) _Pragma("unroll") for (int n = 0; n < 2; ++n) _Pragma("unroll") for (int k = 0; k < 2; ++k) \
;         acc[ai][bj][m][n] = __builtin_amdgcn_mfma_f32_16x16x32_bf16(Bt[n][k], At[m][k], acc[ai][bj][m][n], 0, 0, 0); __builtin_amdgcn_s_setprio(0); } while (0)
; #define PG8_WAIT_V(n) asm volatile("s_waitcnt vmcnt(" #n ")" ::: "memory")
; #define PG8_WAIT_L(n) asm volatile("s_waitcnt lgkmcnt(" #n ")" ::: "memory")
; #define PG8_BAR __builtin_amdgcn_s_barrier()
; #define PG8_SCHED __builtin_amdgcn_sched_barrier(0)
; template <class Epi, class Sched, bool ALIGN_EPI = false, bool SP2 = false>
; __device__ __forceinline__ void gemm_phase(PG8_LAS unsigned char* lds, const Gemm g, const Sched& S, const Epi& E, const int wv) {
;     ...
;             PG8_WAIT_V(8); PG8_WAIT_L(0); PG8_BAR; PG8_MMA(1, 0, At, B0); PG8_MMA(1, 1, At, B1); PG8_BAR; PG8_SCHED;
;             PG8_LDB(B0, 1, 0); PG8_LDB(B1, 1, 1); PG8_SCHED; PG8_LDA(At, 1, 0); PG8_STAGE(PG8_SA(0, 1), a2 + hstepA, voffA);
;             PG8_WAIT_V(8); PG8_WAIT_L(0); PG8_BAR; PG8_MMA(0, 0, At, B0); PG8_MMA(0, 1, At, B1); PG8_BAR; PG8_SCHED;
	s_setprio 1
	s_waitcnt lgkmcnt(0)
	v_mfma_f32_16x16x32_bf16 v[92:95], v[28:31], v[176:179], v[92:95]
	v_mfma_f32_16x16x32_bf16 v[88:91], v[36:39], v[176:179], v[88:91]
	v_mfma_f32_16x16x32_bf16 v[76:79], v[28:31], v[198:201], v[76:79]
	v_mfma_f32_16x16x32_bf16 v[72:75], v[36:39], v[198:201], v[72:75]
	v_mfma_f32_16x16x32_bf16 v[60:63], v[28:31], v[210:213], v[60:63]
	v_mfma_f32_16x16x32_bf16 v[56:59], v[36:39], v[210:213], v[56:59]
	v_mfma_f32_16x16x32_bf16 v[12:15], v[28:31], v[218:221], v[12:15]
	v_mfma_f32_16x16x32_bf16 v[8:11], v[36:39], v[218:221], v[8:11]
	v_mfma_f32_16x16x32_bf16 v[92:95], v[32:35], v[180:183], v[92:95]
	v_mfma_f32_16x16x32_bf16 v[88:91], v[44:47], v[180:183], v[88:91]
	v_mfma_f32_16x16x32_bf16 v[76:79], v[32:35], v[202:205], v[76:79]
	v_mfma_f32_16x16x32_bf16 v[72:75], v[44:47], v[202:205], v[72:75]
	v_mfma_f32_16x16x32_bf16 v[60:63], v[32:35], v[214:217], v[60:63]
	v_mfma_f32_16x16x32_bf16 v[56:59], v[44:47], v[214:217], v[56:59]
	v_mfma_f32_16x16x32_bf16 v[12:15], v[32:35], v[222:225], v[12:15]
	v_mfma_f32_16x16x32_bf16 v[8:11], v[44:47], v[222:225], v[8:11]
	v_mfma_f32_16x16x32_bf16 v[48:51], v[160:163], v[210:213], v[48:51]
	v_mfma_f32_16x16x32_bf16 v[40:43], v[168:171], v[210:213], v[40:43]
	v_mfma_f32_16x16x32_bf16 v[4:7], v[160:163], v[218:221], v[4:7]
	v_mfma_f32_16x16x32_bf16 v[0:3], v[168:171], v[218:221], v[0:3]
	v_mfma_f32_16x16x32_bf16 v[28:31], v[160:163], v[176:179], v[84:87]
	v_mfma_f32_16x16x32_bf16 v[32:35], v[168:171], v[176:179], v[80:83]
	v_mfma_f32_16x16x32_bf16 v[36:39], v[160:163], v[198:201], v[68:71]
	v_mfma_f32_16x16x32_bf16 v[44:47], v[168:171], v[198:201], v[64:67]
	v_mfma_f32_16x16x32_bf16 v[48:51], v[164:167], v[214:217], v[48:51]
	v_mfma_f32_16x16x32_bf16 v[40:43], v[172:175], v[214:217], v[40:43]
	v_mfma_f32_16x16x32_bf16 v[4:7], v[164:167], v[222:225], v[4:7]
	v_mfma_f32_16x16x32_bf16 v[0:3], v[172:175], v[222:225], v[0:3]
	v_mfma_f32_16x16x32_bf16 v[28:31], v[164:167], v[180:183], v[28:31]
	v_mfma_f32_16x16x32_bf16 v[32:35], v[172:175], v[180:183], v[32:35]
	v_mfma_f32_16x16x32_bf16 v[36:39], v[164:167], v[202:205], v[36:39]
	v_mfma_f32_16x16x32_bf16 v[44:47], v[172:175], v[202:205], v[44:47]
	s_setprio 0
	s_barrier
	s_add_i32 s1, 0, 0x18000
	s_add_i32 s68, 0, 0x1c000
	v_add_u32_e32 v84, s1, v208
	v_add_u32_e32 v114, s68, v208
	ds_read_b128 v[64:67], v84
	ds_read_b128 v[68:71], v84 offset:1024
	ds_read_b128 v[80:83], v84 offset:2048
	ds_read_b128 v[84:87], v84 offset:3072
	ds_read_b128 v[160:163], v114
	ds_read_b128 v[164:167], v114 offset:1024
	ds_read_b128 v[168:171], v114 offset:2048
	ds_read_b128 v[172:175], v114 offset:3072
	s_add_u32 s44, s44, 0x40000
	s_addc_u32 s45, s45, 0
	s_mov_b32 m0, s54
	v_lshl_add_u64 v[120:121], s[44:45], 0, v[112:113]
	ds_read_b128 v[176:179], v209 offset:32768
	ds_read_b128 v[180:183], v209 offset:33792
	ds_read_b128 v[198:201], v209 offset:34816
	ds_read_b128 v[202:205], v209 offset:35840
	ds_read_b128 v[210:213], v209 offset:36864
	ds_read_b128 v[214:217], v209 offset:37888
	ds_read_b128 v[218:221], v209 offset:38912
	ds_read_b128 v[222:225], v209 offset:39936
	global_load_lds_dwordx4 v[120:121], off
	v_lshl_add_u64 v[120:121], s[44:45], 0, v[152:153]
	s_mov_b32 m0, s55
	s_nop 0
	global_load_lds_dwordx4 v[120:121], off
	s_waitcnt vmcnt(8)
	s_waitcnt lgkmcnt(0)
	s_barrier
	s_setprio 1
	s_waitcnt lgkmcnt(0)
	v_mfma_f32_16x16x32_bf16 v[52:55], v[64:67], v[176:179], v[52:55]
	v_mfma_f32_16x16x32_bf16 v[24:27], v[80:83], v[176:179], v[24:27]
	v_mfma_f32_16x16x32_bf16 v[146:149], v[64:67], v[198:201], v[146:149]
	v_mfma_f32_16x16x32_bf16 v[142:145], v[80:83], v[198:201], v[142:145]
	v_mfma_f32_16x16x32_bf16 v[130:133], v[64:67], v[210:213], v[130:133]
	v_mfma_f32_16x16x32_bf16 v[126:129], v[80:83], v[210:213], v[126:129]
	v_mfma_f32_16x16x32_bf16 v[108:111], v[64:67], v[218:221], v[108:111]
	v_mfma_f32_16x16x32_bf16 v[104:107], v[80:83], v[218:221], v[104:107]
	v_mfma_f32_16x16x32_bf16 v[52:55], v[68:71], v[180:183], v[52:55]
	v_mfma_f32_16x16x32_bf16 v[24:27], v[84:87], v[180:183], v[24:27]
	v_mfma_f32_16x16x32_bf16 v[146:149], v[68:71], v[202:205], v[146:149]
	v_mfma_f32_16x16x32_bf16 v[142:145], v[84:87], v[202:205], v[142:145]
	v_mfma_f32_16x16x32_bf16 v[130:133], v[68:71], v[214:217], v[130:133]
	v_mfma_f32_16x16x32_bf16 v[126:129], v[84:87], v[214:217], v[126:129]
	v_mfma_f32_16x16x32_bf16 v[108:111], v[68:71], v[222:225], v[108:111]
	v_mfma_f32_16x16x32_bf16 v[104:107], v[84:87], v[222:225], v[104:107]
	v_mfma_f32_16x16x32_bf16 v[20:23], v[160:163], v[176:179], v[20:23]
	v_mfma_f32_16x16x32_bf16 v[16:19], v[168:171], v[176:179], v[16:19]
	v_mfma_f32_16x16x32_bf16 v[138:141], v[160:163], v[198:201], v[138:141]
	v_mfma_f32_16x16x32_bf16 v[134:137], v[168:171], v[198:201], v[134:137]
	v_mfma_f32_16x16x32_bf16 v[120:123], v[160:163], v[210:213], v[122:125]
	v_mfma_f32_16x16x32_bf16 v[116:119], v[168:171], v[210:213], v[116:119]
	v_mfma_f32_16x16x32_bf16 v[100:103], v[160:163], v[218:221], v[100:103]
	v_mfma_f32_16x16x32_bf16 v[96:99], v[168:171], v[218:221], v[96:99]
	v_mfma_f32_16x16x32_bf16 v[20:23], v[164:167], v[180:183], v[20:23]
	v_mfma_f32_16x16x32_bf16 v[16:19], v[172:175], v[180:183], v[16:19]
	v_mfma_f32_16x16x32_bf16 v[138:141], v[164:167], v[202:205], v[138:141]
	v_mfma_f32_16x16x32_bf16 v[134:137], v[172:175], v[202:205], v[134:137]
	v_mfma_f32_16x16x32_bf16 v[122:125], v[164:167], v[214:217], v[120:123]
	v_mfma_f32_16x16x32_bf16 v[118:121], v[172:175], v[214:217], v[116:119]
	v_mfma_f32_16x16x32_bf16 v[100:103], v[164:167], v[222:225], v[100:103]
	v_mfma_f32_16x16x32_bf16 v[96:99], v[172:175], v[222:225], v[96:99]
	s_setprio 0
	s_barrier
; #define PG8_STAGE(bufoff, gbase, voff) do { _Pragma("unroll") for (int _i = 0; _i < 2; ++_i) \
;         __builtin_amdgcn_global_load_lds((const unsigned*)((const char*)(gbase) + (voff)[_i]), (PG8_LAS unsigned*)(lds + (bufoff) + ldsw + _i * 8192), 16, 0, 0); } while (0)
; #define PG8_LDA(dst, b, h) do { _Pragma("unroll") for (int m = 0; m < 4; ++m) _Pragma("unroll") for (int k = 0; k < 2; ++k) dst[m][k] = *(const PG8_LAS bf16x8*)(lds + PG8_SA(b, h) + aoff + m * 2048 + k * 1024); } while (0)
; #define PG8_MMA(ai, bj, At, Bt) do { __builtin_amdgcn_s_setprio(1); _Pragma("unroll") for (int m = 0; m < 4; ++m) _Pragma("unroll") for (int n = 0; n < 2; ++n) _Pragma("unroll") for (int k = 0; k < 2; ++k) \
;         acc[ai][bj][m][n] = __builtin_amdgcn_mfma_f32_16x16x32_bf16(Bt[n][k], At[m][k], acc[ai][bj][m][n], 0, 0, 0); __builtin_amdgcn_s_setprio(0); } while (0)
; #define PG8_WAIT_V(n) asm volatile("s_waitcnt vmcnt(" #n ")" ::: "memory")
; #define PG8_WAIT_L(n) asm volatile("s_waitcnt lgkmcnt(" #n ")" ::: "memory")
; #define PG8_BAR __builtin_amdgcn_s_barrier()
; #define PG8_SCHED __builtin_amdgcn_sched_barrier(0)
; template <class Epi, class Sched, bool ALIGN_EPI = false, bool SP2 = false>
; __device__ __forceinline__ void gemm_phase(PG8_LAS unsigned char* lds, const Gemm g, const Sched& S, const Epi& E, const int wv) {
;     ...
;             PG8_LDA(At, 1, 1); PG8_STAGE(PG8_SB(1, 0), b3, voffB); PG8_STAGE(PG8_SB(1, 1), b3 + hstepB, voffB); PG8_STAGE(PG8_SA(1, 0), a3, voffA);
;             PG8_WAIT_V(8); PG8_WAIT_L(0); PG8_BAR; PG8_MMA(1, 0, At, B0); PG8_MMA(1, 1, At, B1); PG8_BAR; PG8_SCHED;
	s_add_i32 s1, s1, s37
	v_lshl_add_u64 v[116:117], v[184:185], 0, s[28:29]
	s_mov_b32 m0, s1
	ds_read_b128 v[176:179], v209 offset:49152
	ds_read_b128 v[180:183], v209 offset:50176
	ds_read_b128 v[198:201], v209 offset:51200
	ds_read_b128 v[202:205], v209 offset:52224
	ds_read_b128 v[210:213], v209 offset:53248
	ds_read_b128 v[214:217], v209 offset:54272
	ds_read_b128 v[218:221], v209 offset:55296
	ds_read_b128 v[222:225], v209 offset:56320
	global_load_lds_dwordx4 v[116:117], off
	s_add_i32 m0, s1, 0x2000
	s_add_u32 s40, s40, 0x40080
	v_lshl_add_u64 v[116:117], v[186:187], 0, s[28:29]
	s_addc_u32 s41, s41, 0
	s_add_i32 s1, s68, s37
	global_load_lds_dwordx4 v[116:117], off
	v_lshl_add_u64 v[116:117], s[40:41], 0, v[150:151]
	s_mov_b32 m0, s1
	s_nop 0
	global_load_lds_dwordx4 v[116:117], off
	v_lshl_add_u64 v[116:117], s[40:41], 0, v[154:155]
	s_add_i32 m0, s1, 0x2000
	s_nop 0
	global_load_lds_dwordx4 v[116:117], off
	v_lshl_add_u64 v[116:117], v[188:189], 0, s[28:29]
	s_mov_b32 m0, s58
	s_nop 0
	global_load_lds_dwordx4 v[116:117], off
	v_lshl_add_u64 v[116:117], v[190:191], 0, s[28:29]
	s_mov_b32 m0, s59
	s_nop 0
	global_load_lds_dwordx4 v[116:117], off
	s_waitcnt vmcnt(8)
	s_waitcnt lgkmcnt(0)
	s_barrier
	s_setprio 1
	s_waitcnt lgkmcnt(0)
	v_mfma_f32_16x16x32_bf16 v[92:95], v[64:67], v[176:179], v[92:95]
	v_mfma_f32_16x16x32_bf16 v[88:91], v[80:83], v[176:179], v[88:91]
	v_mfma_f32_16x16x32_bf16 v[76:79], v[64:67], v[198:201], v[76:79]
	v_mfma_f32_16x16x32_bf16 v[72:75], v[80:83], v[198:201], v[72:75]
	v_mfma_f32_16x16x32_bf16 v[60:63], v[64:67], v[210:213], v[60:63]
	v_mfma_f32_16x16x32_bf16 v[56:59], v[80:83], v[210:213], v[56:59]
	v_mfma_f32_16x16x32_bf16 v[12:15], v[64:67], v[218:221], v[12:15]
	v_mfma_f32_16x16x32_bf16 v[8:11], v[80:83], v[218:221], v[8:11]
	v_mfma_f32_16x16x32_bf16 v[92:95], v[68:71], v[180:183], v[92:95]
	v_mfma_f32_16x16x32_bf16 v[88:91], v[84:87], v[180:183], v[88:91]
	v_mfma_f32_16x16x32_bf16 v[76:79], v[68:71], v[202:205], v[76:79]
	v_mfma_f32_16x16x32_bf16 v[72:75], v[84:87], v[202:205], v[72:75]
	v_mfma_f32_16x16x32_bf16 v[60:63], v[68:71], v[214:217], v[60:63]
	v_mfma_f32_16x16x32_bf16 v[56:59], v[84:87], v[214:217], v[56:59]
	v_mfma_f32_16x16x32_bf16 v[12:15], v[68:71], v[222:225], v[12:15]
	v_mfma_f32_16x16x32_bf16 v[8:11], v[84:87], v[222:225], v[8:11]
	v_mfma_f32_16x16x32_bf16 v[28:31], v[160:163], v[176:179], v[28:31]
	v_mfma_f32_16x16x32_bf16 v[84:87], v[164:167], v[180:183], v[28:31]
	v_mfma_f32_16x16x32_bf16 v[28:31], v[168:171], v[176:179], v[32:35]
	v_mfma_f32_16x16x32_bf16 v[80:83], v[172:175], v[180:183], v[28:31]
	v_mfma_f32_16x16x32_bf16 v[28:31], v[160:163], v[198:201], v[36:39]
	v_mfma_f32_16x16x32_bf16 v[68:71], v[164:167], v[202:205], v[28:31]
	v_mfma_f32_16x16x32_bf16 v[28:31], v[168:171], v[198:201], v[44:47]
	v_mfma_f32_16x16x32_bf16 v[64:67], v[172:175], v[202:205], v[28:31]
	v_mfma_f32_16x16x32_bf16 v[28:31], v[160:163], v[210:213], v[48:51]
	v_mfma_f32_16x16x32_bf16 v[48:51], v[164:167], v[214:217], v[28:31]
	v_mfma_f32_16x16x32_bf16 v[28:31], v[168:171], v[210:213], v[40:43]
	v_mfma_f32_16x16x32_bf16 v[4:7], v[160:163], v[218:221], v[4:7]
	v_mfma_f32_16x16x32_bf16 v[0:3], v[168:171], v[218:221], v[0:3]
	v_mfma_f32_16x16x32_bf16 v[40:43], v[172:175], v[214:217], v[28:31]
	v_mfma_f32_16x16x32_bf16 v[4:7], v[164:167], v[222:225], v[4:7]
	v_mfma_f32_16x16x32_bf16 v[0:3], v[172:175], v[222:225], v[0:3]
	s_setprio 0
	s_barrier
	s_add_i32 s67, s67, 2
	s_add_u32 s4, s4, 0x100
	s_addc_u32 s5, s5, 0
	s_add_u32 s65, s65, 0x100
	s_addc_u32 s66, s66, 0
	s_cmp_gt_u32 s67, 13
	s_cbranch_scc0 .LBB0_329
	s_and_b64 vcc, exec, s[18:19]
	s_cbranch_vccz .LBB0_332
	s_barrier

; #define PG8_STAGE(bufoff, gbase, voff) do { _Pragma("unroll") for (int _i = 0; _i < 2; ++_i) \
;         __builtin_amdgcn_global_load_lds((const unsigned*)((const char*)(gbase) + (voff)[_i]), (PG8_LAS unsigned*)(lds + (bufoff) + ldsw + _i * 8192), 16, 0, 0); } while (0)
; #define PG8_LDA(dst, b, h) do { _Pragma("unroll") for (int m = 0; m < 4; ++m) _Pragma("unroll") for (int k = 0; k < 2; ++k) dst[m][k] = *(const PG8_LAS bf16x8*)(lds + PG8_SA(b, h) + aoff + m * 2048 + k * 1024); } while (0)
; #define PG8_LDB(dst, b, h) do { _Pragma("unroll") for (int n = 0; n < 2; ++n) _Pragma("unroll") for (int k = 0; k < 2; ++k) dst[n][k] = *(const PG8_LAS bf16x8*)(lds + PG8_SB(b, h) + boff + n * 2048 + k * 1024); } while (0)
; #define PG8_MMA(ai, bj, At, Bt) do { __builtin_amdgcn_s_setprio(1); _Pragma("unroll") for (int m = 0; m < 4; ++m) _Pragma("unroll") for (int n = 0; n < 2; ++n) _Pragma("unroll") for (int k = 0; k < 2; ++k) \
;         acc[ai][bj][m][n] = __builtin_amdgcn_mfma_f32_16x16x32_bf16(Bt[n][k], At[m][k], acc[ai][bj][m][n], 0, 0, 0); __builtin_amdgcn_s_setprio(0); } while (0)
; #define PG8_WAIT_V(n) asm volatile("s_waitcnt vmcnt(" #n ")" ::: "memory")
; #define PG8_WAIT_L(n) asm volatile("s_waitcnt lgkmcnt(" #n ")" ::: "memory")
; #define PG8_BAR __builtin_amdgcn_s_barrier()
; #define PG8_SCHED __builtin_amdgcn_sched_barrier(0)
; template <class Epi, class Sched, bool ALIGN_EPI = false, bool SP2 = false>
; __device__ __forceinline__ void gemm_phase(PG8_LAS unsigned char* lds, const Gemm g, const Sched& S, const Epi& E, const int wv) {
;     ...
;             const bool last = (t == nt - 2);
;             const char* a1 = cA + (size_t)(t + 1) * kstep;
;             const char* a2 = last ? nA : cA + (size_t)(t + 2) * kstep; const char* b2 = last ? nB : cB + (size_t)(t + 2) * kstep;
;             const char* a3 = a2 + kstep; const char* b3 = b2 + kstep;
;             if (last && has_next) S.a_ready(nxt);
;             if constexpr (SP2) {
;             PG8_LDB(B0, 0, 0); PG8_LDB(B1, 0, 1); PG8_SCHED; PG8_LDA(At, 0, 0); PG8_STAGE(PG8_SA(1, 1), a1 + hstepA, voffA);
;             PG8_WAIT_V(8); PG8_WAIT_L(0); PG8_BAR; PG8_MMA(0, 0, At, B0); PG8_MMA(0, 1, At, B1); PG8_BAR; PG8_SCHED;
;             PG8_LDA(At, 0, 1); PG8_STAGE(PG8_SB(0, 0), b2, voffB); PG8_STAGE(PG8_SB(0, 1), b2 + hstepB, voffB); PG8_STAGE(PG8_SA(0, 0), a2, voffA);
.LBB0_504:
	s_add_u32 s1, s4, 0xfffc0080
	s_addc_u32 s30, s5, -1
	s_add_i32 s54, 0, 0x10000
	s_cmp_eq_u32 s53, 28
	s_cselect_b32 s39, s47, s30
	s_cselect_b32 s38, s48, s1
	s_cselect_b32 s31, s49, s52
	s_cselect_b32 s30, s50, s51
	s_add_i32 s1, 0, 0x14000
	v_add_u32_e32 v154, s54, v152
	v_add_u32_e32 v170, s1, v152
	ds_read_b128 v[132:135], v154
	ds_read_b128 v[144:147], v154 offset:1024
	ds_read_b128 v[148:151], v154 offset:2048
	ds_read_b128 v[154:157], v154 offset:3072
	ds_read_b128 v[158:161], v170
	ds_read_b128 v[162:165], v170 offset:1024
	ds_read_b128 v[166:169], v170 offset:2048
	ds_read_b128 v[170:173], v170 offset:3072
	v_lshl_add_u64 v[210:211], s[4:5], 0, v[140:141]
	s_add_i32 m0, s7, 0xc000
	ds_read_b128 v[174:177], v153
	ds_read_b128 v[178:181], v153 offset:1024
	ds_read_b128 v[182:185], v153 offset:2048
	ds_read_b128 v[186:189], v153 offset:3072
	ds_read_b128 v[190:193], v153 offset:4096
	ds_read_b128 v[198:201], v153 offset:5120
	ds_read_b128 v[202:205], v153 offset:6144
	ds_read_b128 v[206:209], v153 offset:7168
	global_load_lds_dwordx4 v[210:211], off
	v_lshl_add_u64 v[210:211], s[4:5], 0, v[142:143]
	s_add_i32 m0, s7, 0xe000
	s_nop 0
	global_load_lds_dwordx4 v[210:211], off
	s_waitcnt vmcnt(8)
	s_waitcnt lgkmcnt(0)
	s_barrier
	s_setprio 1
	s_waitcnt lgkmcnt(0)
	v_mfma_f32_16x16x32_bf16 v[128:131], v[132:135], v[174:177], v[128:131]
	v_mfma_f32_16x16x32_bf16 v[124:127], v[148:151], v[174:177], v[124:127]
	v_mfma_f32_16x16x32_bf16 v[108:111], v[132:135], v[182:185], v[108:111]
	v_mfma_f32_16x16x32_bf16 v[104:107], v[148:151], v[182:185], v[104:107]
	v_mfma_f32_16x16x32_bf16 v[92:95], v[132:135], v[190:193], v[92:95]
	v_mfma_f32_16x16x32_bf16 v[88:91], v[148:151], v[190:193], v[88:91]
	v_mfma_f32_16x16x32_bf16 v[76:79], v[132:135], v[202:205], v[76:79]
	v_mfma_f32_16x16x32_bf16 v[72:75], v[148:151], v[202:205], v[72:75]
	v_mfma_f32_16x16x32_bf16 v[128:131], v[144:147], v[178:181], v[128:131]
	v_mfma_f32_16x16x32_bf16 v[124:127], v[154:157], v[178:181], v[124:127]
	v_mfma_f32_16x16x32_bf16 v[108:111], v[144:147], v[186:189], v[108:111]
	v_mfma_f32_16x16x32_bf16 v[104:107], v[154:157], v[186:189], v[104:107]
	v_mfma_f32_16x16x32_bf16 v[92:95], v[144:147], v[198:201], v[92:95]
	v_mfma_f32_16x16x32_bf16 v[88:91], v[154:157], v[198:201], v[88:91]
	v_mfma_f32_16x16x32_bf16 v[76:79], v[144:147], v[206:209], v[76:79]
	v_mfma_f32_16x16x32_bf16 v[72:75], v[154:157], v[206:209], v[72:75]
	v_mfma_f32_16x16x32_bf16 v[120:123], v[158:161], v[174:177], v[120:123]
	v_mfma_f32_16x16x32_bf16 v[116:119], v[166:169], v[174:177], v[116:119]
	v_mfma_f32_16x16x32_bf16 v[100:103], v[158:161], v[182:185], v[100:103]
	v_mfma_f32_16x16x32_bf16 v[96:99], v[166:169], v[182:185], v[96:99]
	v_mfma_f32_16x16x32_bf16 v[84:87], v[158:161], v[190:193], v[84:87]
	v_mfma_f32_16x16x32_bf16 v[80:83], v[166:169], v[190:193], v[80:83]
	v_mfma_f32_16x16x32_bf16 v[68:71], v[158:161], v[202:205], v[68:71]
	v_mfma_f32_16x16x32_bf16 v[64:67], v[166:169], v[202:205], v[64:67]
	v_mfma_f32_16x16x32_bf16 v[120:123], v[162:165], v[178:181], v[120:123]
	v_mfma_f32_16x16x32_bf16 v[116:119], v[170:173], v[178:181], v[116:119]
	v_mfma_f32_16x16x32_bf16 v[100:103], v[162:165], v[186:189], v[100:103]
	v_mfma_f32_16x16x32_bf16 v[96:99], v[170:173], v[186:189], v[96:99]
	v_mfma_f32_16x16x32_bf16 v[84:87], v[162:165], v[198:201], v[84:87]
	v_mfma_f32_16x16x32_bf16 v[80:83], v[170:173], v[198:201], v[80:83]
	v_mfma_f32_16x16x32_bf16 v[68:71], v[162:165], v[206:209], v[68:71]
	v_mfma_f32_16x16x32_bf16 v[64:67], v[170:173], v[206:209], v[64:67]
	s_setprio 0
	s_barrier
	s_add_i32 s54, s54, s3
	v_lshl_add_u64 v[210:211], s[30:31], 0, v[114:115]
	s_mov_b32 m0, s54
	ds_read_b128 v[174:177], v153 offset:16384
	ds_read_b128 v[178:181], v153 offset:17408
	ds_read_b128 v[182:185], v153 offset:18432
	ds_read_b128 v[186:189], v153 offset:19456
	ds_read_b128 v[190:193], v153 offset:20480
	ds_read_b128 v[198:201], v153 offset:21504
	ds_read_b128 v[202:205], v153 offset:22528
	ds_read_b128 v[206:209], v153 offset:23552
	global_load_lds_dwordx4 v[210:211], off
	s_add_i32 m0, s54, 0x2000
	s_add_u32 s54, s30, 0x80000
	v_lshl_add_u64 v[212:213], s[30:31], 0, v[112:113]
	s_addc_u32 s55, s31, 0
	s_add_i32 s1, s1, s3
	global_load_lds_dwordx4 v[212:213], off
	v_lshl_add_u64 v[214:215], s[54:55], 0, v[114:115]
	s_mov_b32 m0, s1
	v_lshl_add_u64 v[216:217], s[38:39], 0, v[136:137]
	global_load_lds_dwordx4 v[214:215], off
	v_lshl_add_u64 v[214:215], s[54:55], 0, v[112:113]
	s_add_i32 m0, s1, 0x2000
	s_nop 0
	global_load_lds_dwordx4 v[214:215], off
	v_lshl_add_u64 v[214:215], s[38:39], 0, v[138:139]
	s_mov_b32 m0, s7
	s_nop 0
	global_load_lds_dwordx4 v[214:215], off
	s_mov_b32 m0, s33
	s_nop 0
	global_load_lds_dwordx4 v[216:217], off
	s_waitcnt vmcnt(8)
	s_waitcnt lgkmcnt(0)
	s_barrier
; #define PG8_STAGE(bufoff, gbase, voff) do { _Pragma("unroll") for (int _i = 0; _i < 2; ++_i) \
;         __builtin_amdgcn_global_load_lds((const unsigned*)((const char*)(gbase) + (voff)[_i]), (PG8_LAS unsigned*)(lds + (bufoff) + ldsw + _i * 8192), 16, 0, 0); } while (0)
; #define PG8_LDA(dst, b, h) do { _Pragma("unroll") for (int m = 0; m < 4; ++m) _Pragma("unroll") for (int k = 0; k < 2; ++k) dst[m][k] = *(const PG8_LAS bf16x8*)(lds + PG8_SA(b, h) + aoff + m * 2048 + k * 1024); } while (0)
; #define PG8_LDB(dst, b, h) do { _Pragma("unroll") for (int n = 0; n < 2; ++n) _Pragma("unroll") for (int k = 0; k < 2; ++k) dst[n][k] = *(const PG8_LAS bf16x8*)(lds + PG8_SB(b, h) + boff + n * 2048 + k * 1024); } while (0)
; #define PG8_MMA(ai, bj, At, Bt) do { __builtin_amdgcn_s_setprio(1); _Pragma("unroll") for (int m = 0; m < 4; ++m) _Pragma("unroll") for (int n = 0; n < 2; ++n) _Pragma("unroll") for (int k = 0; k < 2; ++k) \
;         acc[ai][bj][m][n] = __builtin_amdgcn_mfma_f32_16x16x32_bf16(Bt[n][k], At[m][k], acc[ai][bj][m][n], 0, 0, 0); __builtin_amdgcn_s_setprio(0); } while (0)
; #define PG8_WAIT_V(n) asm volatile("s_waitcnt vmcnt(" #n ")" ::: "memory")
; #define PG8_WAIT_L(n) asm volatile("s_waitcnt lgkmcnt(" #n ")" ::: "memory")
; #define PG8_BAR __builtin_amdgcn_s_barrier()
; #define PG8_SCHED __builtin_amdgcn_sched_barrier(0)
; template <class Epi, class Sched, bool ALIGN_EPI = false, bool SP2 = false>
; __device__ __forceinline__ void gemm_phase(PG8_LAS unsigned char* lds, const Gemm g, const Sched& S, const Epi& E, const int wv) {
;     ...
;             PG8_WAIT_V(8); PG8_WAIT_L(0); PG8_BAR; PG8_MMA(1, 0, At, B0); PG8_MMA(1, 1, At, B1); PG8_BAR; PG8_SCHED;
;             PG8_LDB(B0, 1, 0); PG8_LDB(B1, 1, 1); PG8_SCHED; PG8_LDA(At, 1, 0); PG8_STAGE(PG8_SA(0, 1), a2 + hstepA, voffA);
;             PG8_WAIT_V(8); PG8_WAIT_L(0); PG8_BAR; PG8_MMA(0, 0, At, B0); PG8_MMA(0, 1, At, B1); PG8_BAR; PG8_SCHED;
	s_setprio 1
	s_waitcnt lgkmcnt(0)
	v_mfma_f32_16x16x32_bf16 v[60:63], v[132:135], v[174:177], v[60:63]
	v_mfma_f32_16x16x32_bf16 v[56:59], v[148:151], v[174:177], v[56:59]
	v_mfma_f32_16x16x32_bf16 v[44:47], v[132:135], v[182:185], v[44:47]
	v_mfma_f32_16x16x32_bf16 v[40:43], v[148:151], v[182:185], v[40:43]
	v_mfma_f32_16x16x32_bf16 v[28:31], v[132:135], v[190:193], v[28:31]
	v_mfma_f32_16x16x32_bf16 v[24:27], v[148:151], v[190:193], v[24:27]
	v_mfma_f32_16x16x32_bf16 v[12:15], v[132:135], v[202:205], v[12:15]
	v_mfma_f32_16x16x32_bf16 v[8:11], v[148:151], v[202:205], v[8:11]
	v_mfma_f32_16x16x32_bf16 v[60:63], v[144:147], v[178:181], v[60:63]
	v_mfma_f32_16x16x32_bf16 v[56:59], v[154:157], v[178:181], v[56:59]
	v_mfma_f32_16x16x32_bf16 v[44:47], v[144:147], v[186:189], v[44:47]
	v_mfma_f32_16x16x32_bf16 v[40:43], v[154:157], v[186:189], v[40:43]
	v_mfma_f32_16x16x32_bf16 v[28:31], v[144:147], v[198:201], v[28:31]
	v_mfma_f32_16x16x32_bf16 v[24:27], v[154:157], v[198:201], v[24:27]
	v_mfma_f32_16x16x32_bf16 v[12:15], v[144:147], v[206:209], v[12:15]
	v_mfma_f32_16x16x32_bf16 v[8:11], v[154:157], v[206:209], v[8:11]
	v_mfma_f32_16x16x32_bf16 v[52:55], v[158:161], v[174:177], v[52:55]
	v_mfma_f32_16x16x32_bf16 v[48:51], v[166:169], v[174:177], v[48:51]
	v_mfma_f32_16x16x32_bf16 v[36:39], v[158:161], v[182:185], v[36:39]
	v_mfma_f32_16x16x32_bf16 v[32:35], v[166:169], v[182:185], v[32:35]
	v_mfma_f32_16x16x32_bf16 v[20:23], v[158:161], v[190:193], v[20:23]
	v_mfma_f32_16x16x32_bf16 v[16:19], v[166:169], v[190:193], v[16:19]
	v_mfma_f32_16x16x32_bf16 v[4:7], v[158:161], v[202:205], v[4:7]
	v_mfma_f32_16x16x32_bf16 v[0:3], v[166:169], v[202:205], v[0:3]
	v_mfma_f32_16x16x32_bf16 v[52:55], v[162:165], v[178:181], v[52:55]
	v_mfma_f32_16x16x32_bf16 v[48:51], v[170:173], v[178:181], v[48:51]
	v_mfma_f32_16x16x32_bf16 v[36:39], v[162:165], v[186:189], v[36:39]
	v_mfma_f32_16x16x32_bf16 v[32:35], v[170:173], v[186:189], v[32:35]
	v_mfma_f32_16x16x32_bf16 v[20:23], v[162:165], v[198:201], v[20:23]
	v_mfma_f32_16x16x32_bf16 v[16:19], v[170:173], v[198:201], v[16:19]
	v_mfma_f32_16x16x32_bf16 v[4:7], v[162:165], v[206:209], v[4:7]
	v_mfma_f32_16x16x32_bf16 v[0:3], v[170:173], v[206:209], v[0:3]
	s_setprio 0
	s_barrier
	s_add_i32 s1, 0, 0x18000
	s_add_i32 s54, 0, 0x1c000
	v_add_u32_e32 v154, s1, v152
	v_add_u32_e32 v170, s54, v152
	ds_read_b128 v[132:135], v154
	ds_read_b128 v[144:147], v154 offset:1024
	ds_read_b128 v[148:151], v154 offset:2048
	ds_read_b128 v[154:157], v154 offset:3072
	ds_read_b128 v[158:161], v170
	ds_read_b128 v[162:165], v170 offset:1024
	ds_read_b128 v[166:169], v170 offset:2048
	ds_read_b128 v[170:173], v170 offset:3072
	s_add_u32 s38, s38, 0x40000
	s_addc_u32 s39, s39, 0
	s_mov_b32 m0, s34
	v_lshl_add_u64 v[218:219], s[38:39], 0, v[138:139]
	ds_read_b128 v[174:177], v153 offset:32768
	ds_read_b128 v[178:181], v153 offset:33792
	ds_read_b128 v[182:185], v153 offset:34816
	ds_read_b128 v[186:189], v153 offset:35840
	ds_read_b128 v[190:193], v153 offset:36864
	ds_read_b128 v[198:201], v153 offset:37888
	ds_read_b128 v[202:205], v153 offset:38912
	ds_read_b128 v[206:209], v153 offset:39936
	global_load_lds_dwordx4 v[218:219], off
	v_lshl_add_u64 v[218:219], s[38:39], 0, v[136:137]
	s_mov_b32 m0, s35
	s_nop 0
	global_load_lds_dwordx4 v[218:219], off
	s_waitcnt vmcnt(8)
	s_waitcnt lgkmcnt(0)
	s_barrier
	s_setprio 1
	s_waitcnt lgkmcnt(0)
	v_mfma_f32_16x16x32_bf16 v[128:131], v[132:135], v[174:177], v[128:131]
	v_mfma_f32_16x16x32_bf16 v[124:127], v[148:151], v[174:177], v[124:127]
	v_mfma_f32_16x16x32_bf16 v[108:111], v[132:135], v[182:185], v[108:111]
	v_mfma_f32_16x16x32_bf16 v[104:107], v[148:151], v[182:185], v[104:107]
	v_mfma_f32_16x16x32_bf16 v[92:95], v[132:135], v[190:193], v[92:95]
	v_mfma_f32_16x16x32_bf16 v[88:91], v[148:151], v[190:193], v[88:91]
	v_mfma_f32_16x16x32_bf16 v[76:79], v[132:135], v[202:205], v[76:79]
	v_mfma_f32_16x16x32_bf16 v[72:75], v[148:151], v[202:205], v[72:75]
	v_mfma_f32_16x16x32_bf16 v[128:131], v[144:147], v[178:181], v[128:131]
	v_mfma_f32_16x16x32_bf16 v[124:127], v[154:157], v[178:181], v[124:127]
	v_mfma_f32_16x16x32_bf16 v[108:111], v[144:147], v[186:189], v[108:111]
	v_mfma_f32_16x16x32_bf16 v[104:107], v[154:157], v[186:189], v[104:107]
	v_mfma_f32_16x16x32_bf16 v[92:95], v[144:147], v[198:201], v[92:95]
	v_mfma_f32_16x16x32_bf16 v[88:91], v[154:157], v[198:201], v[88:91]
	v_mfma_f32_16x16x32_bf16 v[76:79], v[144:147], v[206:209], v[76:79]
	v_mfma_f32_16x16x32_bf16 v[72:75], v[154:157], v[206:209], v[72:75]
	v_mfma_f32_16x16x32_bf16 v[120:123], v[158:161], v[174:177], v[120:123]
	v_mfma_f32_16x16x32_bf16 v[116:119], v[166:169], v[174:177], v[116:119]
	v_mfma_f32_16x16x32_bf16 v[100:103], v[158:161], v[182:185], v[100:103]
	v_mfma_f32_16x16x32_bf16 v[96:99], v[166:169], v[182:185], v[96:99]
	v_mfma_f32_16x16x32_bf16 v[84:87], v[158:161], v[190:193], v[84:87]
	v_mfma_f32_16x16x32_bf16 v[80:83], v[166:169], v[190:193], v[80:83]
	v_mfma_f32_16x16x32_bf16 v[68:71], v[158:161], v[202:205], v[68:71]
	v_mfma_f32_16x16x32_bf16 v[64:67], v[166:169], v[202:205], v[64:67]
	v_mfma_f32_16x16x32_bf16 v[120:123], v[162:165], v[178:181], v[120:123]
	v_mfma_f32_16x16x32_bf16 v[116:119], v[170:173], v[178:181], v[116:119]
	v_mfma_f32_16x16x32_bf16 v[100:103], v[162:165], v[186:189], v[100:103]
	v_mfma_f32_16x16x32_bf16 v[96:99], v[170:173], v[186:189], v[96:99]
	v_mfma_f32_16x16x32_bf16 v[84:87], v[162:165], v[198:201], v[84:87]
	v_mfma_f32_16x16x32_bf16 v[80:83], v[170:173], v[198:201], v[80:83]
	v_mfma_f32_16x16x32_bf16 v[68:71], v[162:165], v[206:209], v[68:71]
	v_mfma_f32_16x16x32_bf16 v[64:67], v[170:173], v[206:209], v[64:67]
	s_setprio 0
	s_barrier
; #define PG8_STAGE(bufoff, gbase, voff) do { _Pragma("unroll") for (int _i = 0; _i < 2; ++_i) \
;         __builtin_amdgcn_global_load_lds((const unsigned*)((const char*)(gbase) + (voff)[_i]), (PG8_LAS unsigned*)(lds + (bufoff) + ldsw + _i * 8192), 16, 0, 0); } while (0)
; #define PG8_LDA(dst, b, h) do { _Pragma("unroll") for (int m = 0; m < 4; ++m) _Pragma("unroll") for (int k = 0; k < 2; ++k) dst[m][k] = *(const PG8_LAS bf16x8*)(lds + PG8_SA(b, h) + aoff + m * 2048 + k * 1024); } while (0)
; #define PG8_MMA(ai, bj, At, Bt) do { __builtin_amdgcn_s_setprio(1); _Pragma("unroll") for (int m = 0; m < 4; ++m) _Pragma("unroll") for (int n = 0; n < 2; ++n) _Pragma("unroll") for (int k = 0; k < 2; ++k) \
;         acc[ai][bj][m][n] = __builtin_amdgcn_mfma_f32_16x16x32_bf16(Bt[n][k], At[m][k], acc[ai][bj][m][n], 0, 0, 0); __builtin_amdgcn_s_setprio(0); } while (0)
; #define PG8_WAIT_V(n) asm volatile("s_waitcnt vmcnt(" #n ")" ::: "memory")
; #define PG8_WAIT_L(n) asm volatile("s_waitcnt lgkmcnt(" #n ")" ::: "memory")
; #define PG8_BAR __builtin_amdgcn_s_barrier()
; #define PG8_SCHED __builtin_amdgcn_sched_barrier(0)
; template <class Epi, class Sched, bool ALIGN_EPI = false, bool SP2 = false>
; __device__ __forceinline__ void gemm_phase(PG8_LAS unsigned char* lds, const Gemm g, const Sched& S, const Epi& E, const int wv) {
;     ...
;             PG8_LDA(At, 1, 1); PG8_STAGE(PG8_SB(1, 0), b3, voffB); PG8_STAGE(PG8_SB(1, 1), b3 + hstepB, voffB); PG8_STAGE(PG8_SA(1, 0), a3, voffA);
;             PG8_WAIT_V(8); PG8_WAIT_L(0); PG8_BAR; PG8_MMA(1, 0, At, B0); PG8_MMA(1, 1, At, B1); PG8_BAR; PG8_SCHED;
	s_add_i32 s1, s1, s3
	v_lshl_add_u64 v[210:211], v[210:211], 0, s[28:29]
	s_mov_b32 m0, s1
	ds_read_b128 v[174:177], v153 offset:49152
	ds_read_b128 v[178:181], v153 offset:50176
	ds_read_b128 v[182:185], v153 offset:51200
	ds_read_b128 v[186:189], v153 offset:52224
	ds_read_b128 v[190:193], v153 offset:53248
	ds_read_b128 v[198:201], v153 offset:54272
	ds_read_b128 v[202:205], v153 offset:55296
	ds_read_b128 v[206:209], v153 offset:56320
	global_load_lds_dwordx4 v[210:211], off
	s_add_i32 m0, s1, 0x2000
	s_add_u32 s30, s30, 0x80080
	v_lshl_add_u64 v[210:211], v[212:213], 0, s[28:29]
	s_addc_u32 s31, s31, 0
	s_add_i32 s1, s54, s3
	global_load_lds_dwordx4 v[210:211], off
	v_lshl_add_u64 v[210:211], s[30:31], 0, v[114:115]
	s_mov_b32 m0, s1
	s_nop 0
	global_load_lds_dwordx4 v[210:211], off
	v_lshl_add_u64 v[210:211], s[30:31], 0, v[112:113]
	s_add_i32 m0, s1, 0x2000
	s_nop 0
	global_load_lds_dwordx4 v[210:211], off
	v_lshl_add_u64 v[210:211], v[214:215], 0, s[28:29]
	s_mov_b32 m0, s37
	s_nop 0
	global_load_lds_dwordx4 v[210:211], off
	v_lshl_add_u64 v[210:211], v[216:217], 0, s[28:29]
	s_mov_b32 m0, s40
	s_nop 0
	global_load_lds_dwordx4 v[210:211], off
	s_waitcnt vmcnt(8)
	s_waitcnt lgkmcnt(0)
	s_barrier
	s_setprio 1
	s_waitcnt lgkmcnt(0)
	v_mfma_f32_16x16x32_bf16 v[60:63], v[132:135], v[174:177], v[60:63]
	v_mfma_f32_16x16x32_bf16 v[56:59], v[148:151], v[174:177], v[56:59]
	v_mfma_f32_16x16x32_bf16 v[44:47], v[132:135], v[182:185], v[44:47]
	v_mfma_f32_16x16x32_bf16 v[40:43], v[148:151], v[182:185], v[40:43]
	v_mfma_f32_16x16x32_bf16 v[28:31], v[132:135], v[190:193], v[28:31]
	v_mfma_f32_16x16x32_bf16 v[24:27], v[148:151], v[190:193], v[24:27]
	v_mfma_f32_16x16x32_bf16 v[12:15], v[132:135], v[202:205], v[12:15]
	v_mfma_f32_16x16x32_bf16 v[8:11], v[148:151], v[202:205], v[8:11]
	v_mfma_f32_16x16x32_bf16 v[60:63], v[144:147], v[178:181], v[60:63]
	v_mfma_f32_16x16x32_bf16 v[56:59], v[154:157], v[178:181], v[56:59]
	v_mfma_f32_16x16x32_bf16 v[44:47], v[144:147], v[186:189], v[44:47]
	v_mfma_f32_16x16x32_bf16 v[40:43], v[154:157], v[186:189], v[40:43]
	v_mfma_f32_16x16x32_bf16 v[28:31], v[144:147], v[198:201], v[28:31]
	v_mfma_f32_16x16x32_bf16 v[24:27], v[154:157], v[198:201], v[24:27]
	v_mfma_f32_16x16x32_bf16 v[12:15], v[144:147], v[206:209], v[12:15]
	v_mfma_f32_16x16x32_bf16 v[8:11], v[154:157], v[206:209], v[8:11]
	v_mfma_f32_16x16x32_bf16 v[52:55], v[158:161], v[174:177], v[52:55]
	v_mfma_f32_16x16x32_bf16 v[48:51], v[166:169], v[174:177], v[48:51]
	v_mfma_f32_16x16x32_bf16 v[36:39], v[158:161], v[182:185], v[36:39]
	v_mfma_f32_16x16x32_bf16 v[32:35], v[166:169], v[182:185], v[32:35]
	v_mfma_f32_16x16x32_bf16 v[20:23], v[158:161], v[190:193], v[20:23]
	v_mfma_f32_16x16x32_bf16 v[16:19], v[166:169], v[190:193], v[16:19]
	v_mfma_f32_16x16x32_bf16 v[4:7], v[158:161], v[202:205], v[4:7]
	v_mfma_f32_16x16x32_bf16 v[0:3], v[166:169], v[202:205], v[0:3]
	v_mfma_f32_16x16x32_bf16 v[52:55], v[162:165], v[178:181], v[52:55]
	v_mfma_f32_16x16x32_bf16 v[48:51], v[170:173], v[178:181], v[48:51]
	v_mfma_f32_16x16x32_bf16 v[36:39], v[162:165], v[186:189], v[36:39]
	v_mfma_f32_16x16x32_bf16 v[32:35], v[170:173], v[186:189], v[32:35]
	v_mfma_f32_16x16x32_bf16 v[20:23], v[162:165], v[198:201], v[20:23]
	v_mfma_f32_16x16x32_bf16 v[16:19], v[170:173], v[198:201], v[16:19]
	v_mfma_f32_16x16x32_bf16 v[4:7], v[162:165], v[206:209], v[4:7]
	v_mfma_f32_16x16x32_bf16 v[0:3], v[170:173], v[206:209], v[0:3]
	s_setprio 0
	s_barrier
	s_add_i32 s53, s53, 2
	s_add_u32 s4, s4, 0x100
	s_addc_u32 s5, s5, 0
	s_add_u32 s51, s51, 0x100
	s_addc_u32 s52, s52, 0
	s_cmp_gt_u32 s53, 29
	s_cbranch_scc0 .LBB0_504
	s_and_b64 vcc, exec, s[16:17]
	s_cbranch_vccz .LBB0_507
	s_barrier

; #define PG8_STAGE(bufoff, gbase, voff) do { _Pragma("unroll") for (int _i = 0; _i < 2; ++_i) \
;         __builtin_amdgcn_global_load_lds((const unsigned*)((const char*)(gbase) + (voff)[_i]), (PG8_LAS unsigned*)(lds + (bufoff) + ldsw + _i * 8192), 16, 0, 0); } while (0)
; #define PG8_LDA(dst, b, h) do { _Pragma("unroll") for (int m = 0; m < 4; ++m) _Pragma("unroll") for (int k = 0; k < 2; ++k) dst[m][k] = *(const PG8_LAS bf16x8*)(lds + PG8_SA(b, h) + aoff + m * 2048 + k * 1024); } while (0)
; #define PG8_LDB(dst, b, h) do { _Pragma("unroll") for (int n = 0; n < 2; ++n) _Pragma("unroll") for (int k = 0; k < 2; ++k) dst[n][k] = *(const PG8_LAS bf16x8*)(lds + PG8_SB(b, h) + boff + n * 2048 + k * 1024); } while (0)
; #define PG8_MMA(ai, bj, At, Bt) do { __builtin_amdgcn_s_setprio(1); _Pragma("unroll") for (int m = 0; m < 4; ++m) _Pragma("unroll") for (int n = 0; n < 2; ++n) _Pragma("unroll") for (int k = 0; k < 2; ++k) \
;         acc[ai][bj][m][n] = __builtin_amdgcn_mfma_f32_16x16x32_bf16(Bt[n][k], At[m][k], acc[ai][bj][m][n], 0, 0, 0); __builtin_amdgcn_s_setprio(0); } while (0)
; #define PG8_WAIT_V(n) asm volatile("s_waitcnt vmcnt(" #n ")" ::: "memory")
; #define PG8_WAIT_L(n) asm volatile("s_waitcnt lgkmcnt(" #n ")" ::: "memory")
; #define PG8_BAR __builtin_amdgcn_s_barrier()
; #define PG8_SCHED __builtin_amdgcn_sched_barrier(0)
; template <class Epi, class Sched, bool ALIGN_EPI = false, bool SP2 = false>
; __device__ __forceinline__ void gemm_phase(PG8_LAS unsigned char* lds, const Gemm g, const Sched& S, const Epi& E, const int wv) {
;     ...
;             const bool last = (t == nt - 2);
;             const char* a1 = cA + (size_t)(t + 1) * kstep;
;             const char* a2 = last ? nA : cA + (size_t)(t + 2) * kstep; const char* b2 = last ? nB : cB + (size_t)(t + 2) * kstep;
;             const char* a3 = a2 + kstep; const char* b3 = b2 + kstep;
;             if (last && has_next) S.a_ready(nxt);
;             if constexpr (SP2) {
;             PG8_LDB(B0, 0, 0); PG8_LDB(B1, 0, 1); PG8_SCHED; PG8_LDA(At, 0, 0); PG8_STAGE(PG8_SA(1, 1), a1 + hstepA, voffA);
;             PG8_WAIT_V(8); PG8_WAIT_L(0); PG8_BAR; PG8_MMA(0, 0, At, B0); PG8_MMA(0, 1, At, B1); PG8_BAR; PG8_SCHED;
;             PG8_LDA(At, 0, 1); PG8_STAGE(PG8_SB(0, 0), b2, voffB); PG8_STAGE(PG8_SB(0, 1), b2 + hstepB, voffB); PG8_STAGE(PG8_SA(0, 0), a2, voffA);
.LBB0_1281:
	s_add_u32 s1, s10, 0xfffc0080
	s_addc_u32 s12, s11, -1
	s_add_i32 s77, 0, 0x10000
	s_cmp_eq_u32 s76, 12
	s_cselect_b32 s61, s0, s12
	s_cselect_b32 s60, s5, s1
	s_cselect_b32 s13, s51, s75
	s_cselect_b32 s12, s53, s59
	s_add_i32 s1, 0, 0x14000
	v_add_u32_e32 v152, s77, v164
	v_add_u32_e32 v170, s1, v164
	ds_read_b128 v[132:135], v152
	ds_read_b128 v[136:139], v152 offset:1024
	ds_read_b128 v[148:151], v152 offset:2048
	ds_read_b128 v[152:155], v152 offset:3072
	ds_read_b128 v[156:159], v170
	ds_read_b128 v[160:163], v170 offset:1024
	ds_read_b128 v[166:169], v170 offset:2048
	ds_read_b128 v[170:173], v170 offset:3072
	v_lshl_add_u64 v[210:211], s[10:11], 0, v[144:145]
	s_add_i32 m0, s65, 0xc000
	ds_read_b128 v[174:177], v165
	ds_read_b128 v[178:181], v165 offset:1024
	ds_read_b128 v[182:185], v165 offset:2048
	ds_read_b128 v[186:189], v165 offset:3072
	ds_read_b128 v[190:193], v165 offset:4096
	ds_read_b128 v[198:201], v165 offset:5120
	ds_read_b128 v[202:205], v165 offset:6144
	ds_read_b128 v[206:209], v165 offset:7168
	global_load_lds_dwordx4 v[210:211], off
	v_lshl_add_u64 v[210:211], s[10:11], 0, v[146:147]
	s_add_i32 m0, s65, 0xe000
	s_nop 0
	global_load_lds_dwordx4 v[210:211], off
	s_waitcnt vmcnt(8)
	s_waitcnt lgkmcnt(0)
	s_barrier
	s_setprio 1
	s_waitcnt lgkmcnt(0)
	v_mfma_f32_16x16x32_bf16 v[128:131], v[132:135], v[174:177], v[128:131]
	v_mfma_f32_16x16x32_bf16 v[124:127], v[148:151], v[174:177], v[124:127]
	v_mfma_f32_16x16x32_bf16 v[108:111], v[132:135], v[182:185], v[108:111]
	v_mfma_f32_16x16x32_bf16 v[104:107], v[148:151], v[182:185], v[104:107]
	v_mfma_f32_16x16x32_bf16 v[92:95], v[132:135], v[190:193], v[92:95]
	v_mfma_f32_16x16x32_bf16 v[88:91], v[148:151], v[190:193], v[88:91]
	v_mfma_f32_16x16x32_bf16 v[76:79], v[132:135], v[202:205], v[76:79]
	v_mfma_f32_16x16x32_bf16 v[72:75], v[148:151], v[202:205], v[72:75]
	v_mfma_f32_16x16x32_bf16 v[128:131], v[136:139], v[178:181], v[128:131]
	v_mfma_f32_16x16x32_bf16 v[124:127], v[152:155], v[178:181], v[124:127]
	v_mfma_f32_16x16x32_bf16 v[108:111], v[136:139], v[186:189], v[108:111]
	v_mfma_f32_16x16x32_bf16 v[104:107], v[152:155], v[186:189], v[104:107]
	v_mfma_f32_16x16x32_bf16 v[92:95], v[136:139], v[198:201], v[92:95]
	v_mfma_f32_16x16x32_bf16 v[88:91], v[152:155], v[198:201], v[88:91]
	v_mfma_f32_16x16x32_bf16 v[76:79], v[136:139], v[206:209], v[76:79]
	v_mfma_f32_16x16x32_bf16 v[72:75], v[152:155], v[206:209], v[72:75]
	v_mfma_f32_16x16x32_bf16 v[120:123], v[156:159], v[174:177], v[120:123]
	v_mfma_f32_16x16x32_bf16 v[116:119], v[166:169], v[174:177], v[116:119]
	v_mfma_f32_16x16x32_bf16 v[100:103], v[156:159], v[182:185], v[100:103]
	v_mfma_f32_16x16x32_bf16 v[96:99], v[166:169], v[182:185], v[96:99]
	v_mfma_f32_16x16x32_bf16 v[84:87], v[156:159], v[190:193], v[84:87]
	v_mfma_f32_16x16x32_bf16 v[80:83], v[166:169], v[190:193], v[80:83]
	v_mfma_f32_16x16x32_bf16 v[68:71], v[156:159], v[202:205], v[68:71]
	v_mfma_f32_16x16x32_bf16 v[64:67], v[166:169], v[202:205], v[64:67]
	v_mfma_f32_16x16x32_bf16 v[120:123], v[160:163], v[178:181], v[120:123]
	v_mfma_f32_16x16x32_bf16 v[116:119], v[170:173], v[178:181], v[116:119]
	v_mfma_f32_16x16x32_bf16 v[100:103], v[160:163], v[186:189], v[100:103]
	v_mfma_f32_16x16x32_bf16 v[96:99], v[170:173], v[186:189], v[96:99]
	v_mfma_f32_16x16x32_bf16 v[84:87], v[160:163], v[198:201], v[84:87]
	v_mfma_f32_16x16x32_bf16 v[80:83], v[170:173], v[198:201], v[80:83]
	v_mfma_f32_16x16x32_bf16 v[68:71], v[160:163], v[206:209], v[68:71]
	v_mfma_f32_16x16x32_bf16 v[64:67], v[170:173], v[206:209], v[64:67]
	s_setprio 0
	s_barrier
	s_add_i32 s77, s77, s36
	v_lshl_add_u64 v[210:211], s[12:13], 0, v[114:115]
	s_mov_b32 m0, s77
	ds_read_b128 v[174:177], v165 offset:16384
	ds_read_b128 v[178:181], v165 offset:17408
	ds_read_b128 v[182:185], v165 offset:18432
	ds_read_b128 v[186:189], v165 offset:19456
	ds_read_b128 v[190:193], v165 offset:20480
	ds_read_b128 v[198:201], v165 offset:21504
	ds_read_b128 v[202:205], v165 offset:22528
	ds_read_b128 v[206:209], v165 offset:23552
	global_load_lds_dwordx4 v[210:211], off
	s_add_i32 m0, s77, 0x2000
	s_add_u32 s78, s12, 0x40000
	v_lshl_add_u64 v[212:213], s[12:13], 0, v[142:143]
	s_addc_u32 s79, s13, 0
	s_add_i32 s1, s1, s36
	global_load_lds_dwordx4 v[212:213], off
	v_lshl_add_u64 v[214:215], s[78:79], 0, v[114:115]
	s_mov_b32 m0, s1
	v_lshl_add_u64 v[216:217], s[60:61], 0, v[140:141]
	global_load_lds_dwordx4 v[214:215], off
	v_lshl_add_u64 v[214:215], s[78:79], 0, v[142:143]
	s_add_i32 m0, s1, 0x2000
	s_nop 0
	global_load_lds_dwordx4 v[214:215], off
	v_lshl_add_u64 v[214:215], s[60:61], 0, v[112:113]
	s_mov_b32 m0, s65
	s_nop 0
	global_load_lds_dwordx4 v[214:215], off
	s_mov_b32 m0, s66
	s_nop 0
	global_load_lds_dwordx4 v[216:217], off
	s_waitcnt vmcnt(8)
	s_waitcnt lgkmcnt(0)
	s_barrier
; #define PG8_STAGE(bufoff, gbase, voff) do { _Pragma("unroll") for (int _i = 0; _i < 2; ++_i) \
;         __builtin_amdgcn_global_load_lds((const unsigned*)((const char*)(gbase) + (voff)[_i]), (PG8_LAS unsigned*)(lds + (bufoff) + ldsw + _i * 8192), 16, 0, 0); } while (0)
; #define PG8_LDA(dst, b, h) do { _Pragma("unroll") for (int m = 0; m < 4; ++m) _Pragma("unroll") for (int k = 0; k < 2; ++k) dst[m][k] = *(const PG8_LAS bf16x8*)(lds + PG8_SA(b, h) + aoff + m * 2048 + k * 1024); } while (0)
; #define PG8_LDB(dst, b, h) do { _Pragma("unroll") for (int n = 0; n < 2; ++n) _Pragma("unroll") for (int k = 0; k < 2; ++k) dst[n][k] = *(const PG8_LAS bf16x8*)(lds + PG8_SB(b, h) + boff + n * 2048 + k * 1024); } while (0)
; #define PG8_MMA(ai, bj, At, Bt) do { __builtin_amdgcn_s_setprio(1); _Pragma("unroll") for (int m = 0; m < 4; ++m) _Pragma("unroll") for (int n = 0; n < 2; ++n) _Pragma("unroll") for (int k = 0; k < 2; ++k) \
;         acc[ai][bj][m][n] = __builtin_amdgcn_mfma_f32_16x16x32_bf16(Bt[n][k], At[m][k], acc[ai][bj][m][n], 0, 0, 0); __builtin_amdgcn_s_setprio(0); } while (0)
; #define PG8_WAIT_V(n) asm volatile("s_waitcnt vmcnt(" #n ")" ::: "memory")
; #define PG8_WAIT_L(n) asm volatile("s_waitcnt lgkmcnt(" #n ")" ::: "memory")
; #define PG8_BAR __builtin_amdgcn_s_barrier()
; #define PG8_SCHED __builtin_amdgcn_sched_barrier(0)
; template <class Epi, class Sched, bool ALIGN_EPI = false, bool SP2 = false>
; __device__ __forceinline__ void gemm_phase(PG8_LAS unsigned char* lds, const Gemm g, const Sched& S, const Epi& E, const int wv) {
;     ...
;             PG8_WAIT_V(8); PG8_WAIT_L(0); PG8_BAR; PG8_MMA(1, 0, At, B0); PG8_MMA(1, 1, At, B1); PG8_BAR; PG8_SCHED;
;             PG8_LDB(B0, 1, 0); PG8_LDB(B1, 1, 1); PG8_SCHED; PG8_LDA(At, 1, 0); PG8_STAGE(PG8_SA(0, 1), a2 + hstepA, voffA);
;             PG8_WAIT_V(8); PG8_WAIT_L(0); PG8_BAR; PG8_MMA(0, 0, At, B0); PG8_MMA(0, 1, At, B1); PG8_BAR; PG8_SCHED;
	s_setprio 1
	s_waitcnt lgkmcnt(0)
	v_mfma_f32_16x16x32_bf16 v[60:63], v[132:135], v[174:177], v[60:63]
	v_mfma_f32_16x16x32_bf16 v[56:59], v[148:151], v[174:177], v[56:59]
	v_mfma_f32_16x16x32_bf16 v[44:47], v[132:135], v[182:185], v[44:47]
	v_mfma_f32_16x16x32_bf16 v[40:43], v[148:151], v[182:185], v[40:43]
	v_mfma_f32_16x16x32_bf16 v[28:31], v[132:135], v[190:193], v[28:31]
	v_mfma_f32_16x16x32_bf16 v[24:27], v[148:151], v[190:193], v[24:27]
	v_mfma_f32_16x16x32_bf16 v[12:15], v[132:135], v[202:205], v[12:15]
	v_mfma_f32_16x16x32_bf16 v[8:11], v[148:151], v[202:205], v[8:11]
	v_mfma_f32_16x16x32_bf16 v[60:63], v[136:139], v[178:181], v[60:63]
	v_mfma_f32_16x16x32_bf16 v[56:59], v[152:155], v[178:181], v[56:59]
	v_mfma_f32_16x16x32_bf16 v[44:47], v[136:139], v[186:189], v[44:47]
	v_mfma_f32_16x16x32_bf16 v[40:43], v[152:155], v[186:189], v[40:43]
	v_mfma_f32_16x16x32_bf16 v[28:31], v[136:139], v[198:201], v[28:31]
	v_mfma_f32_16x16x32_bf16 v[24:27], v[152:155], v[198:201], v[24:27]
	v_mfma_f32_16x16x32_bf16 v[12:15], v[136:139], v[206:209], v[12:15]
	v_mfma_f32_16x16x32_bf16 v[8:11], v[152:155], v[206:209], v[8:11]
	v_mfma_f32_16x16x32_bf16 v[52:55], v[156:159], v[174:177], v[52:55]
	v_mfma_f32_16x16x32_bf16 v[48:51], v[166:169], v[174:177], v[48:51]
	v_mfma_f32_16x16x32_bf16 v[36:39], v[156:159], v[182:185], v[36:39]
	v_mfma_f32_16x16x32_bf16 v[32:35], v[166:169], v[182:185], v[32:35]
	v_mfma_f32_16x16x32_bf16 v[20:23], v[156:159], v[190:193], v[20:23]
	v_mfma_f32_16x16x32_bf16 v[16:19], v[166:169], v[190:193], v[16:19]
	v_mfma_f32_16x16x32_bf16 v[4:7], v[156:159], v[202:205], v[4:7]
	v_mfma_f32_16x16x32_bf16 v[0:3], v[166:169], v[202:205], v[0:3]
	v_mfma_f32_16x16x32_bf16 v[52:55], v[160:163], v[178:181], v[52:55]
	v_mfma_f32_16x16x32_bf16 v[48:51], v[170:173], v[178:181], v[48:51]
	v_mfma_f32_16x16x32_bf16 v[36:39], v[160:163], v[186:189], v[36:39]
	v_mfma_f32_16x16x32_bf16 v[32:35], v[170:173], v[186:189], v[32:35]
	v_mfma_f32_16x16x32_bf16 v[20:23], v[160:163], v[198:201], v[20:23]
	v_mfma_f32_16x16x32_bf16 v[16:19], v[170:173], v[198:201], v[16:19]
	v_mfma_f32_16x16x32_bf16 v[4:7], v[160:163], v[206:209], v[4:7]
	v_mfma_f32_16x16x32_bf16 v[0:3], v[170:173], v[206:209], v[0:3]
	s_setprio 0
	s_barrier
	s_add_i32 s1, 0, 0x18000
	s_add_i32 s77, 0, 0x1c000
	v_add_u32_e32 v152, s1, v164
	v_add_u32_e32 v170, s77, v164
	ds_read_b128 v[132:135], v152
	ds_read_b128 v[136:139], v152 offset:1024
	ds_read_b128 v[148:151], v152 offset:2048
	ds_read_b128 v[152:155], v152 offset:3072
	ds_read_b128 v[156:159], v170
	ds_read_b128 v[160:163], v170 offset:1024
	ds_read_b128 v[166:169], v170 offset:2048
	ds_read_b128 v[170:173], v170 offset:3072
	s_add_u32 s60, s60, 0x40000
	s_addc_u32 s61, s61, 0
	s_mov_b32 m0, s67
	v_lshl_add_u64 v[218:219], s[60:61], 0, v[112:113]
	ds_read_b128 v[174:177], v165 offset:32768
	ds_read_b128 v[178:181], v165 offset:33792
	ds_read_b128 v[182:185], v165 offset:34816
	ds_read_b128 v[186:189], v165 offset:35840
	ds_read_b128 v[190:193], v165 offset:36864
	ds_read_b128 v[198:201], v165 offset:37888
	ds_read_b128 v[202:205], v165 offset:38912
	ds_read_b128 v[206:209], v165 offset:39936
	global_load_lds_dwordx4 v[218:219], off
	v_lshl_add_u64 v[218:219], s[60:61], 0, v[140:141]
	s_mov_b32 m0, s68
	s_nop 0
	global_load_lds_dwordx4 v[218:219], off
	s_waitcnt vmcnt(8)
	s_waitcnt lgkmcnt(0)
	s_barrier
	s_setprio 1
	s_waitcnt lgkmcnt(0)
	v_mfma_f32_16x16x32_bf16 v[128:131], v[132:135], v[174:177], v[128:131]
	v_mfma_f32_16x16x32_bf16 v[124:127], v[148:151], v[174:177], v[124:127]
	v_mfma_f32_16x16x32_bf16 v[108:111], v[132:135], v[182:185], v[108:111]
	v_mfma_f32_16x16x32_bf16 v[104:107], v[148:151], v[182:185], v[104:107]
	v_mfma_f32_16x16x32_bf16 v[92:95], v[132:135], v[190:193], v[92:95]
	v_mfma_f32_16x16x32_bf16 v[88:91], v[148:151], v[190:193], v[88:91]
	v_mfma_f32_16x16x32_bf16 v[76:79], v[132:135], v[202:205], v[76:79]
	v_mfma_f32_16x16x32_bf16 v[72:75], v[148:151], v[202:205], v[72:75]
	v_mfma_f32_16x16x32_bf16 v[128:131], v[136:139], v[178:181], v[128:131]
	v_mfma_f32_16x16x32_bf16 v[124:127], v[152:155], v[178:181], v[124:127]
	v_mfma_f32_16x16x32_bf16 v[108:111], v[136:139], v[186:189], v[108:111]
	v_mfma_f32_16x16x32_bf16 v[104:107], v[152:155], v[186:189], v[104:107]
	v_mfma_f32_16x16x32_bf16 v[92:95], v[136:139], v[198:201], v[92:95]
	v_mfma_f32_16x16x32_bf16 v[88:91], v[152:155], v[198:201], v[88:91]
	v_mfma_f32_16x16x32_bf16 v[76:79], v[136:139], v[206:209], v[76:79]
	v_mfma_f32_16x16x32_bf16 v[72:75], v[152:155], v[206:209], v[72:75]
	v_mfma_f32_16x16x32_bf16 v[120:123], v[156:159], v[174:177], v[120:123]
	v_mfma_f32_16x16x32_bf16 v[116:119], v[166:169], v[174:177], v[116:119]
	v_mfma_f32_16x16x32_bf16 v[100:103], v[156:159], v[182:185], v[100:103]
	v_mfma_f32_16x16x32_bf16 v[96:99], v[166:169], v[182:185], v[96:99]
	v_mfma_f32_16x16x32_bf16 v[84:87], v[156:159], v[190:193], v[84:87]
	v_mfma_f32_16x16x32_bf16 v[80:83], v[166:169], v[190:193], v[80:83]
	v_mfma_f32_16x16x32_bf16 v[68:71], v[156:159], v[202:205], v[68:71]
	v_mfma_f32_16x16x32_bf16 v[64:67], v[166:169], v[202:205], v[64:67]
	v_mfma_f32_16x16x32_bf16 v[120:123], v[160:163], v[178:181], v[120:123]
	v_mfma_f32_16x16x32_bf16 v[116:119], v[170:173], v[178:181], v[116:119]
	v_mfma_f32_16x16x32_bf16 v[100:103], v[160:163], v[186:189], v[100:103]
	v_mfma_f32_16x16x32_bf16 v[96:99], v[170:173], v[186:189], v[96:99]
	v_mfma_f32_16x16x32_bf16 v[84:87], v[160:163], v[198:201], v[84:87]
	v_mfma_f32_16x16x32_bf16 v[80:83], v[170:173], v[198:201], v[80:83]
	v_mfma_f32_16x16x32_bf16 v[68:71], v[160:163], v[206:209], v[68:71]
	v_mfma_f32_16x16x32_bf16 v[64:67], v[170:173], v[206:209], v[64:67]
	s_setprio 0
	s_barrier
; #define PG8_STAGE(bufoff, gbase, voff) do { _Pragma("unroll") for (int _i = 0; _i < 2; ++_i) \
;         __builtin_amdgcn_global_load_lds((const unsigned*)((const char*)(gbase) + (voff)[_i]), (PG8_LAS unsigned*)(lds + (bufoff) + ldsw + _i * 8192), 16, 0, 0); } while (0)
; #define PG8_LDA(dst, b, h) do { _Pragma("unroll") for (int m = 0; m < 4; ++m) _Pragma("unroll") for (int k = 0; k < 2; ++k) dst[m][k] = *(const PG8_LAS bf16x8*)(lds + PG8_SA(b, h) + aoff + m * 2048 + k * 1024); } while (0)
; #define PG8_MMA(ai, bj, At, Bt) do { __builtin_amdgcn_s_setprio(1); _Pragma("unroll") for (int m = 0; m < 4; ++m) _Pragma("unroll") for (int n = 0; n < 2; ++n) _Pragma("unroll") for (int k = 0; k < 2; ++k) \
;         acc[ai][bj][m][n] = __builtin_amdgcn_mfma_f32_16x16x32_bf16(Bt[n][k], At[m][k], acc[ai][bj][m][n], 0, 0, 0); __builtin_amdgcn_s_setprio(0); } while (0)
; #define PG8_WAIT_V(n) asm volatile("s_waitcnt vmcnt(" #n ")" ::: "memory")
; #define PG8_WAIT_L(n) asm volatile("s_waitcnt lgkmcnt(" #n ")" ::: "memory")
; #define PG8_BAR __builtin_amdgcn_s_barrier()
; #define PG8_SCHED __builtin_amdgcn_sched_barrier(0)
; template <class Epi, class Sched, bool ALIGN_EPI = false, bool SP2 = false>
; __device__ __forceinline__ void gemm_phase(PG8_LAS unsigned char* lds, const Gemm g, const Sched& S, const Epi& E, const int wv) {
;     ...
;             PG8_LDA(At, 1, 1); PG8_STAGE(PG8_SB(1, 0), b3, voffB); PG8_STAGE(PG8_SB(1, 1), b3 + hstepB, voffB); PG8_STAGE(PG8_SA(1, 0), a3, voffA);
;             PG8_WAIT_V(8); PG8_WAIT_L(0); PG8_BAR; PG8_MMA(1, 0, At, B0); PG8_MMA(1, 1, At, B1); PG8_BAR; PG8_SCHED;
	s_add_i32 s1, s1, s36
	v_lshl_add_u64 v[210:211], v[210:211], 0, s[28:29]
	s_mov_b32 m0, s1
	ds_read_b128 v[174:177], v165 offset:49152
	ds_read_b128 v[178:181], v165 offset:50176
	ds_read_b128 v[182:185], v165 offset:51200
	ds_read_b128 v[186:189], v165 offset:52224
	ds_read_b128 v[190:193], v165 offset:53248
	ds_read_b128 v[198:201], v165 offset:54272
	ds_read_b128 v[202:205], v165 offset:55296
	ds_read_b128 v[206:209], v165 offset:56320
	global_load_lds_dwordx4 v[210:211], off
	s_add_i32 m0, s1, 0x2000
	s_add_u32 s12, s12, 0x40080
	v_lshl_add_u64 v[210:211], v[212:213], 0, s[28:29]
	s_addc_u32 s13, s13, 0
	s_add_i32 s1, s77, s36
	global_load_lds_dwordx4 v[210:211], off
	v_lshl_add_u64 v[210:211], s[12:13], 0, v[114:115]
	s_mov_b32 m0, s1
	s_nop 0
	global_load_lds_dwordx4 v[210:211], off
	v_lshl_add_u64 v[210:211], s[12:13], 0, v[142:143]
	s_add_i32 m0, s1, 0x2000
	s_nop 0
	global_load_lds_dwordx4 v[210:211], off
	v_lshl_add_u64 v[210:211], v[214:215], 0, s[28:29]
	s_mov_b32 m0, s72
	s_nop 0
	global_load_lds_dwordx4 v[210:211], off
	v_lshl_add_u64 v[210:211], v[216:217], 0, s[28:29]
	s_mov_b32 m0, s73
	s_nop 0
	global_load_lds_dwordx4 v[210:211], off
	s_waitcnt vmcnt(8)
	s_waitcnt lgkmcnt(0)
	s_barrier
	s_setprio 1
	s_waitcnt lgkmcnt(0)
	v_mfma_f32_16x16x32_bf16 v[60:63], v[132:135], v[174:177], v[60:63]
	v_mfma_f32_16x16x32_bf16 v[56:59], v[148:151], v[174:177], v[56:59]
	v_mfma_f32_16x16x32_bf16 v[44:47], v[132:135], v[182:185], v[44:47]
	v_mfma_f32_16x16x32_bf16 v[40:43], v[148:151], v[182:185], v[40:43]
	v_mfma_f32_16x16x32_bf16 v[28:31], v[132:135], v[190:193], v[28:31]
	v_mfma_f32_16x16x32_bf16 v[24:27], v[148:151], v[190:193], v[24:27]
	v_mfma_f32_16x16x32_bf16 v[12:15], v[132:135], v[202:205], v[12:15]
	v_mfma_f32_16x16x32_bf16 v[8:11], v[148:151], v[202:205], v[8:11]
	v_mfma_f32_16x16x32_bf16 v[60:63], v[136:139], v[178:181], v[60:63]
	v_mfma_f32_16x16x32_bf16 v[56:59], v[152:155], v[178:181], v[56:59]
	v_mfma_f32_16x16x32_bf16 v[44:47], v[136:139], v[186:189], v[44:47]
	v_mfma_f32_16x16x32_bf16 v[40:43], v[152:155], v[186:189], v[40:43]
	v_mfma_f32_16x16x32_bf16 v[28:31], v[136:139], v[198:201], v[28:31]
	v_mfma_f32_16x16x32_bf16 v[24:27], v[152:155], v[198:201], v[24:27]
	v_mfma_f32_16x16x32_bf16 v[12:15], v[136:139], v[206:209], v[12:15]
	v_mfma_f32_16x16x32_bf16 v[8:11], v[152:155], v[206:209], v[8:11]
	v_mfma_f32_16x16x32_bf16 v[52:55], v[156:159], v[174:177], v[52:55]
	v_mfma_f32_16x16x32_bf16 v[48:51], v[166:169], v[174:177], v[48:51]
	v_mfma_f32_16x16x32_bf16 v[36:39], v[156:159], v[182:185], v[36:39]
	v_mfma_f32_16x16x32_bf16 v[32:35], v[166:169], v[182:185], v[32:35]
	v_mfma_f32_16x16x32_bf16 v[20:23], v[156:159], v[190:193], v[20:23]
	v_mfma_f32_16x16x32_bf16 v[16:19], v[166:169], v[190:193], v[16:19]
	v_mfma_f32_16x16x32_bf16 v[4:7], v[156:159], v[202:205], v[4:7]
	v_mfma_f32_16x16x32_bf16 v[0:3], v[166:169], v[202:205], v[0:3]
	v_mfma_f32_16x16x32_bf16 v[52:55], v[160:163], v[178:181], v[52:55]
	v_mfma_f32_16x16x32_bf16 v[48:51], v[170:173], v[178:181], v[48:51]
	v_mfma_f32_16x16x32_bf16 v[36:39], v[160:163], v[186:189], v[36:39]
	v_mfma_f32_16x16x32_bf16 v[32:35], v[170:173], v[186:189], v[32:35]
	v_mfma_f32_16x16x32_bf16 v[20:23], v[160:163], v[198:201], v[20:23]
	v_mfma_f32_16x16x32_bf16 v[16:19], v[170:173], v[198:201], v[16:19]
	v_mfma_f32_16x16x32_bf16 v[4:7], v[160:163], v[206:209], v[4:7]
	v_mfma_f32_16x16x32_bf16 v[0:3], v[170:173], v[206:209], v[0:3]
	s_setprio 0
	s_barrier
	s_add_i32 s76, s76, 2
	s_add_u32 s10, s10, 0x100
	s_addc_u32 s11, s11, 0
	s_add_u32 s59, s59, 0x100
	s_addc_u32 s75, s75, 0
	s_cmp_gt_u32 s76, 13
	s_cbranch_scc0 .LBB0_1281
	s_and_b64 vcc, exec, s[46:47]
	s_cbranch_vccz .LBB0_1284
	s_barrier

; #define PG8_STAGE(bufoff, gbase, voff) do { _Pragma("unroll") for (int _i = 0; _i < 2; ++_i) \
;         __builtin_amdgcn_global_load_lds((const unsigned*)((const char*)(gbase) + (voff)[_i]), (PG8_LAS unsigned*)(lds + (bufoff) + ldsw + _i * 8192), 16, 0, 0); } while (0)
; #define PG8_LDA(dst, b, h) do { _Pragma("unroll") for (int m = 0; m < 4; ++m) _Pragma("unroll") for (int k = 0; k < 2; ++k) dst[m][k] = *(const PG8_LAS bf16x8*)(lds + PG8_SA(b, h) + aoff + m * 2048 + k * 1024); } while (0)
; #define PG8_LDB(dst, b, h) do { _Pragma("unroll") for (int n = 0; n < 2; ++n) _Pragma("unroll") for (int k = 0; k < 2; ++k) dst[n][k] = *(const PG8_LAS bf16x8*)(lds + PG8_SB(b, h) + boff + n * 2048 + k * 1024); } while (0)
; #define PG8_MMA(ai, bj, At, Bt) do { __builtin_amdgcn_s_setprio(1); _Pragma("unroll") for (int m = 0; m < 4; ++m) _Pragma("unroll") for (int n = 0; n < 2; ++n) _Pragma("unroll") for (int k = 0; k < 2; ++k) \
;         acc[ai][bj][m][n] = __builtin_amdgcn_mfma_f32_16x16x32_bf16(Bt[n][k], At[m][k], acc[ai][bj][m][n], 0, 0, 0); __builtin_amdgcn_s_setprio(0); } while (0)
; template <class Epi, class Sched, bool ALIGN_EPI = false, bool SP2 = false>
; __device__ __forceinline__ void gemm_phase(PG8_LAS unsigned char* lds, const Gemm g, const Sched& S, const Epi& E, const int wv) {
;     ...
;         const bool has_next = S.next(ui + 1, nxt);
;         const char* nA = has_next ? (const char*)g.A + (size_t)nxt.pm * tstepA : cA; const char* nB = has_next ? (const char*)g.Bt + (size_t)nxt.pn * tstepB : cB;
;         for (int t = 0; t < nt; t += 2) {
;             const bool last = (t == nt - 2);
;             const char* a1 = cA + (size_t)(t + 1) * kstep;
;             const char* a2 = last ? nA : cA + (size_t)(t + 2) * kstep; const char* b2 = last ? nB : cB + (size_t)(t + 2) * kstep;
;             const char* a3 = a2 + kstep; const char* b3 = b2 + kstep;
;             if (last && has_next) S.a_ready(nxt);
;             if constexpr (SP2) {
;             PG8_LDB(B0, 0, 0); PG8_LDB(B1, 0, 1); PG8_SCHED; PG8_LDA(At, 0, 0); PG8_STAGE(PG8_SA(1, 1), a1 + hstepA, voffA);
;             PG8_WAIT_V(8); PG8_WAIT_L(0); PG8_BAR; PG8_MMA(0, 0, At, B0); PG8_MMA(0, 1, At, B1); PG8_BAR; PG8_SCHED;
;             PG8_LDA(At, 0, 1); PG8_STAGE(PG8_SB(0, 0), b2, voffB); PG8_STAGE(PG8_SB(0, 1), b2 + hstepB, voffB); PG8_STAGE(PG8_SA(0, 0), a2, voffA);
.LBB0_1381:
	s_ashr_i32 s13, s12, 31
	s_lshl_b64 s[14:15], s[12:13], 17
	s_add_u32 s14, s40, s14
	v_cmp_lt_i64_e32 vcc, s[2:3], v[234:235]
	s_addc_u32 s15, s41, s15
	s_and_b64 s[16:17], vcc, exec
	s_cselect_b32 s39, s15, s21
	s_cselect_b32 s38, s14, s20
	s_ashr_i32 s11, s10, 31
	s_lshl_b64 s[16:17], s[10:11], 17
	s_add_u32 s16, s42, s16
	s_addc_u32 s17, s43, s17
	s_and_b64 s[18:19], vcc, exec
	s_cselect_b32 s19, s17, s31
	s_cselect_b32 s18, s16, s30
	s_add_i32 s11, 0, 0x10000
	s_add_i32 s13, 0, 0x14000
	v_add_u32_e32 v7, s11, v14
	v_add_u32_e32 v15, s13, v14
	ds_read_b128 v[8:11], v7
	ds_read_b128 v[16:19], v7 offset:1024
	ds_read_b128 v[20:23], v7 offset:2048
	ds_read_b128 v[24:27], v7 offset:3072
	ds_read_b128 v[28:31], v15
	ds_read_b128 v[32:35], v15 offset:1024
	ds_read_b128 v[36:39], v15 offset:2048
	ds_read_b128 v[40:43], v15 offset:3072
	s_add_u32 s48, s20, 0x10080
	s_addc_u32 s49, s21, 0
	s_add_i32 s51, s9, 0xc000
	v_lshl_add_u64 v[12:13], s[48:49], 0, v[4:5]
	s_mov_b32 m0, s51
	s_add_i32 s1, s9, 0xe000
	ds_read_b128 v[44:47], v6
	ds_read_b128 v[48:51], v6 offset:1024
	ds_read_b128 v[52:55], v6 offset:2048
	ds_read_b128 v[56:59], v6 offset:3072
	ds_read_b128 v[60:63], v6 offset:4096
	ds_read_b128 v[64:67], v6 offset:5120
	ds_read_b128 v[68:71], v6 offset:6144
	ds_read_b128 v[72:75], v6 offset:7168
	global_load_lds_dwordx4 v[12:13], off
	v_lshl_add_u64 v[12:13], s[48:49], 0, v[2:3]
	s_mov_b32 m0, s1
	s_nop 0
	global_load_lds_dwordx4 v[12:13], off
	s_waitcnt vmcnt(8)
	s_waitcnt lgkmcnt(0)
	s_barrier
	s_setprio 1
	s_waitcnt lgkmcnt(0)
	v_mfma_f32_16x16x32_bf16 v[76:79], v[8:11], v[44:47], 0
	v_mfma_f32_16x16x32_bf16 v[80:83], v[20:23], v[44:47], 0
	v_mfma_f32_16x16x32_bf16 v[84:87], v[8:11], v[52:55], 0
	v_mfma_f32_16x16x32_bf16 v[88:91], v[20:23], v[52:55], 0
	v_mfma_f32_16x16x32_bf16 v[92:95], v[8:11], v[60:63], 0
	v_mfma_f32_16x16x32_bf16 v[96:99], v[20:23], v[60:63], 0
	v_mfma_f32_16x16x32_bf16 v[100:103], v[8:11], v[68:71], 0
	v_mfma_f32_16x16x32_bf16 v[104:107], v[20:23], v[68:71], 0
	v_mfma_f32_16x16x32_bf16 v[76:79], v[16:19], v[48:51], v[76:79]
	v_mfma_f32_16x16x32_bf16 v[80:83], v[24:27], v[48:51], v[80:83]
	v_mfma_f32_16x16x32_bf16 v[84:87], v[16:19], v[56:59], v[84:87]
	v_mfma_f32_16x16x32_bf16 v[88:91], v[24:27], v[56:59], v[88:91]
	v_mfma_f32_16x16x32_bf16 v[92:95], v[16:19], v[64:67], v[92:95]
	v_mfma_f32_16x16x32_bf16 v[96:99], v[24:27], v[64:67], v[96:99]
	v_mfma_f32_16x16x32_bf16 v[100:103], v[16:19], v[72:75], v[100:103]
	v_mfma_f32_16x16x32_bf16 v[104:107], v[24:27], v[72:75], v[104:107]
	v_mfma_f32_16x16x32_bf16 v[108:111], v[28:31], v[44:47], 0
	v_mfma_f32_16x16x32_bf16 v[44:47], v[36:39], v[44:47], 0
	v_mfma_f32_16x16x32_bf16 v[108:111], v[32:35], v[48:51], v[108:111]
	v_mfma_f32_16x16x32_bf16 v[44:47], v[40:43], v[48:51], v[44:47]
	v_mfma_f32_16x16x32_bf16 v[48:51], v[28:31], v[52:55], 0
	v_mfma_f32_16x16x32_bf16 v[52:55], v[36:39], v[52:55], 0
	v_mfma_f32_16x16x32_bf16 v[48:51], v[32:35], v[56:59], v[48:51]
	v_mfma_f32_16x16x32_bf16 v[52:55], v[40:43], v[56:59], v[52:55]
	v_mfma_f32_16x16x32_bf16 v[56:59], v[28:31], v[60:63], 0
	v_mfma_f32_16x16x32_bf16 v[60:63], v[36:39], v[60:63], 0
	v_mfma_f32_16x16x32_bf16 v[56:59], v[32:35], v[64:67], v[56:59]
	v_mfma_f32_16x16x32_bf16 v[60:63], v[40:43], v[64:67], v[60:63]
	v_mfma_f32_16x16x32_bf16 v[64:67], v[28:31], v[68:71], 0
	v_mfma_f32_16x16x32_bf16 v[68:71], v[36:39], v[68:71], 0
	v_mfma_f32_16x16x32_bf16 v[64:67], v[32:35], v[72:75], v[64:67]
	v_mfma_f32_16x16x32_bf16 v[68:71], v[40:43], v[72:75], v[68:71]
	s_setprio 0
	s_barrier
	v_lshl_add_u64 v[12:13], s[30:31], 0, v[114:115]
	s_mov_b64 s[54:55], 0x100
	s_add_i32 s49, s11, s37
	v_lshl_add_u64 v[112:113], v[12:13], 0, s[54:55]
	s_mov_b32 m0, s49
	s_add_i32 s11, s49, 0x2000
	ds_read_b128 v[72:75], v6 offset:16384
	ds_read_b128 v[116:119], v6 offset:17408
	ds_read_b128 v[120:123], v6 offset:18432
	ds_read_b128 v[124:127], v6 offset:19456
	ds_read_b128 v[128:131], v6 offset:20480
	ds_read_b128 v[132:135], v6 offset:21504
	ds_read_b128 v[136:139], v6 offset:22528
	ds_read_b128 v[140:143], v6 offset:23552
	global_load_lds_dwordx4 v[112:113], off
	v_lshl_add_u64 v[112:113], s[30:31], 0, v[0:1]
	s_add_u32 s52, s30, 0x10100
	v_lshl_add_u64 v[144:145], v[112:113], 0, s[54:55]
	s_mov_b32 m0, s11
	s_addc_u32 s53, s31, 0
	s_add_i32 s13, s13, s37
	global_load_lds_dwordx4 v[144:145], off
	v_lshl_add_u64 v[144:145], s[52:53], 0, v[114:115]
	s_mov_b32 m0, s13
	s_add_i32 s48, s13, 0x2000
	global_load_lds_dwordx4 v[144:145], off
	v_lshl_add_u64 v[144:145], s[52:53], 0, v[0:1]
	s_mov_b32 m0, s48
	v_lshl_add_u64 v[192:193], s[20:21], 0, v[4:5]
	global_load_lds_dwordx4 v[144:145], off
	v_lshl_add_u64 v[144:145], v[192:193], 0, s[54:55]
	s_mov_b32 m0, s9
	v_lshl_add_u64 v[214:215], s[20:21], 0, v[2:3]
	global_load_lds_dwordx4 v[144:145], off
	v_lshl_add_u64 v[144:145], v[214:215], 0, s[54:55]
	s_mov_b32 m0, s33
	s_nop 0
	global_load_lds_dwordx4 v[144:145], off
	s_waitcnt vmcnt(8)
	s_waitcnt lgkmcnt(0)
	s_barrier
; #define PG8_STAGE(bufoff, gbase, voff) do { _Pragma("unroll") for (int _i = 0; _i < 2; ++_i) \
;         __builtin_amdgcn_global_load_lds((const unsigned*)((const char*)(gbase) + (voff)[_i]), (PG8_LAS unsigned*)(lds + (bufoff) + ldsw + _i * 8192), 16, 0, 0); } while (0)
; #define PG8_LDA(dst, b, h) do { _Pragma("unroll") for (int m = 0; m < 4; ++m) _Pragma("unroll") for (int k = 0; k < 2; ++k) dst[m][k] = *(const PG8_LAS bf16x8*)(lds + PG8_SA(b, h) + aoff + m * 2048 + k * 1024); } while (0)
; #define PG8_LDB(dst, b, h) do { _Pragma("unroll") for (int n = 0; n < 2; ++n) _Pragma("unroll") for (int k = 0; k < 2; ++k) dst[n][k] = *(const PG8_LAS bf16x8*)(lds + PG8_SB(b, h) + boff + n * 2048 + k * 1024); } while (0)
; #define PG8_MMA(ai, bj, At, Bt) do { __builtin_amdgcn_s_setprio(1); _Pragma("unroll") for (int m = 0; m < 4; ++m) _Pragma("unroll") for (int n = 0; n < 2; ++n) _Pragma("unroll") for (int k = 0; k < 2; ++k) \
;         acc[ai][bj][m][n] = __builtin_amdgcn_mfma_f32_16x16x32_bf16(Bt[n][k], At[m][k], acc[ai][bj][m][n], 0, 0, 0); __builtin_amdgcn_s_setprio(0); } while (0)
; #define PG8_WAIT_V(n) asm volatile("s_waitcnt vmcnt(" #n ")" ::: "memory")
; #define PG8_WAIT_L(n) asm volatile("s_waitcnt lgkmcnt(" #n ")" ::: "memory")
; #define PG8_BAR __builtin_amdgcn_s_barrier()
; #define PG8_SCHED __builtin_amdgcn_sched_barrier(0)
; template <class Epi, class Sched, bool ALIGN_EPI = false, bool SP2 = false>
; __device__ __forceinline__ void gemm_phase(PG8_LAS unsigned char* lds, const Gemm g, const Sched& S, const Epi& E, const int wv) {
;     ...
;             PG8_WAIT_V(8); PG8_WAIT_L(0); PG8_BAR; PG8_MMA(1, 0, At, B0); PG8_MMA(1, 1, At, B1); PG8_BAR; PG8_SCHED;
;             PG8_LDB(B0, 1, 0); PG8_LDB(B1, 1, 1); PG8_SCHED; PG8_LDA(At, 1, 0); PG8_STAGE(PG8_SA(0, 1), a2 + hstepA, voffA);
;             PG8_WAIT_V(8); PG8_WAIT_L(0); PG8_BAR; PG8_MMA(0, 0, At, B0); PG8_MMA(0, 1, At, B1); PG8_BAR; PG8_SCHED;
	s_setprio 1
	s_waitcnt lgkmcnt(0)
	v_mfma_f32_16x16x32_bf16 v[144:147], v[8:11], v[72:75], 0
	v_mfma_f32_16x16x32_bf16 v[152:155], v[8:11], v[120:123], 0
	v_mfma_f32_16x16x32_bf16 v[160:163], v[8:11], v[128:131], 0
	v_mfma_f32_16x16x32_bf16 v[8:11], v[8:11], v[136:139], 0
	v_mfma_f32_16x16x32_bf16 v[144:147], v[16:19], v[116:119], v[144:147]
	v_mfma_f32_16x16x32_bf16 v[148:151], v[20:23], v[72:75], 0
	v_mfma_f32_16x16x32_bf16 v[152:155], v[16:19], v[124:127], v[152:155]
	v_mfma_f32_16x16x32_bf16 v[156:159], v[20:23], v[120:123], 0
	v_mfma_f32_16x16x32_bf16 v[160:163], v[16:19], v[132:135], v[160:163]
	v_mfma_f32_16x16x32_bf16 v[164:167], v[20:23], v[128:131], 0
	v_mfma_f32_16x16x32_bf16 v[8:11], v[16:19], v[140:143], v[8:11]
	v_mfma_f32_16x16x32_bf16 v[16:19], v[20:23], v[136:139], 0
	v_mfma_f32_16x16x32_bf16 v[148:151], v[24:27], v[116:119], v[148:151]
	v_mfma_f32_16x16x32_bf16 v[156:159], v[24:27], v[124:127], v[156:159]
	v_mfma_f32_16x16x32_bf16 v[164:167], v[24:27], v[132:135], v[164:167]
	v_mfma_f32_16x16x32_bf16 v[16:19], v[24:27], v[140:143], v[16:19]
	v_mfma_f32_16x16x32_bf16 v[20:23], v[28:31], v[72:75], 0
	v_mfma_f32_16x16x32_bf16 v[24:27], v[36:39], v[72:75], 0
	v_mfma_f32_16x16x32_bf16 v[20:23], v[32:35], v[116:119], v[20:23]
	v_mfma_f32_16x16x32_bf16 v[24:27], v[40:43], v[116:119], v[24:27]
	v_mfma_f32_16x16x32_bf16 v[72:75], v[28:31], v[120:123], 0
	v_mfma_f32_16x16x32_bf16 v[116:119], v[36:39], v[120:123], 0
	v_mfma_f32_16x16x32_bf16 v[120:123], v[28:31], v[128:131], 0
	v_mfma_f32_16x16x32_bf16 v[28:31], v[28:31], v[136:139], 0
	v_mfma_f32_16x16x32_bf16 v[72:75], v[32:35], v[124:127], v[72:75]
	v_mfma_f32_16x16x32_bf16 v[116:119], v[40:43], v[124:127], v[116:119]
	v_mfma_f32_16x16x32_bf16 v[120:123], v[32:35], v[132:135], v[120:123]
	v_mfma_f32_16x16x32_bf16 v[124:127], v[36:39], v[128:131], 0
	v_mfma_f32_16x16x32_bf16 v[28:31], v[32:35], v[140:143], v[28:31]
	v_mfma_f32_16x16x32_bf16 v[32:35], v[36:39], v[136:139], 0
	v_mfma_f32_16x16x32_bf16 v[124:127], v[40:43], v[132:135], v[124:127]
	v_mfma_f32_16x16x32_bf16 v[32:35], v[40:43], v[140:143], v[32:35]
	s_setprio 0
	s_barrier
	s_add_i32 s50, 0, 0x18000
	s_add_i32 s56, 0, 0x1c000
	v_add_u32_e32 v218, s50, v14
	v_add_u32_e32 v219, s56, v14
	ds_read_b128 v[36:39], v218
	ds_read_b128 v[40:43], v218 offset:1024
	ds_read_b128 v[128:131], v218 offset:2048
	ds_read_b128 v[132:135], v218 offset:3072
	ds_read_b128 v[136:139], v219
	ds_read_b128 v[140:143], v219 offset:1024
	ds_read_b128 v[168:171], v219 offset:2048
	ds_read_b128 v[172:175], v219 offset:3072
	s_add_u32 s52, s20, 0x10100
	s_addc_u32 s53, s21, 0
	s_mov_b32 m0, s34
	v_lshl_add_u64 v[216:217], s[52:53], 0, v[4:5]
	ds_read_b128 v[176:179], v6 offset:32768
	ds_read_b128 v[180:183], v6 offset:33792
	ds_read_b128 v[184:187], v6 offset:34816
	ds_read_b128 v[188:191], v6 offset:35840
	ds_read_b128 v[198:201], v6 offset:36864
	ds_read_b128 v[202:205], v6 offset:37888
	ds_read_b128 v[206:209], v6 offset:38912
	ds_read_b128 v[210:213], v6 offset:39936
	global_load_lds_dwordx4 v[216:217], off
	v_lshl_add_u64 v[216:217], s[52:53], 0, v[2:3]
	s_mov_b32 m0, s35
	s_nop 0
	global_load_lds_dwordx4 v[216:217], off
	s_waitcnt vmcnt(8)
	s_waitcnt lgkmcnt(0)
	s_barrier
	s_setprio 1
	s_waitcnt lgkmcnt(0)
	v_mfma_f32_16x16x32_bf16 v[76:79], v[36:39], v[176:179], v[76:79]
	v_mfma_f32_16x16x32_bf16 v[80:83], v[128:131], v[176:179], v[80:83]
	v_mfma_f32_16x16x32_bf16 v[84:87], v[36:39], v[184:187], v[84:87]
	v_mfma_f32_16x16x32_bf16 v[88:91], v[128:131], v[184:187], v[88:91]
	v_mfma_f32_16x16x32_bf16 v[92:95], v[36:39], v[198:201], v[92:95]
	v_mfma_f32_16x16x32_bf16 v[96:99], v[128:131], v[198:201], v[96:99]
	v_mfma_f32_16x16x32_bf16 v[100:103], v[36:39], v[206:209], v[100:103]
	v_mfma_f32_16x16x32_bf16 v[104:107], v[128:131], v[206:209], v[104:107]
	v_mfma_f32_16x16x32_bf16 v[76:79], v[40:43], v[180:183], v[76:79]
	v_mfma_f32_16x16x32_bf16 v[80:83], v[132:135], v[180:183], v[80:83]
	v_mfma_f32_16x16x32_bf16 v[84:87], v[40:43], v[188:191], v[84:87]
	v_mfma_f32_16x16x32_bf16 v[88:91], v[132:135], v[188:191], v[88:91]
	v_mfma_f32_16x16x32_bf16 v[92:95], v[40:43], v[202:205], v[92:95]
	v_mfma_f32_16x16x32_bf16 v[96:99], v[132:135], v[202:205], v[96:99]
	v_mfma_f32_16x16x32_bf16 v[100:103], v[40:43], v[210:213], v[100:103]
	v_mfma_f32_16x16x32_bf16 v[104:107], v[132:135], v[210:213], v[104:107]
	v_mfma_f32_16x16x32_bf16 v[108:111], v[136:139], v[176:179], v[108:111]
	v_mfma_f32_16x16x32_bf16 v[44:47], v[168:171], v[176:179], v[44:47]
	v_mfma_f32_16x16x32_bf16 v[48:51], v[136:139], v[184:187], v[48:51]
	v_mfma_f32_16x16x32_bf16 v[52:55], v[168:171], v[184:187], v[52:55]
	v_mfma_f32_16x16x32_bf16 v[56:59], v[136:139], v[198:201], v[56:59]
	v_mfma_f32_16x16x32_bf16 v[60:63], v[168:171], v[198:201], v[60:63]
	v_mfma_f32_16x16x32_bf16 v[64:67], v[136:139], v[206:209], v[64:67]
	v_mfma_f32_16x16x32_bf16 v[68:71], v[168:171], v[206:209], v[68:71]
	v_mfma_f32_16x16x32_bf16 v[108:111], v[140:143], v[180:183], v[108:111]
	v_mfma_f32_16x16x32_bf16 v[44:47], v[172:175], v[180:183], v[44:47]
	v_mfma_f32_16x16x32_bf16 v[48:51], v[140:143], v[188:191], v[48:51]
	v_mfma_f32_16x16x32_bf16 v[52:55], v[172:175], v[188:191], v[52:55]
	v_mfma_f32_16x16x32_bf16 v[56:59], v[140:143], v[202:205], v[56:59]
	v_mfma_f32_16x16x32_bf16 v[60:63], v[172:175], v[202:205], v[60:63]
	v_mfma_f32_16x16x32_bf16 v[64:67], v[140:143], v[210:213], v[64:67]
	v_mfma_f32_16x16x32_bf16 v[68:71], v[172:175], v[210:213], v[68:71]
	s_setprio 0
	s_barrier
; #define PG8_STAGE(bufoff, gbase, voff) do { _Pragma("unroll") for (int _i = 0; _i < 2; ++_i) \
;         __builtin_amdgcn_global_load_lds((const unsigned*)((const char*)(gbase) + (voff)[_i]), (PG8_LAS unsigned*)(lds + (bufoff) + ldsw + _i * 8192), 16, 0, 0); } while (0)
; #define PG8_LDA(dst, b, h) do { _Pragma("unroll") for (int m = 0; m < 4; ++m) _Pragma("unroll") for (int k = 0; k < 2; ++k) dst[m][k] = *(const PG8_LAS bf16x8*)(lds + PG8_SA(b, h) + aoff + m * 2048 + k * 1024); } while (0)
; #define PG8_LDB(dst, b, h) do { _Pragma("unroll") for (int n = 0; n < 2; ++n) _Pragma("unroll") for (int k = 0; k < 2; ++k) dst[n][k] = *(const PG8_LAS bf16x8*)(lds + PG8_SB(b, h) + boff + n * 2048 + k * 1024); } while (0)
; #define PG8_MMA(ai, bj, At, Bt) do { __builtin_amdgcn_s_setprio(1); _Pragma("unroll") for (int m = 0; m < 4; ++m) _Pragma("unroll") for (int n = 0; n < 2; ++n) _Pragma("unroll") for (int k = 0; k < 2; ++k) \
;         acc[ai][bj][m][n] = __builtin_amdgcn_mfma_f32_16x16x32_bf16(Bt[n][k], At[m][k], acc[ai][bj][m][n], 0, 0, 0); __builtin_amdgcn_s_setprio(0); } while (0)
; #define PG8_WAIT_V(n) asm volatile("s_waitcnt vmcnt(" #n ")" ::: "memory")
; #define PG8_WAIT_L(n) asm volatile("s_waitcnt lgkmcnt(" #n ")" ::: "memory")
; #define PG8_BAR __builtin_amdgcn_s_barrier()
; #define PG8_SCHED __builtin_amdgcn_sched_barrier(0)
; template <class Epi, class Sched, bool ALIGN_EPI = false, bool SP2 = false>
; __device__ __forceinline__ void gemm_phase(PG8_LAS unsigned char* lds, const Gemm g, const Sched& S, const Epi& E, const int wv) {
;     ...
;             PG8_LDB(B0, 0, 0); PG8_LDB(B1, 0, 1); PG8_SCHED; PG8_LDA(At, 0, 0); PG8_STAGE(PG8_SA(1, 1), a1 + hstepA, voffA);
;             PG8_WAIT_V(8); PG8_WAIT_L(0); PG8_BAR; PG8_MMA(0, 0, At, B0); PG8_MMA(0, 1, At, B1); PG8_BAR; PG8_SCHED;
;     ...
;             PG8_LDA(At, 1, 1); PG8_STAGE(PG8_SB(1, 0), b3, voffB); PG8_STAGE(PG8_SB(1, 1), b3 + hstepB, voffB); PG8_STAGE(PG8_SA(1, 0), a3, voffA);
;             PG8_WAIT_V(8); PG8_WAIT_L(0); PG8_BAR; PG8_MMA(1, 0, At, B0); PG8_MMA(1, 1, At, B1); PG8_BAR; PG8_SCHED;
	s_add_i32 s52, s50, s37
	s_mov_b64 s[58:59], 0x180
	s_add_i32 s50, s52, 0x2000
	v_lshl_add_u64 v[12:13], v[12:13], 0, s[58:59]
	s_mov_b32 m0, s52
	s_add_u32 s54, s30, 0x10180
	ds_read_b128 v[176:179], v6 offset:49152
	ds_read_b128 v[180:183], v6 offset:50176
	ds_read_b128 v[184:187], v6 offset:51200
	ds_read_b128 v[188:191], v6 offset:52224
	ds_read_b128 v[198:201], v6 offset:53248
	ds_read_b128 v[202:205], v6 offset:54272
	ds_read_b128 v[206:209], v6 offset:55296
	ds_read_b128 v[210:213], v6 offset:56320
	global_load_lds_dwordx4 v[12:13], off
	v_lshl_add_u64 v[12:13], v[112:113], 0, s[58:59]
	s_mov_b32 m0, s50
	s_addc_u32 s55, s31, 0
	s_add_i32 s30, s56, s37
	global_load_lds_dwordx4 v[12:13], off
	v_lshl_add_u64 v[12:13], s[54:55], 0, v[114:115]
	s_mov_b32 m0, s30
	s_add_i32 s31, s30, 0x2000
	global_load_lds_dwordx4 v[12:13], off
	v_lshl_add_u64 v[12:13], s[54:55], 0, v[0:1]
	s_mov_b32 m0, s31
	s_nop 0
	global_load_lds_dwordx4 v[12:13], off
	v_lshl_add_u64 v[12:13], v[192:193], 0, s[58:59]
	s_mov_b32 m0, s45
	s_nop 0
	global_load_lds_dwordx4 v[12:13], off
	v_lshl_add_u64 v[12:13], v[214:215], 0, s[58:59]
	s_mov_b32 m0, s46
	s_nop 0
	global_load_lds_dwordx4 v[12:13], off
	s_waitcnt vmcnt(8)
	s_waitcnt lgkmcnt(0)
	s_barrier
	s_setprio 1
	s_waitcnt lgkmcnt(0)
	v_mfma_f32_16x16x32_bf16 v[144:147], v[36:39], v[176:179], v[144:147]
	v_mfma_f32_16x16x32_bf16 v[148:151], v[128:131], v[176:179], v[148:151]
	v_mfma_f32_16x16x32_bf16 v[152:155], v[36:39], v[184:187], v[152:155]
	v_mfma_f32_16x16x32_bf16 v[156:159], v[128:131], v[184:187], v[156:159]
	v_mfma_f32_16x16x32_bf16 v[160:163], v[36:39], v[198:201], v[160:163]
	v_mfma_f32_16x16x32_bf16 v[164:167], v[128:131], v[198:201], v[164:167]
	v_mfma_f32_16x16x32_bf16 v[8:11], v[36:39], v[206:209], v[8:11]
	v_mfma_f32_16x16x32_bf16 v[16:19], v[128:131], v[206:209], v[16:19]
	v_mfma_f32_16x16x32_bf16 v[144:147], v[40:43], v[180:183], v[144:147]
	v_mfma_f32_16x16x32_bf16 v[148:151], v[132:135], v[180:183], v[148:151]
	v_mfma_f32_16x16x32_bf16 v[152:155], v[40:43], v[188:191], v[152:155]
	v_mfma_f32_16x16x32_bf16 v[156:159], v[132:135], v[188:191], v[156:159]
	v_mfma_f32_16x16x32_bf16 v[160:163], v[40:43], v[202:205], v[160:163]
	v_mfma_f32_16x16x32_bf16 v[164:167], v[132:135], v[202:205], v[164:167]
	v_mfma_f32_16x16x32_bf16 v[8:11], v[40:43], v[210:213], v[8:11]
	v_mfma_f32_16x16x32_bf16 v[16:19], v[132:135], v[210:213], v[16:19]
	v_mfma_f32_16x16x32_bf16 v[20:23], v[136:139], v[176:179], v[20:23]
	v_mfma_f32_16x16x32_bf16 v[24:27], v[168:171], v[176:179], v[24:27]
	v_mfma_f32_16x16x32_bf16 v[36:39], v[136:139], v[184:187], v[72:75]
	v_mfma_f32_16x16x32_bf16 v[40:43], v[168:171], v[184:187], v[116:119]
	v_mfma_f32_16x16x32_bf16 v[72:75], v[136:139], v[198:201], v[120:123]
	v_mfma_f32_16x16x32_bf16 v[116:119], v[168:171], v[198:201], v[124:127]
	v_mfma_f32_16x16x32_bf16 v[28:31], v[136:139], v[206:209], v[28:31]
	v_mfma_f32_16x16x32_bf16 v[32:35], v[168:171], v[206:209], v[32:35]
	v_mfma_f32_16x16x32_bf16 v[20:23], v[140:143], v[180:183], v[20:23]
	v_mfma_f32_16x16x32_bf16 v[24:27], v[172:175], v[180:183], v[24:27]
	v_mfma_f32_16x16x32_bf16 v[36:39], v[140:143], v[188:191], v[36:39]
	v_mfma_f32_16x16x32_bf16 v[40:43], v[172:175], v[188:191], v[40:43]
	v_mfma_f32_16x16x32_bf16 v[72:75], v[140:143], v[202:205], v[72:75]
	v_mfma_f32_16x16x32_bf16 v[116:119], v[172:175], v[202:205], v[116:119]
	v_mfma_f32_16x16x32_bf16 v[28:31], v[140:143], v[210:213], v[28:31]
	v_mfma_f32_16x16x32_bf16 v[32:35], v[172:175], v[210:213], v[32:35]
	s_setprio 0
	s_barrier
	ds_read_b128 v[120:123], v7
	ds_read_b128 v[124:127], v7 offset:1024
	ds_read_b128 v[128:131], v7 offset:2048
	ds_read_b128 v[132:135], v7 offset:3072
	ds_read_b128 v[136:139], v15
	ds_read_b128 v[140:143], v15 offset:1024
	ds_read_b128 v[168:171], v15 offset:2048
	ds_read_b128 v[172:175], v15 offset:3072
	s_add_u32 s20, s20, 0x10180
	s_addc_u32 s21, s21, 0
	s_mov_b32 m0, s51
	v_lshl_add_u64 v[12:13], s[20:21], 0, v[4:5]
	ds_read_b128 v[176:179], v6
	ds_read_b128 v[180:183], v6 offset:1024
	ds_read_b128 v[184:187], v6 offset:2048
	ds_read_b128 v[188:191], v6 offset:3072
	ds_read_b128 v[198:201], v6 offset:4096
	ds_read_b128 v[202:205], v6 offset:5120
	ds_read_b128 v[206:209], v6 offset:6144
	ds_read_b128 v[210:213], v6 offset:7168
	global_load_lds_dwordx4 v[12:13], off
	v_lshl_add_u64 v[12:13], s[20:21], 0, v[2:3]
	s_mov_b32 m0, s1
	s_nop 0
	global_load_lds_dwordx4 v[12:13], off
	s_waitcnt vmcnt(8)
	s_waitcnt lgkmcnt(0)
	s_barrier
; #define PG8_STAGE(bufoff, gbase, voff) do { _Pragma("unroll") for (int _i = 0; _i < 2; ++_i) \
;         __builtin_amdgcn_global_load_lds((const unsigned*)((const char*)(gbase) + (voff)[_i]), (PG8_LAS unsigned*)(lds + (bufoff) + ldsw + _i * 8192), 16, 0, 0); } while (0)
; #define PG8_LDA(dst, b, h) do { _Pragma("unroll") for (int m = 0; m < 4; ++m) _Pragma("unroll") for (int k = 0; k < 2; ++k) dst[m][k] = *(const PG8_LAS bf16x8*)(lds + PG8_SA(b, h) + aoff + m * 2048 + k * 1024); } while (0)
; #define PG8_MMA(ai, bj, At, Bt) do { __builtin_amdgcn_s_setprio(1); _Pragma("unroll") for (int m = 0; m < 4; ++m) _Pragma("unroll") for (int n = 0; n < 2; ++n) _Pragma("unroll") for (int k = 0; k < 2; ++k) \
;         acc[ai][bj][m][n] = __builtin_amdgcn_mfma_f32_16x16x32_bf16(Bt[n][k], At[m][k], acc[ai][bj][m][n], 0, 0, 0); __builtin_amdgcn_s_setprio(0); } while (0)
; #define PG8_WAIT_V(n) asm volatile("s_waitcnt vmcnt(" #n ")" ::: "memory")
; #define PG8_WAIT_L(n) asm volatile("s_waitcnt lgkmcnt(" #n ")" ::: "memory")
; #define PG8_BAR __builtin_amdgcn_s_barrier()
; #define PG8_SCHED __builtin_amdgcn_sched_barrier(0)
; template <class Epi, class Sched, bool ALIGN_EPI = false, bool SP2 = false>
; __device__ __forceinline__ void gemm_phase(PG8_LAS unsigned char* lds, const Gemm g, const Sched& S, const Epi& E, const int wv) {
;     ...
;             PG8_WAIT_V(8); PG8_WAIT_L(0); PG8_BAR; PG8_MMA(0, 0, At, B0); PG8_MMA(0, 1, At, B1); PG8_BAR; PG8_SCHED;
;             PG8_LDA(At, 0, 1); PG8_STAGE(PG8_SB(0, 0), b2, voffB); PG8_STAGE(PG8_SB(0, 1), b2 + hstepB, voffB); PG8_STAGE(PG8_SA(0, 0), a2, voffA);
;             PG8_WAIT_V(8); PG8_WAIT_L(0); PG8_BAR; PG8_MMA(1, 0, At, B0); PG8_MMA(1, 1, At, B1); PG8_BAR; PG8_SCHED;
	s_setprio 1
	s_waitcnt lgkmcnt(0)
	v_mfma_f32_16x16x32_bf16 v[76:79], v[120:123], v[176:179], v[76:79]
	v_mfma_f32_16x16x32_bf16 v[80:83], v[128:131], v[176:179], v[80:83]
	v_mfma_f32_16x16x32_bf16 v[84:87], v[120:123], v[184:187], v[84:87]
	v_mfma_f32_16x16x32_bf16 v[88:91], v[128:131], v[184:187], v[88:91]
	v_mfma_f32_16x16x32_bf16 v[92:95], v[120:123], v[198:201], v[92:95]
	v_mfma_f32_16x16x32_bf16 v[96:99], v[128:131], v[198:201], v[96:99]
	v_mfma_f32_16x16x32_bf16 v[100:103], v[120:123], v[206:209], v[100:103]
	v_mfma_f32_16x16x32_bf16 v[104:107], v[128:131], v[206:209], v[104:107]
	v_mfma_f32_16x16x32_bf16 v[76:79], v[124:127], v[180:183], v[76:79]
	v_mfma_f32_16x16x32_bf16 v[80:83], v[132:135], v[180:183], v[80:83]
	v_mfma_f32_16x16x32_bf16 v[84:87], v[124:127], v[188:191], v[84:87]
	v_mfma_f32_16x16x32_bf16 v[88:91], v[132:135], v[188:191], v[88:91]
	v_mfma_f32_16x16x32_bf16 v[92:95], v[124:127], v[202:205], v[92:95]
	v_mfma_f32_16x16x32_bf16 v[96:99], v[132:135], v[202:205], v[96:99]
	v_mfma_f32_16x16x32_bf16 v[100:103], v[124:127], v[210:213], v[100:103]
	v_mfma_f32_16x16x32_bf16 v[104:107], v[132:135], v[210:213], v[104:107]
	v_mfma_f32_16x16x32_bf16 v[108:111], v[136:139], v[176:179], v[108:111]
	v_mfma_f32_16x16x32_bf16 v[44:47], v[168:171], v[176:179], v[44:47]
	v_mfma_f32_16x16x32_bf16 v[48:51], v[136:139], v[184:187], v[48:51]
	v_mfma_f32_16x16x32_bf16 v[52:55], v[168:171], v[184:187], v[52:55]
	v_mfma_f32_16x16x32_bf16 v[56:59], v[136:139], v[198:201], v[56:59]
	v_mfma_f32_16x16x32_bf16 v[60:63], v[168:171], v[198:201], v[60:63]
	v_mfma_f32_16x16x32_bf16 v[64:67], v[136:139], v[206:209], v[64:67]
	v_mfma_f32_16x16x32_bf16 v[68:71], v[168:171], v[206:209], v[68:71]
	v_mfma_f32_16x16x32_bf16 v[108:111], v[140:143], v[180:183], v[108:111]
	v_mfma_f32_16x16x32_bf16 v[44:47], v[172:175], v[180:183], v[44:47]
	v_mfma_f32_16x16x32_bf16 v[48:51], v[140:143], v[188:191], v[48:51]
	v_mfma_f32_16x16x32_bf16 v[52:55], v[172:175], v[188:191], v[52:55]
	v_mfma_f32_16x16x32_bf16 v[56:59], v[140:143], v[202:205], v[56:59]
	v_mfma_f32_16x16x32_bf16 v[60:63], v[172:175], v[202:205], v[60:63]
	v_mfma_f32_16x16x32_bf16 v[64:67], v[140:143], v[210:213], v[64:67]
	v_mfma_f32_16x16x32_bf16 v[68:71], v[172:175], v[210:213], v[68:71]
	s_setprio 0
	s_barrier
	s_mov_b32 m0, s49
	v_lshl_add_u64 v[12:13], s[18:19], 0, v[114:115]
	s_add_u32 s20, s18, 0x10000
	ds_read_b128 v[176:179], v6 offset:16384
	ds_read_b128 v[180:183], v6 offset:17408
	ds_read_b128 v[184:187], v6 offset:18432
	ds_read_b128 v[188:191], v6 offset:19456
	ds_read_b128 v[198:201], v6 offset:20480
	ds_read_b128 v[202:205], v6 offset:21504
	ds_read_b128 v[206:209], v6 offset:22528
	ds_read_b128 v[210:213], v6 offset:23552
	global_load_lds_dwordx4 v[12:13], off
	v_lshl_add_u64 v[112:113], s[18:19], 0, v[0:1]
	s_mov_b32 m0, s11
	s_addc_u32 s21, s19, 0
	global_load_lds_dwordx4 v[112:113], off
	v_lshl_add_u64 v[192:193], s[20:21], 0, v[114:115]
	s_mov_b32 m0, s13
	v_lshl_add_u64 v[214:215], s[38:39], 0, v[2:3]
	global_load_lds_dwordx4 v[192:193], off
	v_lshl_add_u64 v[192:193], s[20:21], 0, v[0:1]
	s_mov_b32 m0, s48
	s_nop 0
	global_load_lds_dwordx4 v[192:193], off
	v_lshl_add_u64 v[192:193], s[38:39], 0, v[4:5]
	s_mov_b32 m0, s9
	s_nop 0
	global_load_lds_dwordx4 v[192:193], off
	s_mov_b32 m0, s33
	s_nop 0
	global_load_lds_dwordx4 v[214:215], off
	s_waitcnt vmcnt(8)
	s_waitcnt lgkmcnt(0)
	s_barrier
	s_setprio 1
	s_waitcnt lgkmcnt(0)
	v_mfma_f32_16x16x32_bf16 v[144:147], v[120:123], v[176:179], v[144:147]
	v_mfma_f32_16x16x32_bf16 v[148:151], v[128:131], v[176:179], v[148:151]
	v_mfma_f32_16x16x32_bf16 v[152:155], v[120:123], v[184:187], v[152:155]
	v_mfma_f32_16x16x32_bf16 v[156:159], v[128:131], v[184:187], v[156:159]
	v_mfma_f32_16x16x32_bf16 v[160:163], v[120:123], v[198:201], v[160:163]
	v_mfma_f32_16x16x32_bf16 v[164:167], v[128:131], v[198:201], v[164:167]
	v_mfma_f32_16x16x32_bf16 v[8:11], v[120:123], v[206:209], v[8:11]
	v_mfma_f32_16x16x32_bf16 v[16:19], v[128:131], v[206:209], v[16:19]
	v_mfma_f32_16x16x32_bf16 v[144:147], v[124:127], v[180:183], v[144:147]
	v_mfma_f32_16x16x32_bf16 v[148:151], v[132:135], v[180:183], v[148:151]
	v_mfma_f32_16x16x32_bf16 v[152:155], v[124:127], v[188:191], v[152:155]
	v_mfma_f32_16x16x32_bf16 v[156:159], v[132:135], v[188:191], v[156:159]
	v_mfma_f32_16x16x32_bf16 v[160:163], v[124:127], v[202:205], v[160:163]
	v_mfma_f32_16x16x32_bf16 v[164:167], v[132:135], v[202:205], v[164:167]
	v_mfma_f32_16x16x32_bf16 v[8:11], v[124:127], v[210:213], v[8:11]
	v_mfma_f32_16x16x32_bf16 v[16:19], v[132:135], v[210:213], v[16:19]
	v_mfma_f32_16x16x32_bf16 v[20:23], v[136:139], v[176:179], v[20:23]
	v_mfma_f32_16x16x32_bf16 v[24:27], v[168:171], v[176:179], v[24:27]
	v_mfma_f32_16x16x32_bf16 v[36:39], v[136:139], v[184:187], v[36:39]
	v_mfma_f32_16x16x32_bf16 v[40:43], v[168:171], v[184:187], v[40:43]
	v_mfma_f32_16x16x32_bf16 v[72:75], v[136:139], v[198:201], v[72:75]
	v_mfma_f32_16x16x32_bf16 v[116:119], v[168:171], v[198:201], v[116:119]
	v_mfma_f32_16x16x32_bf16 v[28:31], v[136:139], v[206:209], v[28:31]
	v_mfma_f32_16x16x32_bf16 v[32:35], v[168:171], v[206:209], v[32:35]
	v_mfma_f32_16x16x32_bf16 v[20:23], v[140:143], v[180:183], v[20:23]
	v_mfma_f32_16x16x32_bf16 v[24:27], v[172:175], v[180:183], v[24:27]
	v_mfma_f32_16x16x32_bf16 v[36:39], v[140:143], v[188:191], v[36:39]
	v_mfma_f32_16x16x32_bf16 v[40:43], v[172:175], v[188:191], v[40:43]
	v_mfma_f32_16x16x32_bf16 v[72:75], v[140:143], v[202:205], v[72:75]
	v_mfma_f32_16x16x32_bf16 v[116:119], v[172:175], v[202:205], v[116:119]
	v_mfma_f32_16x16x32_bf16 v[28:31], v[140:143], v[210:213], v[28:31]
	v_mfma_f32_16x16x32_bf16 v[32:35], v[172:175], v[210:213], v[32:35]
	s_setprio 0
	s_barrier
; #define PG8_STAGE(bufoff, gbase, voff) do { _Pragma("unroll") for (int _i = 0; _i < 2; ++_i) \
;         __builtin_amdgcn_global_load_lds((const unsigned*)((const char*)(gbase) + (voff)[_i]), (PG8_LAS unsigned*)(lds + (bufoff) + ldsw + _i * 8192), 16, 0, 0); } while (0)
; #define PG8_LDA(dst, b, h) do { _Pragma("unroll") for (int m = 0; m < 4; ++m) _Pragma("unroll") for (int k = 0; k < 2; ++k) dst[m][k] = *(const PG8_LAS bf16x8*)(lds + PG8_SA(b, h) + aoff + m * 2048 + k * 1024); } while (0)
; #define PG8_LDB(dst, b, h) do { _Pragma("unroll") for (int n = 0; n < 2; ++n) _Pragma("unroll") for (int k = 0; k < 2; ++k) dst[n][k] = *(const PG8_LAS bf16x8*)(lds + PG8_SB(b, h) + boff + n * 2048 + k * 1024); } while (0)
; #define PG8_MMA(ai, bj, At, Bt) do { __builtin_amdgcn_s_setprio(1); _Pragma("unroll") for (int m = 0; m < 4; ++m) _Pragma("unroll") for (int n = 0; n < 2; ++n) _Pragma("unroll") for (int k = 0; k < 2; ++k) \
;         acc[ai][bj][m][n] = __builtin_amdgcn_mfma_f32_16x16x32_bf16(Bt[n][k], At[m][k], acc[ai][bj][m][n], 0, 0, 0); __builtin_amdgcn_s_setprio(0); } while (0)
; #define PG8_WAIT_V(n) asm volatile("s_waitcnt vmcnt(" #n ")" ::: "memory")
; #define PG8_WAIT_L(n) asm volatile("s_waitcnt lgkmcnt(" #n ")" ::: "memory")
; #define PG8_BAR __builtin_amdgcn_s_barrier()
; #define PG8_SCHED __builtin_amdgcn_sched_barrier(0)
; template <class Epi, class Sched, bool ALIGN_EPI = false, bool SP2 = false>
; __device__ __forceinline__ void gemm_phase(PG8_LAS unsigned char* lds, const Gemm g, const Sched& S, const Epi& E, const int wv) {
;     ...
;             PG8_LDB(B0, 1, 0); PG8_LDB(B1, 1, 1); PG8_SCHED; PG8_LDA(At, 1, 0); PG8_STAGE(PG8_SA(0, 1), a2 + hstepA, voffA);
;             PG8_WAIT_V(8); PG8_WAIT_L(0); PG8_BAR; PG8_MMA(0, 0, At, B0); PG8_MMA(0, 1, At, B1); PG8_BAR; PG8_SCHED;
;             PG8_LDA(At, 1, 1); PG8_STAGE(PG8_SB(1, 0), b3, voffB); PG8_STAGE(PG8_SB(1, 1), b3 + hstepB, voffB); PG8_STAGE(PG8_SA(1, 0), a3, voffA);
;             PG8_WAIT_V(8); PG8_WAIT_L(0); PG8_BAR; PG8_MMA(1, 0, At, B0); PG8_MMA(1, 1, At, B1); PG8_BAR; PG8_SCHED;
	ds_read_b128 v[120:123], v218
	ds_read_b128 v[124:127], v218 offset:1024
	ds_read_b128 v[128:131], v218 offset:2048
	ds_read_b128 v[132:135], v218 offset:3072
	ds_read_b128 v[136:139], v219
	ds_read_b128 v[140:143], v219 offset:1024
	ds_read_b128 v[168:171], v219 offset:2048
	ds_read_b128 v[172:175], v219 offset:3072
	s_add_u32 s20, s38, 0x10000
	s_addc_u32 s21, s39, 0
	s_mov_b32 m0, s34
	v_lshl_add_u64 v[216:217], s[20:21], 0, v[4:5]
	ds_read_b128 v[176:179], v6 offset:32768
	ds_read_b128 v[180:183], v6 offset:33792
	ds_read_b128 v[184:187], v6 offset:34816
	ds_read_b128 v[188:191], v6 offset:35840
	ds_read_b128 v[198:201], v6 offset:36864
	ds_read_b128 v[202:205], v6 offset:37888
	ds_read_b128 v[206:209], v6 offset:38912
	ds_read_b128 v[210:213], v6 offset:39936
	global_load_lds_dwordx4 v[216:217], off
	v_lshl_add_u64 v[216:217], s[20:21], 0, v[2:3]
	s_mov_b32 m0, s35
	s_nop 0
	global_load_lds_dwordx4 v[216:217], off
	s_waitcnt vmcnt(8)
	s_waitcnt lgkmcnt(0)
	s_barrier
	s_setprio 1
	s_waitcnt lgkmcnt(0)
	v_mfma_f32_16x16x32_bf16 v[76:79], v[120:123], v[176:179], v[76:79]
	v_mfma_f32_16x16x32_bf16 v[80:83], v[128:131], v[176:179], v[80:83]
	v_mfma_f32_16x16x32_bf16 v[84:87], v[120:123], v[184:187], v[84:87]
	v_mfma_f32_16x16x32_bf16 v[88:91], v[128:131], v[184:187], v[88:91]
	v_mfma_f32_16x16x32_bf16 v[92:95], v[120:123], v[198:201], v[92:95]
	v_mfma_f32_16x16x32_bf16 v[96:99], v[128:131], v[198:201], v[96:99]
	v_mfma_f32_16x16x32_bf16 v[100:103], v[120:123], v[206:209], v[100:103]
	v_mfma_f32_16x16x32_bf16 v[104:107], v[128:131], v[206:209], v[104:107]
	v_mfma_f32_16x16x32_bf16 v[76:79], v[124:127], v[180:183], v[76:79]
	v_mfma_f32_16x16x32_bf16 v[80:83], v[132:135], v[180:183], v[80:83]
	v_mfma_f32_16x16x32_bf16 v[84:87], v[124:127], v[188:191], v[84:87]
	v_mfma_f32_16x16x32_bf16 v[88:91], v[132:135], v[188:191], v[88:91]
	v_mfma_f32_16x16x32_bf16 v[92:95], v[124:127], v[202:205], v[92:95]
	v_mfma_f32_16x16x32_bf16 v[96:99], v[132:135], v[202:205], v[96:99]
	v_mfma_f32_16x16x32_bf16 v[100:103], v[124:127], v[210:213], v[100:103]
	v_mfma_f32_16x16x32_bf16 v[104:107], v[132:135], v[210:213], v[104:107]
	v_mfma_f32_16x16x32_bf16 v[108:111], v[136:139], v[176:179], v[108:111]
	v_mfma_f32_16x16x32_bf16 v[44:47], v[168:171], v[176:179], v[44:47]
	v_mfma_f32_16x16x32_bf16 v[48:51], v[136:139], v[184:187], v[48:51]
	v_mfma_f32_16x16x32_bf16 v[52:55], v[168:171], v[184:187], v[52:55]
	v_mfma_f32_16x16x32_bf16 v[56:59], v[136:139], v[198:201], v[56:59]
	v_mfma_f32_16x16x32_bf16 v[60:63], v[168:171], v[198:201], v[60:63]
	v_mfma_f32_16x16x32_bf16 v[64:67], v[136:139], v[206:209], v[64:67]
	v_mfma_f32_16x16x32_bf16 v[68:71], v[168:171], v[206:209], v[68:71]
	v_mfma_f32_16x16x32_bf16 v[108:111], v[140:143], v[180:183], v[108:111]
	v_mfma_f32_16x16x32_bf16 v[44:47], v[172:175], v[180:183], v[44:47]
	v_mfma_f32_16x16x32_bf16 v[48:51], v[140:143], v[188:191], v[48:51]
	v_mfma_f32_16x16x32_bf16 v[52:55], v[172:175], v[188:191], v[52:55]
	v_mfma_f32_16x16x32_bf16 v[56:59], v[140:143], v[202:205], v[56:59]
	v_mfma_f32_16x16x32_bf16 v[60:63], v[172:175], v[202:205], v[60:63]
	v_mfma_f32_16x16x32_bf16 v[64:67], v[140:143], v[210:213], v[64:67]
	v_mfma_f32_16x16x32_bf16 v[68:71], v[172:175], v[210:213], v[68:71]
	s_setprio 0
	s_barrier
	s_mov_b32 m0, s52
	v_lshl_add_u64 v[12:13], v[12:13], 0, s[28:29]
	s_add_u32 s18, s18, 0x10080
	ds_read_b128 v[176:179], v6 offset:49152
	ds_read_b128 v[180:183], v6 offset:50176
	ds_read_b128 v[184:187], v6 offset:51200
	ds_read_b128 v[188:191], v6 offset:52224
	ds_read_b128 v[198:201], v6 offset:53248
	ds_read_b128 v[202:205], v6 offset:54272
	ds_read_b128 v[206:209], v6 offset:55296
	ds_read_b128 v[210:213], v6 offset:56320
	global_load_lds_dwordx4 v[12:13], off
	v_lshl_add_u64 v[12:13], v[112:113], 0, s[28:29]
	s_mov_b32 m0, s50
	s_addc_u32 s19, s19, 0
	global_load_lds_dwordx4 v[12:13], off
	v_lshl_add_u64 v[12:13], s[18:19], 0, v[114:115]
	s_mov_b32 m0, s30
	s_nop 0
	global_load_lds_dwordx4 v[12:13], off
	v_lshl_add_u64 v[12:13], s[18:19], 0, v[0:1]
	s_mov_b32 m0, s31
	s_nop 0
	global_load_lds_dwordx4 v[12:13], off
	v_lshl_add_u64 v[12:13], v[192:193], 0, s[28:29]
	s_mov_b32 m0, s45
	s_nop 0
	global_load_lds_dwordx4 v[12:13], off
	v_lshl_add_u64 v[12:13], v[214:215], 0, s[28:29]
	s_mov_b32 m0, s46
	s_nop 0
	global_load_lds_dwordx4 v[12:13], off
	s_waitcnt vmcnt(8)
	s_waitcnt lgkmcnt(0)
	s_barrier
	s_setprio 1
	s_waitcnt lgkmcnt(0)
	v_mfma_f32_16x16x32_bf16 v[144:147], v[120:123], v[176:179], v[144:147]
	v_mfma_f32_16x16x32_bf16 v[148:151], v[128:131], v[176:179], v[148:151]
	v_mfma_f32_16x16x32_bf16 v[152:155], v[120:123], v[184:187], v[152:155]
	v_mfma_f32_16x16x32_bf16 v[156:159], v[128:131], v[184:187], v[156:159]
	v_mfma_f32_16x16x32_bf16 v[160:163], v[120:123], v[198:201], v[160:163]
	v_mfma_f32_16x16x32_bf16 v[164:167], v[128:131], v[198:201], v[164:167]
	v_mfma_f32_16x16x32_bf16 v[8:11], v[120:123], v[206:209], v[8:11]
	v_mfma_f32_16x16x32_bf16 v[16:19], v[128:131], v[206:209], v[16:19]
	v_mfma_f32_16x16x32_bf16 v[144:147], v[124:127], v[180:183], v[144:147]
	v_mfma_f32_16x16x32_bf16 v[148:151], v[132:135], v[180:183], v[148:151]
	v_mfma_f32_16x16x32_bf16 v[152:155], v[124:127], v[188:191], v[152:155]
	v_mfma_f32_16x16x32_bf16 v[156:159], v[132:135], v[188:191], v[156:159]
	v_mfma_f32_16x16x32_bf16 v[160:163], v[124:127], v[202:205], v[160:163]
	v_mfma_f32_16x16x32_bf16 v[164:167], v[132:135], v[202:205], v[164:167]
	v_mfma_f32_16x16x32_bf16 v[8:11], v[124:127], v[210:213], v[8:11]
	v_mfma_f32_16x16x32_bf16 v[16:19], v[132:135], v[210:213], v[16:19]
	v_mfma_f32_16x16x32_bf16 v[20:23], v[136:139], v[176:179], v[20:23]
	v_mfma_f32_16x16x32_bf16 v[24:27], v[168:171], v[176:179], v[24:27]
	v_mfma_f32_16x16x32_bf16 v[36:39], v[136:139], v[184:187], v[36:39]
	v_mfma_f32_16x16x32_bf16 v[40:43], v[168:171], v[184:187], v[40:43]
	v_mfma_f32_16x16x32_bf16 v[72:75], v[136:139], v[198:201], v[72:75]
	v_mfma_f32_16x16x32_bf16 v[116:119], v[168:171], v[198:201], v[116:119]
	v_mfma_f32_16x16x32_bf16 v[28:31], v[136:139], v[206:209], v[28:31]
	v_mfma_f32_16x16x32_bf16 v[32:35], v[168:171], v[206:209], v[32:35]
	v_mfma_f32_16x16x32_bf16 v[20:23], v[140:143], v[180:183], v[20:23]
	v_mfma_f32_16x16x32_bf16 v[24:27], v[172:175], v[180:183], v[24:27]
	v_mfma_f32_16x16x32_bf16 v[36:39], v[140:143], v[188:191], v[36:39]
	v_mfma_f32_16x16x32_bf16 v[40:43], v[172:175], v[188:191], v[40:43]
	v_mfma_f32_16x16x32_bf16 v[72:75], v[140:143], v[202:205], v[72:75]
	v_mfma_f32_16x16x32_bf16 v[116:119], v[172:175], v[202:205], v[116:119]
	v_mfma_f32_16x16x32_bf16 v[28:31], v[140:143], v[210:213], v[28:31]
	v_mfma_f32_16x16x32_bf16 v[32:35], v[172:175], v[210:213], v[32:35]
	s_setprio 0
	s_barrier
; __device__ __forceinline__ int fresh_lane() { int l; asm volatile("v_mbcnt_lo_u32_b32 %0, -1, 0\n\tv_mbcnt_hi_u32_b32 %0, -1, %0" : "=v"(l)); return l; }
; __device__ __forceinline__ unsigned cvtpk(float lo, float hi) { f32x2_t v = {lo, hi}; bf16x2_t b = __builtin_convertvector(v, bf16x2_t); return __builtin_bit_cast(unsigned, b); }
;     __device__ __forceinline__ void operator()(accv (&acc)[2][2][4][2], const pg8::Unit& u, int wr, int wc, int fr, int fq) const {
;         { const int ln_ = fresh_lane(); fr = ln_ & 15; fq = ln_ >> 4; }
;         bf16* rp0 = Y + (size_t)(u.pm * 256 + wr * 64 + fr) * ldy + u.pn * 256 + wc * 32 + 8 * fq;
; #pragma unroll
;         for (int ai = 0; ai < 2; ++ai)
; #pragma unroll
;             for (int m = 0; m < 4; ++m) {
;                 bf16* rp = rp0 + (size_t)(128 * ai + 16 * m) * ldy;
; #pragma unroll
;                 for (int bj = 0; bj < 2; ++bj) {
;                     const accv v0 = acc[ai][bj][m][0], v1 = acc[ai][bj][m][1];
;                     *(v4u*)(rp + 128 * bj) = (v4u){cvtpk(v0[0], v0[1]), cvtpk(v0[2], v0[3]), cvtpk(v1[0], v1[1]), cvtpk(v1[2], v1[3])};
;                 }
;             }
	s_lshl_b32 s1, s8, 8
	s_add_i32 s1, s1, s44
	v_mbcnt_lo_u32_b32 v7, -1, 0
	v_mbcnt_hi_u32_b32 v7, -1, v7
	s_lshl_b32 s0, s0, 8
	v_and_or_b32 v12, v7, 15, s1
	v_ashrrev_i32_e32 v13, 31, v12
	v_lshlrev_b64 v[12:13], 11, v[12:13]
	v_lshl_add_u64 v[12:13], s[4:5], 0, v[12:13]
	s_ashr_i32 s1, s0, 31
	v_lshl_add_u64 v[12:13], s[0:1], 1, v[12:13]
	v_readlane_b32 s0, v254, 9
	v_ashrrev_i32_e32 v7, 1, v7
	v_readlane_b32 s1, v254, 10
	v_and_b32_e32 v112, -8, v7
	v_ashrrev_i32_e32 v113, 31, v112
	v_lshl_add_u64 v[12:13], v[12:13], 0, s[0:1]
	v_lshl_add_u64 v[12:13], v[112:113], 1, v[12:13]
	v_cvt_pk_bf16_f32 v76, v76, v77
	v_cvt_pk_bf16_f32 v77, v78, v79
	v_cvt_pk_bf16_f32 v78, v80, v81
	v_cvt_pk_bf16_f32 v79, v82, v83
	global_store_dwordx4 v[12:13], v[76:79], off
	s_mov_b32 s0, 0x8000
	v_cvt_pk_bf16_f32 v20, v20, v21
	v_cvt_pk_bf16_f32 v76, v108, v109
	v_cvt_pk_bf16_f32 v77, v110, v111
	v_cvt_pk_bf16_f32 v78, v44, v45
	v_cvt_pk_bf16_f32 v79, v46, v47
	global_store_dwordx4 v[12:13], v[76:79], off offset:256
	v_cvt_pk_bf16_f32 v44, v84, v85
	v_cvt_pk_bf16_f32 v45, v86, v87
	v_add_co_u32_e32 v76, vcc, s0, v12
	v_cvt_pk_bf16_f32 v46, v88, v89
	v_cvt_pk_bf16_f32 v47, v90, v91
	v_addc_co_u32_e32 v77, vcc, 0, v13, vcc
	s_mov_b32 s0, 0x10000
	global_store_dwordx4 v[76:77], v[44:47], off
	v_cvt_pk_bf16_f32 v21, v22, v23
	v_cvt_pk_bf16_f32 v22, v24, v25
	v_cvt_pk_bf16_f32 v44, v48, v49
	v_cvt_pk_bf16_f32 v45, v50, v51
	v_cvt_pk_bf16_f32 v46, v52, v53
	v_cvt_pk_bf16_f32 v47, v54, v55
	v_add_co_u32_e32 v48, vcc, s0, v12
	global_store_dwordx4 v[76:77], v[44:47], off offset:256
	s_nop 0
	v_addc_co_u32_e32 v49, vcc, 0, v13, vcc
	v_cvt_pk_bf16_f32 v44, v92, v93
	v_cvt_pk_bf16_f32 v45, v94, v95
	v_cvt_pk_bf16_f32 v46, v96, v97
	v_cvt_pk_bf16_f32 v47, v98, v99
	global_store_dwordx4 v[48:49], v[44:47], off
	s_mov_b32 s0, 0x18000
	v_cvt_pk_bf16_f32 v23, v26, v27
	v_cvt_pk_bf16_f32 v44, v56, v57
	v_cvt_pk_bf16_f32 v45, v58, v59
	v_cvt_pk_bf16_f32 v46, v60, v61
	v_cvt_pk_bf16_f32 v47, v62, v63
	global_store_dwordx4 v[48:49], v[44:47], off offset:256
	v_add_co_u32_e32 v48, vcc, s0, v12
	s_nop 0
	v_cvt_pk_bf16_f32 v44, v100, v101
	v_cvt_pk_bf16_f32 v45, v102, v103
	v_cvt_pk_bf16_f32 v46, v104, v105
	v_cvt_pk_bf16_f32 v47, v106, v107
	v_addc_co_u32_e32 v49, vcc, 0, v13, vcc
	global_store_dwordx4 v[48:49], v[44:47], off
	s_mov_b32 s0, 0x40000
	v_cvt_pk_bf16_f32 v8, v8, v9
	v_cvt_pk_bf16_f32 v44, v64, v65
	v_cvt_pk_bf16_f32 v45, v66, v67
	v_cvt_pk_bf16_f32 v46, v68, v69
	v_cvt_pk_bf16_f32 v47, v70, v71
	global_store_dwordx4 v[48:49], v[44:47], off offset:256
	v_add_co_u32_e32 v48, vcc, s0, v12
	s_mov_b32 s0, 0x48000
	s_nop 0
	v_addc_co_u32_e32 v49, vcc, 0, v13, vcc
	v_add_co_u32_e32 v24, vcc, s0, v12
	global_store_dwordx4 v[48:49], v[20:23], off offset:256
	s_nop 0
	v_addc_co_u32_e32 v25, vcc, 0, v13, vcc
	v_cvt_pk_bf16_f32 v20, v152, v153
	v_cvt_pk_bf16_f32 v21, v154, v155
	v_cvt_pk_bf16_f32 v22, v156, v157
	v_cvt_pk_bf16_f32 v23, v158, v159
	global_store_dwordx4 v[24:25], v[20:23], off
	s_mov_b32 s0, 0x50000
	v_cvt_pk_bf16_f32 v9, v10, v11
	v_cvt_pk_bf16_f32 v20, v36, v37
	v_cvt_pk_bf16_f32 v21, v38, v39
	v_cvt_pk_bf16_f32 v22, v40, v41
	v_cvt_pk_bf16_f32 v23, v42, v43
	global_store_dwordx4 v[24:25], v[20:23], off offset:256
	v_add_co_u32_e32 v24, vcc, s0, v12
	s_mov_b32 s0, 0x58000
	s_nop 0
	v_addc_co_u32_e32 v25, vcc, 0, v13, vcc
	v_add_co_u32_e32 v12, vcc, s0, v12
	v_cvt_pk_bf16_f32 v20, v160, v161
	v_cvt_pk_bf16_f32 v21, v162, v163
	v_cvt_pk_bf16_f32 v22, v164, v165
	v_cvt_pk_bf16_f32 v23, v166, v167
	v_cvt_pk_bf16_f32 v10, v16, v17
	v_cvt_pk_bf16_f32 v11, v18, v19
	v_addc_co_u32_e32 v13, vcc, 0, v13, vcc
	v_cvt_pk_bf16_f32 v44, v144, v145
	v_cvt_pk_bf16_f32 v45, v146, v147
	v_cvt_pk_bf16_f32 v46, v148, v149
	v_cvt_pk_bf16_f32 v47, v150, v151
	global_store_dwordx4 v[24:25], v[20:23], off
	global_store_dwordx4 v[12:13], v[8:11], off
	s_add_i32 s47, s47, s23
	v_cvt_pk_bf16_f32 v20, v72, v73
	v_cvt_pk_bf16_f32 v21, v74, v75
	v_cvt_pk_bf16_f32 v22, v116, v117
	v_cvt_pk_bf16_f32 v23, v118, v119
	v_cvt_pk_bf16_f32 v8, v28, v29
	v_cvt_pk_bf16_f32 v9, v30, v31
	v_cvt_pk_bf16_f32 v10, v32, v33
	v_cvt_pk_bf16_f32 v11, v34, v35
	s_andn2_b64 vcc, exec, s[6:7]
	s_mov_b32 s0, s10
	s_mov_b32 s8, s12
	s_mov_b64 s[30:31], s[16:17]
	s_mov_b64 s[20:21], s[14:15]
	global_store_dwordx4 v[48:49], v[44:47], off
	global_store_dwordx4 v[24:25], v[20:23], off offset:256
	global_store_dwordx4 v[12:13], v[8:11], off offset:256
	s_cbranch_vccz .LBB0_1387

; #define PG8_STAGE(bufoff, gbase, voff) do { _Pragma("unroll") for (int _i = 0; _i < 2; ++_i) \
;         __builtin_amdgcn_global_load_lds((const unsigned*)((const char*)(gbase) + (voff)[_i]), (PG8_LAS unsigned*)(lds + (bufoff) + ldsw + _i * 8192), 16, 0, 0); } while (0)
; #define PG8_LDA(dst, b, h) do { _Pragma("unroll") for (int m = 0; m < 4; ++m) _Pragma("unroll") for (int k = 0; k < 2; ++k) dst[m][k] = *(const PG8_LAS bf16x8*)(lds + PG8_SA(b, h) + aoff + m * 2048 + k * 1024); } while (0)
; #define PG8_LDB(dst, b, h) do { _Pragma("unroll") for (int n = 0; n < 2; ++n) _Pragma("unroll") for (int k = 0; k < 2; ++k) dst[n][k] = *(const PG8_LAS bf16x8*)(lds + PG8_SB(b, h) + boff + n * 2048 + k * 1024); } while (0)
; #define PG8_MMA(ai, bj, At, Bt) do { __builtin_amdgcn_s_setprio(1); _Pragma("unroll") for (int m = 0; m < 4; ++m) _Pragma("unroll") for (int n = 0; n < 2; ++n) _Pragma("unroll") for (int k = 0; k < 2; ++k) \
;         acc[ai][bj][m][n] = __builtin_amdgcn_mfma_f32_16x16x32_bf16(Bt[n][k], At[m][k], acc[ai][bj][m][n], 0, 0, 0); __builtin_amdgcn_s_setprio(0); } while (0)
; #define PG8_WAIT_V(n) asm volatile("s_waitcnt vmcnt(" #n ")" ::: "memory")
; #define PG8_WAIT_L(n) asm volatile("s_waitcnt lgkmcnt(" #n ")" ::: "memory")
; #define PG8_BAR __builtin_amdgcn_s_barrier()
; #define PG8_SCHED __builtin_amdgcn_sched_barrier(0)
; template <class Epi, class Sched, bool ALIGN_EPI = false, bool SP2 = false>
; __device__ __forceinline__ void gemm_phase(PG8_LAS unsigned char* lds, const Gemm g, const Sched& S, const Epi& E, const int wv) {
;     ...
;             const bool last = (t == nt - 2);
;             const char* a1 = cA + (size_t)(t + 1) * kstep;
;             const char* a2 = last ? nA : cA + (size_t)(t + 2) * kstep; const char* b2 = last ? nB : cB + (size_t)(t + 2) * kstep;
;             const char* a3 = a2 + kstep; const char* b3 = b2 + kstep;
;             if (last && has_next) S.a_ready(nxt);
;             if constexpr (SP2) {
;             PG8_LDB(B0, 0, 0); PG8_LDB(B1, 0, 1); PG8_SCHED; PG8_LDA(At, 0, 0); PG8_STAGE(PG8_SA(1, 1), a1 + hstepA, voffA);
;             PG8_WAIT_V(8); PG8_WAIT_L(0); PG8_BAR; PG8_MMA(0, 0, At, B0); PG8_MMA(0, 1, At, B1); PG8_BAR; PG8_SCHED;
;             PG8_LDA(At, 0, 1); PG8_STAGE(PG8_SB(0, 0), b2, voffB); PG8_STAGE(PG8_SB(0, 1), b2 + hstepB, voffB); PG8_STAGE(PG8_SA(0, 0), a2, voffA);
.LBB0_1465:
	s_add_u32 s1, s42, 0xfffc0080
	s_addc_u32 s44, s43, -1
	s_add_i32 s72, 0, 0x10000
	s_cmp_eq_u32 s71, 12
	s_cselect_b32 s59, s0, s44
	s_cselect_b32 s58, s5, s1
	s_cselect_b32 s45, s47, s70
	s_cselect_b32 s44, s51, s53
	s_add_i32 s1, 0, 0x14000
	v_add_u32_e32 v152, s72, v206
	v_add_u32_e32 v168, s1, v206
	ds_read_b128 v[132:135], v152
	ds_read_b128 v[144:147], v152 offset:1024
	ds_read_b128 v[148:151], v152 offset:2048
	ds_read_b128 v[152:155], v152 offset:3072
	ds_read_b128 v[156:159], v168
	ds_read_b128 v[160:163], v168 offset:1024
	ds_read_b128 v[164:167], v168 offset:2048
	ds_read_b128 v[168:171], v168 offset:3072
	v_lshl_add_u64 v[192:193], s[42:43], 0, v[140:141]
	s_add_i32 m0, s36, 0xc000
	ds_read_b128 v[172:175], v207
	ds_read_b128 v[176:179], v207 offset:1024
	ds_read_b128 v[180:183], v207 offset:2048
	ds_read_b128 v[184:187], v207 offset:3072
	ds_read_b128 v[188:191], v207 offset:4096
	ds_read_b128 v[198:201], v207 offset:5120
	ds_read_b128 v[202:205], v207 offset:6144
	ds_read_b128 v[208:211], v207 offset:7168
	global_load_lds_dwordx4 v[192:193], off
	v_lshl_add_u64 v[192:193], s[42:43], 0, v[142:143]
	s_add_i32 m0, s36, 0xe000
	s_nop 0
	global_load_lds_dwordx4 v[192:193], off
	s_waitcnt vmcnt(8)
	s_waitcnt lgkmcnt(0)
	s_barrier
	s_setprio 1
	s_waitcnt lgkmcnt(0)
	v_mfma_f32_16x16x32_bf16 v[128:131], v[132:135], v[172:175], v[128:131]
	v_mfma_f32_16x16x32_bf16 v[124:127], v[148:151], v[172:175], v[124:127]
	v_mfma_f32_16x16x32_bf16 v[108:111], v[132:135], v[180:183], v[108:111]
	v_mfma_f32_16x16x32_bf16 v[104:107], v[148:151], v[180:183], v[104:107]
	v_mfma_f32_16x16x32_bf16 v[92:95], v[132:135], v[188:191], v[92:95]
	v_mfma_f32_16x16x32_bf16 v[88:91], v[148:151], v[188:191], v[88:91]
	v_mfma_f32_16x16x32_bf16 v[76:79], v[132:135], v[202:205], v[76:79]
	v_mfma_f32_16x16x32_bf16 v[72:75], v[148:151], v[202:205], v[72:75]
	v_mfma_f32_16x16x32_bf16 v[128:131], v[144:147], v[176:179], v[128:131]
	v_mfma_f32_16x16x32_bf16 v[124:127], v[152:155], v[176:179], v[124:127]
	v_mfma_f32_16x16x32_bf16 v[108:111], v[144:147], v[184:187], v[108:111]
	v_mfma_f32_16x16x32_bf16 v[104:107], v[152:155], v[184:187], v[104:107]
	v_mfma_f32_16x16x32_bf16 v[92:95], v[144:147], v[198:201], v[92:95]
	v_mfma_f32_16x16x32_bf16 v[88:91], v[152:155], v[198:201], v[88:91]
	v_mfma_f32_16x16x32_bf16 v[76:79], v[144:147], v[208:211], v[76:79]
	v_mfma_f32_16x16x32_bf16 v[72:75], v[152:155], v[208:211], v[72:75]
	v_mfma_f32_16x16x32_bf16 v[120:123], v[156:159], v[172:175], v[120:123]
	v_mfma_f32_16x16x32_bf16 v[116:119], v[164:167], v[172:175], v[116:119]
	v_mfma_f32_16x16x32_bf16 v[100:103], v[156:159], v[180:183], v[100:103]
	v_mfma_f32_16x16x32_bf16 v[96:99], v[164:167], v[180:183], v[96:99]
	v_mfma_f32_16x16x32_bf16 v[84:87], v[156:159], v[188:191], v[84:87]
	v_mfma_f32_16x16x32_bf16 v[80:83], v[164:167], v[188:191], v[80:83]
	v_mfma_f32_16x16x32_bf16 v[68:71], v[156:159], v[202:205], v[68:71]
	v_mfma_f32_16x16x32_bf16 v[64:67], v[164:167], v[202:205], v[64:67]
	v_mfma_f32_16x16x32_bf16 v[120:123], v[160:163], v[176:179], v[120:123]
	v_mfma_f32_16x16x32_bf16 v[116:119], v[168:171], v[176:179], v[116:119]
	v_mfma_f32_16x16x32_bf16 v[100:103], v[160:163], v[184:187], v[100:103]
	v_mfma_f32_16x16x32_bf16 v[96:99], v[168:171], v[184:187], v[96:99]
	v_mfma_f32_16x16x32_bf16 v[84:87], v[160:163], v[198:201], v[84:87]
	v_mfma_f32_16x16x32_bf16 v[80:83], v[168:171], v[198:201], v[80:83]
	v_mfma_f32_16x16x32_bf16 v[68:71], v[160:163], v[208:211], v[68:71]
	v_mfma_f32_16x16x32_bf16 v[64:67], v[168:171], v[208:211], v[64:67]
	s_setprio 0
	s_barrier
	s_add_i32 s72, s72, s35
	v_lshl_add_u64 v[192:193], s[44:45], 0, v[114:115]
	s_mov_b32 m0, s72
	ds_read_b128 v[172:175], v207 offset:16384
	ds_read_b128 v[176:179], v207 offset:17408
	ds_read_b128 v[180:183], v207 offset:18432
	ds_read_b128 v[184:187], v207 offset:19456
	ds_read_b128 v[188:191], v207 offset:20480
	ds_read_b128 v[198:201], v207 offset:21504
	ds_read_b128 v[202:205], v207 offset:22528
	ds_read_b128 v[208:211], v207 offset:23552
	global_load_lds_dwordx4 v[192:193], off
	s_add_i32 m0, s72, 0x2000
	s_add_u32 s72, s44, 0x40000
	v_lshl_add_u64 v[212:213], s[44:45], 0, v[138:139]
	s_addc_u32 s73, s45, 0
	s_add_i32 s1, s1, s35
	global_load_lds_dwordx4 v[212:213], off
	v_lshl_add_u64 v[214:215], s[72:73], 0, v[114:115]
	s_mov_b32 m0, s1
	v_lshl_add_u64 v[216:217], s[58:59], 0, v[136:137]
	global_load_lds_dwordx4 v[214:215], off
	v_lshl_add_u64 v[214:215], s[72:73], 0, v[138:139]
	s_add_i32 m0, s1, 0x2000
	s_nop 0
	global_load_lds_dwordx4 v[214:215], off
	v_lshl_add_u64 v[214:215], s[58:59], 0, v[112:113]
	s_mov_b32 m0, s36
	s_nop 0
	global_load_lds_dwordx4 v[214:215], off
	s_mov_b32 m0, s37
	s_nop 0
	global_load_lds_dwordx4 v[216:217], off
	s_waitcnt vmcnt(8)
	s_waitcnt lgkmcnt(0)
	s_barrier
; #define PG8_STAGE(bufoff, gbase, voff) do { _Pragma("unroll") for (int _i = 0; _i < 2; ++_i) \
;         __builtin_amdgcn_global_load_lds((const unsigned*)((const char*)(gbase) + (voff)[_i]), (PG8_LAS unsigned*)(lds + (bufoff) + ldsw + _i * 8192), 16, 0, 0); } while (0)
; #define PG8_LDA(dst, b, h) do { _Pragma("unroll") for (int m = 0; m < 4; ++m) _Pragma("unroll") for (int k = 0; k < 2; ++k) dst[m][k] = *(const PG8_LAS bf16x8*)(lds + PG8_SA(b, h) + aoff + m * 2048 + k * 1024); } while (0)
; #define PG8_LDB(dst, b, h) do { _Pragma("unroll") for (int n = 0; n < 2; ++n) _Pragma("unroll") for (int k = 0; k < 2; ++k) dst[n][k] = *(const PG8_LAS bf16x8*)(lds + PG8_SB(b, h) + boff + n * 2048 + k * 1024); } while (0)
; #define PG8_MMA(ai, bj, At, Bt) do { __builtin_amdgcn_s_setprio(1); _Pragma("unroll") for (int m = 0; m < 4; ++m) _Pragma("unroll") for (int n = 0; n < 2; ++n) _Pragma("unroll") for (int k = 0; k < 2; ++k) \
;         acc[ai][bj][m][n] = __builtin_amdgcn_mfma_f32_16x16x32_bf16(Bt[n][k], At[m][k], acc[ai][bj][m][n], 0, 0, 0); __builtin_amdgcn_s_setprio(0); } while (0)
; #define PG8_WAIT_V(n) asm volatile("s_waitcnt vmcnt(" #n ")" ::: "memory")
; #define PG8_WAIT_L(n) asm volatile("s_waitcnt lgkmcnt(" #n ")" ::: "memory")
; #define PG8_BAR __builtin_amdgcn_s_barrier()
; #define PG8_SCHED __builtin_amdgcn_sched_barrier(0)
; template <class Epi, class Sched, bool ALIGN_EPI = false, bool SP2 = false>
; __device__ __forceinline__ void gemm_phase(PG8_LAS unsigned char* lds, const Gemm g, const Sched& S, const Epi& E, const int wv) {
;     ...
;             PG8_WAIT_V(8); PG8_WAIT_L(0); PG8_BAR; PG8_MMA(1, 0, At, B0); PG8_MMA(1, 1, At, B1); PG8_BAR; PG8_SCHED;
;             PG8_LDB(B0, 1, 0); PG8_LDB(B1, 1, 1); PG8_SCHED; PG8_LDA(At, 1, 0); PG8_STAGE(PG8_SA(0, 1), a2 + hstepA, voffA);
;             PG8_WAIT_V(8); PG8_WAIT_L(0); PG8_BAR; PG8_MMA(0, 0, At, B0); PG8_MMA(0, 1, At, B1); PG8_BAR; PG8_SCHED;
	s_setprio 1
	s_waitcnt lgkmcnt(0)
	v_mfma_f32_16x16x32_bf16 v[60:63], v[132:135], v[172:175], v[60:63]
	v_mfma_f32_16x16x32_bf16 v[56:59], v[148:151], v[172:175], v[56:59]
	v_mfma_f32_16x16x32_bf16 v[44:47], v[132:135], v[180:183], v[44:47]
	v_mfma_f32_16x16x32_bf16 v[40:43], v[148:151], v[180:183], v[40:43]
	v_mfma_f32_16x16x32_bf16 v[28:31], v[132:135], v[188:191], v[28:31]
	v_mfma_f32_16x16x32_bf16 v[24:27], v[148:151], v[188:191], v[24:27]
	v_mfma_f32_16x16x32_bf16 v[12:15], v[132:135], v[202:205], v[12:15]
	v_mfma_f32_16x16x32_bf16 v[8:11], v[148:151], v[202:205], v[8:11]
	v_mfma_f32_16x16x32_bf16 v[60:63], v[144:147], v[176:179], v[60:63]
	v_mfma_f32_16x16x32_bf16 v[56:59], v[152:155], v[176:179], v[56:59]
	v_mfma_f32_16x16x32_bf16 v[44:47], v[144:147], v[184:187], v[44:47]
	v_mfma_f32_16x16x32_bf16 v[40:43], v[152:155], v[184:187], v[40:43]
	v_mfma_f32_16x16x32_bf16 v[28:31], v[144:147], v[198:201], v[28:31]
	v_mfma_f32_16x16x32_bf16 v[24:27], v[152:155], v[198:201], v[24:27]
	v_mfma_f32_16x16x32_bf16 v[12:15], v[144:147], v[208:211], v[12:15]
	v_mfma_f32_16x16x32_bf16 v[8:11], v[152:155], v[208:211], v[8:11]
	v_mfma_f32_16x16x32_bf16 v[52:55], v[156:159], v[172:175], v[52:55]
	v_mfma_f32_16x16x32_bf16 v[48:51], v[164:167], v[172:175], v[48:51]
	v_mfma_f32_16x16x32_bf16 v[36:39], v[156:159], v[180:183], v[36:39]
	v_mfma_f32_16x16x32_bf16 v[32:35], v[164:167], v[180:183], v[32:35]
	v_mfma_f32_16x16x32_bf16 v[20:23], v[156:159], v[188:191], v[20:23]
	v_mfma_f32_16x16x32_bf16 v[16:19], v[164:167], v[188:191], v[16:19]
	v_mfma_f32_16x16x32_bf16 v[4:7], v[156:159], v[202:205], v[4:7]
	v_mfma_f32_16x16x32_bf16 v[0:3], v[164:167], v[202:205], v[0:3]
	v_mfma_f32_16x16x32_bf16 v[52:55], v[160:163], v[176:179], v[52:55]
	v_mfma_f32_16x16x32_bf16 v[48:51], v[168:171], v[176:179], v[48:51]
	v_mfma_f32_16x16x32_bf16 v[36:39], v[160:163], v[184:187], v[36:39]
	v_mfma_f32_16x16x32_bf16 v[32:35], v[168:171], v[184:187], v[32:35]
	v_mfma_f32_16x16x32_bf16 v[20:23], v[160:163], v[198:201], v[20:23]
	v_mfma_f32_16x16x32_bf16 v[16:19], v[168:171], v[198:201], v[16:19]
	v_mfma_f32_16x16x32_bf16 v[4:7], v[160:163], v[208:211], v[4:7]
	v_mfma_f32_16x16x32_bf16 v[0:3], v[168:171], v[208:211], v[0:3]
	s_setprio 0
	s_barrier
	s_add_i32 s1, 0, 0x18000
	s_add_i32 s72, 0, 0x1c000
	v_add_u32_e32 v152, s1, v206
	v_add_u32_e32 v168, s72, v206
	ds_read_b128 v[132:135], v152
	ds_read_b128 v[144:147], v152 offset:1024
	ds_read_b128 v[148:151], v152 offset:2048
	ds_read_b128 v[152:155], v152 offset:3072
	ds_read_b128 v[156:159], v168
	ds_read_b128 v[160:163], v168 offset:1024
	ds_read_b128 v[164:167], v168 offset:2048
	ds_read_b128 v[168:171], v168 offset:3072
	s_add_u32 s58, s58, 0x40000
	s_addc_u32 s59, s59, 0
	s_mov_b32 m0, s60
	v_lshl_add_u64 v[218:219], s[58:59], 0, v[112:113]
	ds_read_b128 v[172:175], v207 offset:32768
	ds_read_b128 v[176:179], v207 offset:33792
	ds_read_b128 v[180:183], v207 offset:34816
	ds_read_b128 v[184:187], v207 offset:35840
	ds_read_b128 v[188:191], v207 offset:36864
	ds_read_b128 v[198:201], v207 offset:37888
	ds_read_b128 v[202:205], v207 offset:38912
	ds_read_b128 v[208:211], v207 offset:39936
	global_load_lds_dwordx4 v[218:219], off
	v_lshl_add_u64 v[218:219], s[58:59], 0, v[136:137]
	s_mov_b32 m0, s61
	s_nop 0
	global_load_lds_dwordx4 v[218:219], off
	s_waitcnt vmcnt(8)
	s_waitcnt lgkmcnt(0)
	s_barrier
	s_setprio 1
	s_waitcnt lgkmcnt(0)
	v_mfma_f32_16x16x32_bf16 v[128:131], v[132:135], v[172:175], v[128:131]
	v_mfma_f32_16x16x32_bf16 v[124:127], v[148:151], v[172:175], v[124:127]
	v_mfma_f32_16x16x32_bf16 v[108:111], v[132:135], v[180:183], v[108:111]
	v_mfma_f32_16x16x32_bf16 v[104:107], v[148:151], v[180:183], v[104:107]
	v_mfma_f32_16x16x32_bf16 v[92:95], v[132:135], v[188:191], v[92:95]
	v_mfma_f32_16x16x32_bf16 v[88:91], v[148:151], v[188:191], v[88:91]
	v_mfma_f32_16x16x32_bf16 v[76:79], v[132:135], v[202:205], v[76:79]
	v_mfma_f32_16x16x32_bf16 v[72:75], v[148:151], v[202:205], v[72:75]
	v_mfma_f32_16x16x32_bf16 v[128:131], v[144:147], v[176:179], v[128:131]
	v_mfma_f32_16x16x32_bf16 v[124:127], v[152:155], v[176:179], v[124:127]
	v_mfma_f32_16x16x32_bf16 v[108:111], v[144:147], v[184:187], v[108:111]
	v_mfma_f32_16x16x32_bf16 v[104:107], v[152:155], v[184:187], v[104:107]
	v_mfma_f32_16x16x32_bf16 v[92:95], v[144:147], v[198:201], v[92:95]
	v_mfma_f32_16x16x32_bf16 v[88:91], v[152:155], v[198:201], v[88:91]
	v_mfma_f32_16x16x32_bf16 v[76:79], v[144:147], v[208:211], v[76:79]
	v_mfma_f32_16x16x32_bf16 v[72:75], v[152:155], v[208:211], v[72:75]
	v_mfma_f32_16x16x32_bf16 v[120:123], v[156:159], v[172:175], v[120:123]
	v_mfma_f32_16x16x32_bf16 v[116:119], v[164:167], v[172:175], v[116:119]
	v_mfma_f32_16x16x32_bf16 v[100:103], v[156:159], v[180:183], v[100:103]
	v_mfma_f32_16x16x32_bf16 v[96:99], v[164:167], v[180:183], v[96:99]
	v_mfma_f32_16x16x32_bf16 v[84:87], v[156:159], v[188:191], v[84:87]
	v_mfma_f32_16x16x32_bf16 v[80:83], v[164:167], v[188:191], v[80:83]
	v_mfma_f32_16x16x32_bf16 v[68:71], v[156:159], v[202:205], v[68:71]
	v_mfma_f32_16x16x32_bf16 v[64:67], v[164:167], v[202:205], v[64:67]
	v_mfma_f32_16x16x32_bf16 v[120:123], v[160:163], v[176:179], v[120:123]
	v_mfma_f32_16x16x32_bf16 v[116:119], v[168:171], v[176:179], v[116:119]
	v_mfma_f32_16x16x32_bf16 v[100:103], v[160:163], v[184:187], v[100:103]
	v_mfma_f32_16x16x32_bf16 v[96:99], v[168:171], v[184:187], v[96:99]
	v_mfma_f32_16x16x32_bf16 v[84:87], v[160:163], v[198:201], v[84:87]
	v_mfma_f32_16x16x32_bf16 v[80:83], v[168:171], v[198:201], v[80:83]
	v_mfma_f32_16x16x32_bf16 v[68:71], v[160:163], v[208:211], v[68:71]
	v_mfma_f32_16x16x32_bf16 v[64:67], v[168:171], v[208:211], v[64:67]
	s_setprio 0
	s_barrier
; #define PG8_STAGE(bufoff, gbase, voff) do { _Pragma("unroll") for (int _i = 0; _i < 2; ++_i) \
;         __builtin_amdgcn_global_load_lds((const unsigned*)((const char*)(gbase) + (voff)[_i]), (PG8_LAS unsigned*)(lds + (bufoff) + ldsw + _i * 8192), 16, 0, 0); } while (0)
; #define PG8_LDA(dst, b, h) do { _Pragma("unroll") for (int m = 0; m < 4; ++m) _Pragma("unroll") for (int k = 0; k < 2; ++k) dst[m][k] = *(const PG8_LAS bf16x8*)(lds + PG8_SA(b, h) + aoff + m * 2048 + k * 1024); } while (0)
; #define PG8_MMA(ai, bj, At, Bt) do { __builtin_amdgcn_s_setprio(1); _Pragma("unroll") for (int m = 0; m < 4; ++m) _Pragma("unroll") for (int n = 0; n < 2; ++n) _Pragma("unroll") for (int k = 0; k < 2; ++k) \
;         acc[ai][bj][m][n] = __builtin_amdgcn_mfma_f32_16x16x32_bf16(Bt[n][k], At[m][k], acc[ai][bj][m][n], 0, 0, 0); __builtin_amdgcn_s_setprio(0); } while (0)
; #define PG8_WAIT_V(n) asm volatile("s_waitcnt vmcnt(" #n ")" ::: "memory")
; #define PG8_WAIT_L(n) asm volatile("s_waitcnt lgkmcnt(" #n ")" ::: "memory")
; #define PG8_BAR __builtin_amdgcn_s_barrier()
; #define PG8_SCHED __builtin_amdgcn_sched_barrier(0)
; template <class Epi, class Sched, bool ALIGN_EPI = false, bool SP2 = false>
; __device__ __forceinline__ void gemm_phase(PG8_LAS unsigned char* lds, const Gemm g, const Sched& S, const Epi& E, const int wv) {
;     ...
;             PG8_LDA(At, 1, 1); PG8_STAGE(PG8_SB(1, 0), b3, voffB); PG8_STAGE(PG8_SB(1, 1), b3 + hstepB, voffB); PG8_STAGE(PG8_SA(1, 0), a3, voffA);
;             PG8_WAIT_V(8); PG8_WAIT_L(0); PG8_BAR; PG8_MMA(1, 0, At, B0); PG8_MMA(1, 1, At, B1); PG8_BAR; PG8_SCHED;
	s_add_i32 s1, s1, s35
	v_lshl_add_u64 v[192:193], v[192:193], 0, s[28:29]
	s_mov_b32 m0, s1
	ds_read_b128 v[172:175], v207 offset:49152
	ds_read_b128 v[176:179], v207 offset:50176
	ds_read_b128 v[180:183], v207 offset:51200
	ds_read_b128 v[184:187], v207 offset:52224
	ds_read_b128 v[188:191], v207 offset:53248
	ds_read_b128 v[198:201], v207 offset:54272
	ds_read_b128 v[202:205], v207 offset:55296
	ds_read_b128 v[208:211], v207 offset:56320
	global_load_lds_dwordx4 v[192:193], off
	s_add_i32 m0, s1, 0x2000
	s_add_u32 s44, s44, 0x40080
	v_lshl_add_u64 v[192:193], v[212:213], 0, s[28:29]
	s_addc_u32 s45, s45, 0
	s_add_i32 s1, s72, s35
	global_load_lds_dwordx4 v[192:193], off
	v_lshl_add_u64 v[192:193], s[44:45], 0, v[114:115]
	s_mov_b32 m0, s1
	s_nop 0
	global_load_lds_dwordx4 v[192:193], off
	v_lshl_add_u64 v[192:193], s[44:45], 0, v[138:139]
	s_add_i32 m0, s1, 0x2000
	s_nop 0
	global_load_lds_dwordx4 v[192:193], off
	v_lshl_add_u64 v[192:193], v[214:215], 0, s[28:29]
	s_mov_b32 m0, s66
	s_nop 0
	global_load_lds_dwordx4 v[192:193], off
	v_lshl_add_u64 v[192:193], v[216:217], 0, s[28:29]
	s_mov_b32 m0, s67
	s_nop 0
	global_load_lds_dwordx4 v[192:193], off
	s_waitcnt vmcnt(8)
	s_waitcnt lgkmcnt(0)
	s_barrier
	s_setprio 1
	s_waitcnt lgkmcnt(0)
	v_mfma_f32_16x16x32_bf16 v[60:63], v[132:135], v[172:175], v[60:63]
	v_mfma_f32_16x16x32_bf16 v[56:59], v[148:151], v[172:175], v[56:59]
	v_mfma_f32_16x16x32_bf16 v[44:47], v[132:135], v[180:183], v[44:47]
	v_mfma_f32_16x16x32_bf16 v[40:43], v[148:151], v[180:183], v[40:43]
	v_mfma_f32_16x16x32_bf16 v[28:31], v[132:135], v[188:191], v[28:31]
	v_mfma_f32_16x16x32_bf16 v[24:27], v[148:151], v[188:191], v[24:27]
	v_mfma_f32_16x16x32_bf16 v[12:15], v[132:135], v[202:205], v[12:15]
	v_mfma_f32_16x16x32_bf16 v[8:11], v[148:151], v[202:205], v[8:11]
	v_mfma_f32_16x16x32_bf16 v[60:63], v[144:147], v[176:179], v[60:63]
	v_mfma_f32_16x16x32_bf16 v[56:59], v[152:155], v[176:179], v[56:59]
	v_mfma_f32_16x16x32_bf16 v[44:47], v[144:147], v[184:187], v[44:47]
	v_mfma_f32_16x16x32_bf16 v[40:43], v[152:155], v[184:187], v[40:43]
	v_mfma_f32_16x16x32_bf16 v[28:31], v[144:147], v[198:201], v[28:31]
	v_mfma_f32_16x16x32_bf16 v[24:27], v[152:155], v[198:201], v[24:27]
	v_mfma_f32_16x16x32_bf16 v[12:15], v[144:147], v[208:211], v[12:15]
	v_mfma_f32_16x16x32_bf16 v[8:11], v[152:155], v[208:211], v[8:11]
	v_mfma_f32_16x16x32_bf16 v[52:55], v[156:159], v[172:175], v[52:55]
	v_mfma_f32_16x16x32_bf16 v[48:51], v[164:167], v[172:175], v[48:51]
	v_mfma_f32_16x16x32_bf16 v[36:39], v[156:159], v[180:183], v[36:39]
	v_mfma_f32_16x16x32_bf16 v[32:35], v[164:167], v[180:183], v[32:35]
	v_mfma_f32_16x16x32_bf16 v[20:23], v[156:159], v[188:191], v[20:23]
	v_mfma_f32_16x16x32_bf16 v[16:19], v[164:167], v[188:191], v[16:19]
	v_mfma_f32_16x16x32_bf16 v[4:7], v[156:159], v[202:205], v[4:7]
	v_mfma_f32_16x16x32_bf16 v[0:3], v[164:167], v[202:205], v[0:3]
	v_mfma_f32_16x16x32_bf16 v[52:55], v[160:163], v[176:179], v[52:55]
	v_mfma_f32_16x16x32_bf16 v[48:51], v[168:171], v[176:179], v[48:51]
	v_mfma_f32_16x16x32_bf16 v[36:39], v[160:163], v[184:187], v[36:39]
	v_mfma_f32_16x16x32_bf16 v[32:35], v[168:171], v[184:187], v[32:35]
	v_mfma_f32_16x16x32_bf16 v[20:23], v[160:163], v[198:201], v[20:23]
	v_mfma_f32_16x16x32_bf16 v[16:19], v[168:171], v[198:201], v[16:19]
	v_mfma_f32_16x16x32_bf16 v[4:7], v[160:163], v[208:211], v[4:7]
	v_mfma_f32_16x16x32_bf16 v[0:3], v[168:171], v[208:211], v[0:3]
	s_setprio 0
	s_barrier
	s_add_i32 s71, s71, 2
	s_add_u32 s42, s42, 0x100
	s_addc_u32 s43, s43, 0
	s_add_u32 s53, s53, 0x100
	s_addc_u32 s70, s70, 0
	s_cmp_gt_u32 s71, 13
	s_cbranch_scc0 .LBB0_1465
	s_and_b64 vcc, exec, s[30:31]
	s_cbranch_vccz .LBB0_1468
	s_barrier
